# gelu peepholes, wider still: select rewritten at 147 of 192 sites (also when the first compare was issued ahead of the packed ops), abs at 169
# baseline (speedup 1.0000x reference)
.LBB0_443:
	s_waitcnt vmcnt(0)
	v_mov_b32_e32 v55, v0
	s_mov_b64 s[12:13], s[74:75]
	v_readfirstlane_b32 s0, v55
	s_ashr_i32 s10, s0, 6
	s_add_u32 s4, s12, 0x696e000
	v_bfe_u32 v3, v55, 4, 2
	s_addc_u32 s5, s13, 0
	s_lshl_b32 s11, s10, 4
	s_ashr_i32 s71, s70, 31
	v_or_b32_e32 v16, s11, v3
	s_lshl_b64 s[6:7], s[70:71], 7
	v_ashrrev_i32_e32 v17, 31, v16
	v_lshl_add_u64 v[4:5], s[6:7], 0, v[16:17]
	v_and_b32_e32 v54, 15, v55
	v_lshlrev_b64 v[4:5], 11, v[4:5]
	v_lshl_add_u64 v[4:5], s[4:5], 0, v[4:5]
	v_lshlrev_b32_e32 v6, 4, v54
	s_waitcnt lgkmcnt(0)
	v_mov_b32_e32 v7, v2
	v_lshl_add_u64 v[20:21], v[4:5], 0, v[6:7]
	s_barrier
	global_load_dwordx4 v[8:11], v[20:21], off
	global_load_dwordx4 v[4:7], v[20:21], off offset:256
	v_mov_b64_e32 v[18:19], s[44:45]
	v_mov_b32_e32 v13, v2
	s_waitcnt vmcnt(1)
	v_lshlrev_b32_e32 v24, 16, v10
	v_and_b32_e32 v25, 0xffff0000, v10
	v_and_b32_e32 v15, 0xffff0000, v8
	v_and_b32_e32 v23, 0xffff0000, v9
	v_lshlrev_b32_e32 v22, 16, v9
	v_lshlrev_b32_e32 v14, 16, v8
	v_lshlrev_b32_e32 v8, 16, v11
	v_and_b32_e32 v9, 0xffff0000, v11
	v_fma_f32 v10, |v24|, s40, 1.0
	v_fma_f32 v11, |v25|, s40, 1.0
	v_fma_f32 v28, |v14|, s40, 1.0
	v_fma_f32 v29, |v15|, s40, 1.0
	v_rcp_f32_e32 v10, v10
	v_rcp_f32_e32 v11, v11
	v_fma_f32 v32, |v22|, s40, 1.0
	v_fma_f32 v33, |v23|, s40, 1.0
	v_rcp_f32_e32 v28, v28
	v_rcp_f32_e32 v29, v29
	v_rcp_f32_e32 v32, v32
	v_rcp_f32_e32 v33, v33
	v_pk_mul_f32 v[26:27], v[24:25], v[24:25]
	v_pk_mul_f32 v[30:31], v[14:15], v[14:15]
	v_pk_mul_f32 v[26:27], v[26:27], s[64:65] op_sel_hi:[1,0]
	v_pk_fma_f32 v[36:37], v[10:11], s[42:43], v[18:19] op_sel_hi:[1,0,0]
	v_pk_mul_f32 v[34:35], v[22:23], v[22:23]
	v_pk_mul_f32 v[30:31], v[30:31], s[64:65] op_sel_hi:[1,0]
	v_exp_f32_e32 v26, v26
	v_exp_f32_e32 v27, v27
	v_pk_fma_f32 v[38:39], v[28:29], s[42:43], v[18:19] op_sel_hi:[1,0,0]
	v_pk_fma_f32 v[36:37], v[10:11], v[36:37], s[48:49] op_sel_hi:[1,1,0]
	v_pk_mul_f32 v[34:35], v[34:35], s[64:65] op_sel_hi:[1,0]
	v_exp_f32_e32 v30, v30
	v_exp_f32_e32 v31, v31
	v_pk_fma_f32 v[40:41], v[32:33], s[42:43], v[18:19] op_sel_hi:[1,0,0]
	v_pk_fma_f32 v[38:39], v[28:29], v[38:39], s[48:49] op_sel_hi:[1,1,0]
	v_pk_fma_f32 v[36:37], v[10:11], v[36:37], s[50:51] op_sel_hi:[1,1,0]
	v_exp_f32_e32 v34, v34
	v_exp_f32_e32 v35, v35
	v_pk_fma_f32 v[40:41], v[32:33], v[40:41], s[48:49] op_sel_hi:[1,1,0]
	v_pk_fma_f32 v[38:39], v[28:29], v[38:39], s[50:51] op_sel_hi:[1,1,0]
	v_pk_fma_f32 v[36:37], v[10:11], v[36:37], s[56:57] op_sel_hi:[1,1,0]
	v_pk_fma_f32 v[40:41], v[32:33], v[40:41], s[50:51] op_sel_hi:[1,1,0]
	v_pk_fma_f32 v[38:39], v[28:29], v[38:39], s[56:57] op_sel_hi:[1,1,0]
	v_pk_mul_f32 v[10:11], v[10:11], v[36:37]
	v_pk_fma_f32 v[40:41], v[32:33], v[40:41], s[56:57] op_sel_hi:[1,1,0]
	v_pk_mul_f32 v[28:29], v[28:29], v[38:39]
	v_pk_mul_f32 v[10:11], v[26:27], v[10:11]
	v_pk_mul_f32 v[32:33], v[32:33], v[40:41]
	v_pk_mul_f32 v[26:27], v[30:31], v[28:29]
	v_max_f32_e32 v80, 0, v24
	v_fma_f32 v37, -|v24|, v10, v80
	v_max_f32_e32 v81, 0, v25
	v_fma_f32 v11, -|v25|, v11, v81
	v_pk_mul_f32 v[28:29], v[34:35], v[32:33]
	v_pk_mul_f32 v[32:33], v[26:27], v[14:15]
	v_max_f32_e32 v82, 0, v22
	v_fma_f32 v25, -|v22|, v28, v82
	v_max_f32_e32 v83, 0, v23
	v_fma_f32 v23, -|v23|, v29, v83
	v_pk_fma_f32 v[26:27], v[26:27], v[14:15], v[14:15] neg_lo:[1,0,0] neg_hi:[1,0,0]
	v_mul_f32_e32 v36, v37, v37
	v_cmp_gt_f32_e32 vcc, 0, v14
	v_mov_b32_e32 v14, v25
	v_mul_f32_e32 v10, v11, v11
	v_cndmask_b32_e32 v24, v26, v32, vcc
	v_cmp_gt_f32_e32 vcc, 0, v15
	v_mul_f32_e32 v26, v24, v24
	v_pk_add_f32 v[10:11], v[36:37], v[10:11]
	v_cndmask_b32_e32 v15, v27, v33, vcc
	v_mov_b32_e32 v27, v25
	v_mul_f32_e32 v22, v15, v15
	v_mul_f32_e32 v12, v23, v23
	v_pk_add_f32 v[22:23], v[26:27], v[22:23]
	v_pk_mul_f32 v[26:27], v[24:25], v[14:15] op_sel:[1,0] op_sel_hi:[0,1]
	v_pk_add_f32 v[14:15], v[24:25], v[14:15] op_sel:[1,0] op_sel_hi:[0,1]
	v_mov_b32_e32 v27, v15
	v_fma_f32 v14, |v8|, s40, 1.0
	v_fma_f32 v15, |v9|, s40, 1.0
	v_pk_add_f32 v[12:13], v[26:27], v[12:13]
	v_rcp_f32_e32 v14, v14
	v_rcp_f32_e32 v15, v15
	v_pk_add_f32 v[12:13], v[22:23], v[12:13]
	v_cmp_gt_f32_e32 vcc, 0, v8
	v_pk_add_f32 v[22:23], v[10:11], v[12:13]
	v_pk_mul_f32 v[12:13], v[8:9], v[8:9]
	v_pk_fma_f32 v[10:11], v[14:15], s[42:43], v[18:19] op_sel_hi:[1,0,0]
	v_pk_mul_f32 v[12:13], v[12:13], s[64:65] op_sel_hi:[1,0]
	v_pk_fma_f32 v[10:11], v[14:15], v[10:11], s[48:49] op_sel_hi:[1,1,0]
	v_exp_f32_e32 v12, v12
	v_exp_f32_e32 v13, v13
	v_pk_fma_f32 v[10:11], v[14:15], v[10:11], s[50:51] op_sel_hi:[1,1,0]
	s_waitcnt vmcnt(0)
	v_lshlrev_b32_e32 v36, 16, v6
	v_pk_fma_f32 v[10:11], v[14:15], v[10:11], s[56:57] op_sel_hi:[1,1,0]
	v_and_b32_e32 v37, 0xffff0000, v6
	v_pk_mul_f32 v[10:11], v[14:15], v[10:11]
	v_pk_mul_f32 v[10:11], v[12:13], v[10:11]
	v_pk_mul_f32 v[12:13], v[8:9], v[10:11]
	v_pk_fma_f32 v[10:11], v[8:9], v[10:11], v[8:9] neg_lo:[1,0,0] neg_hi:[1,0,0]
	v_fma_f32 v32, |v36|, s40, 1.0
	v_fma_f32 v33, |v37|, s40, 1.0
	v_cndmask_b32_e32 v15, v10, v12, vcc
	v_cmp_gt_f32_e32 vcc, 0, v9
	v_lshlrev_b32_e32 v12, 16, v4
	v_and_b32_e32 v10, 0x7fffffff, v12
	v_cndmask_b32_e32 v9, v11, v13, vcc
	v_and_b32_e32 v13, 0xffff0000, v4
	v_and_b32_e32 v11, 0x7fffffff, v13
	v_pk_fma_f32 v[10:11], v[10:11], s[40:41], 1.0 op_sel_hi:[1,0,0]
	v_mul_f32_e32 v14, v15, v15
	v_rcp_f32_e32 v10, v10
	v_rcp_f32_e32 v11, v11
	v_mul_f32_e32 v8, v9, v9
	v_pk_add_f32 v[24:25], v[14:15], v[8:9]
	v_pk_mul_f32 v[14:15], v[12:13], v[12:13]
	v_pk_fma_f32 v[8:9], v[10:11], s[42:43], v[18:19] op_sel_hi:[1,0,0]
	v_pk_mul_f32 v[14:15], v[14:15], s[64:65] op_sel_hi:[1,0]
	v_pk_fma_f32 v[8:9], v[10:11], v[8:9], s[48:49] op_sel_hi:[1,1,0]
	v_exp_f32_e32 v14, v14
	v_exp_f32_e32 v15, v15
	v_pk_fma_f32 v[8:9], v[10:11], v[8:9], s[50:51] op_sel_hi:[1,1,0]
	v_lshlrev_b32_e32 v4, 16, v5
	v_pk_fma_f32 v[8:9], v[10:11], v[8:9], s[56:57] op_sel_hi:[1,1,0]
	v_and_b32_e32 v5, 0xffff0000, v5
	v_pk_mul_f32 v[8:9], v[10:11], v[8:9]
	v_pk_mul_f32 v[14:15], v[14:15], v[8:9]
	global_load_dwordx4 v[8:11], v[20:21], off offset:512
	v_fma_f32 v30, |v4|, s40, 1.0
	v_fma_f32 v31, |v5|, s40, 1.0
	v_rcp_f32_e32 v30, v30
	v_rcp_f32_e32 v31, v31
	v_max_f32_e32 v84, 0, v12
	v_fma_f32 v27, -|v12|, v14, v84
	v_max_f32_e32 v85, 0, v13
	v_fma_f32 v29, -|v13|, v15, v85
	v_rcp_f32_e32 v34, v32
	v_rcp_f32_e32 v35, v33
	v_pk_fma_f32 v[12:13], v[30:31], s[42:43], v[18:19] op_sel_hi:[1,0,0]
	v_mul_f32_e32 v26, v27, v27
	v_pk_mul_f32 v[14:15], v[4:5], v[4:5]
	v_pk_fma_f32 v[12:13], v[30:31], v[12:13], s[48:49] op_sel_hi:[1,1,0]
	v_pk_mul_f32 v[14:15], v[14:15], s[64:65] op_sel_hi:[1,0]
	v_pk_fma_f32 v[12:13], v[30:31], v[12:13], s[50:51] op_sel_hi:[1,1,0]
	v_exp_f32_e32 v14, v14
	v_exp_f32_e32 v15, v15
	v_pk_fma_f32 v[12:13], v[30:31], v[12:13], s[56:57] op_sel_hi:[1,1,0]
	v_pk_mul_f32 v[12:13], v[30:31], v[12:13]
	v_mul_f32_e32 v28, v29, v29
	v_pk_mul_f32 v[12:13], v[14:15], v[12:13]
	v_pk_add_f32 v[22:23], v[24:25], v[22:23]
	v_max_f32_e32 v86, 0, v4
	v_fma_f32 v31, -|v4|, v12, v86
	v_max_f32_e32 v90, 0, v5
	v_fma_f32 v33, -|v5|, v13, v90
	v_pk_add_f32 v[24:25], v[26:27], v[28:29]
	v_pk_fma_f32 v[4:5], v[34:35], s[42:43], v[18:19] op_sel_hi:[1,0,0]
	v_lshlrev_b32_e32 v14, 16, v7
	v_pk_mul_f32 v[12:13], v[36:37], v[36:37]
	v_pk_fma_f32 v[4:5], v[34:35], v[4:5], s[48:49] op_sel_hi:[1,1,0]
	v_pk_mul_f32 v[12:13], v[12:13], s[64:65] op_sel_hi:[1,0]
	v_pk_fma_f32 v[4:5], v[34:35], v[4:5], s[50:51] op_sel_hi:[1,1,0]
	v_exp_f32_e32 v12, v12
	v_exp_f32_e32 v13, v13
	v_and_b32_e32 v15, 0xffff0000, v7
	v_pk_fma_f32 v[4:5], v[34:35], v[4:5], s[56:57] op_sel_hi:[1,1,0]
	v_pk_mul_f32 v[4:5], v[34:35], v[4:5]
	v_fma_f32 v6, |v14|, s40, 1.0
	v_fma_f32 v7, |v15|, s40, 1.0
	v_pk_mul_f32 v[4:5], v[12:13], v[4:5]
	v_rcp_f32_e32 v6, v6
	v_rcp_f32_e32 v7, v7
	v_max_f32_e32 v91, 0, v36
	v_fma_f32 v35, -|v36|, v4, v91
	v_max_f32_e32 v92, 0, v37
	v_fma_f32 v37, -|v37|, v5, v92
	v_mul_f32_e32 v30, v31, v31
	v_mul_f32_e32 v32, v33, v33
	v_mul_f32_e32 v34, v35, v35
	v_pk_add_f32 v[22:23], v[24:25], v[22:23]
	v_pk_mul_f32 v[12:13], v[14:15], v[14:15]
	v_pk_fma_f32 v[4:5], v[6:7], s[42:43], v[18:19] op_sel_hi:[1,0,0]
	v_pk_mul_f32 v[12:13], v[12:13], s[64:65] op_sel_hi:[1,0]
	v_pk_fma_f32 v[4:5], v[6:7], v[4:5], s[48:49] op_sel_hi:[1,1,0]
	v_exp_f32_e32 v12, v12
	v_exp_f32_e32 v13, v13
	v_pk_fma_f32 v[4:5], v[6:7], v[4:5], s[50:51] op_sel_hi:[1,1,0]
	v_pk_fma_f32 v[4:5], v[6:7], v[4:5], s[56:57] op_sel_hi:[1,1,0]
	v_mul_f32_e32 v36, v37, v37
	v_pk_mul_f32 v[4:5], v[6:7], v[4:5]
	v_pk_add_f32 v[24:25], v[30:31], v[32:33]
	v_pk_mul_f32 v[4:5], v[12:13], v[4:5]
	v_pk_add_f32 v[22:23], v[24:25], v[22:23]
	v_max_f32_e32 v93, 0, v14
	v_fma_f32 v39, -|v14|, v4, v93
	v_max_f32_e32 v94, 0, v15
	v_fma_f32 v41, -|v15|, v5, v94
	global_load_dwordx4 v[4:7], v[20:21], off offset:768
	v_mul_f32_e32 v38, v39, v39
	s_waitcnt vmcnt(1)
	v_lshlrev_b32_e32 v44, 16, v8
	v_and_b32_e32 v45, 0xffff0000, v8
	v_fma_f32 v42, |v44|, s40, 1.0
	v_fma_f32 v43, |v45|, s40, 1.0
	v_pk_mul_f32 v[14:15], v[44:45], v[44:45]
	v_rcp_f32_e32 v42, v42
	v_rcp_f32_e32 v43, v43
	v_pk_mul_f32 v[14:15], v[14:15], s[64:65] op_sel_hi:[1,0]
	v_lshlrev_b32_e32 v46, 16, v9
	v_pk_fma_f32 v[12:13], v[42:43], s[42:43], v[18:19] op_sel_hi:[1,0,0]
	v_exp_f32_e32 v14, v14
	v_pk_fma_f32 v[12:13], v[42:43], v[12:13], s[48:49] op_sel_hi:[1,1,0]
	v_exp_f32_e32 v15, v15
	v_and_b32_e32 v47, 0xffff0000, v9
	v_pk_fma_f32 v[12:13], v[42:43], v[12:13], s[50:51] op_sel_hi:[1,1,0]
	v_pk_fma_f32 v[12:13], v[42:43], v[12:13], s[56:57] op_sel_hi:[1,1,0]
	v_fma_f32 v8, |v46|, s40, 1.0
	v_fma_f32 v9, |v47|, s40, 1.0
	v_pk_mul_f32 v[12:13], v[42:43], v[12:13]
	v_rcp_f32_e32 v48, v8
	v_rcp_f32_e32 v49, v9
	v_pk_mul_f32 v[12:13], v[14:15], v[12:13]
	v_max_f32_e32 v95, 0, v44
	v_fma_f32 v43, -|v44|, v12, v95
	v_max_f32_e32 v96, 0, v45
	v_fma_f32 v9, -|v45|, v13, v96
	v_lshlrev_b32_e32 v50, 16, v10
	v_and_b32_e32 v51, 0xffff0000, v10
	v_lshlrev_b32_e32 v10, 16, v11
	v_pk_fma_f32 v[12:13], v[48:49], s[42:43], v[18:19] op_sel_hi:[1,0,0]
	v_pk_mul_f32 v[14:15], v[46:47], v[46:47]
	v_pk_fma_f32 v[12:13], v[48:49], v[12:13], s[48:49] op_sel_hi:[1,1,0]
	v_pk_mul_f32 v[14:15], v[14:15], s[64:65] op_sel_hi:[1,0]
	v_pk_fma_f32 v[12:13], v[48:49], v[12:13], s[50:51] op_sel_hi:[1,1,0]
	v_exp_f32_e32 v14, v14
	v_exp_f32_e32 v15, v15
	v_pk_fma_f32 v[12:13], v[48:49], v[12:13], s[56:57] op_sel_hi:[1,1,0]
	v_pk_mul_f32 v[12:13], v[48:49], v[12:13]
	v_fma_f32 v48, |v50|, s40, 1.0
	v_fma_f32 v49, |v51|, s40, 1.0
	v_pk_mul_f32 v[12:13], v[14:15], v[12:13]
	v_rcp_f32_e32 v48, v48
	v_rcp_f32_e32 v49, v49
	v_max_f32_e32 v97, 0, v46
	v_fma_f32 v45, -|v46|, v12, v97
	v_max_f32_e32 v98, 0, v47
	v_fma_f32 v47, -|v47|, v13, v98
	v_and_b32_e32 v11, 0xffff0000, v11
	v_pk_mul_f32 v[14:15], v[50:51], v[50:51]
	v_pk_fma_f32 v[12:13], v[48:49], s[42:43], v[18:19] op_sel_hi:[1,0,0]
	v_pk_mul_f32 v[14:15], v[14:15], s[64:65] op_sel_hi:[1,0]
	v_pk_fma_f32 v[12:13], v[48:49], v[12:13], s[48:49] op_sel_hi:[1,1,0]
	v_exp_f32_e32 v14, v14
	v_exp_f32_e32 v15, v15
	v_pk_fma_f32 v[12:13], v[48:49], v[12:13], s[50:51] op_sel_hi:[1,1,0]
	v_fma_f32 v52, |v10|, s40, 1.0
	v_fma_f32 v53, |v11|, s40, 1.0
	v_pk_fma_f32 v[12:13], v[48:49], v[12:13], s[56:57] op_sel_hi:[1,1,0]
	v_rcp_f32_e32 v52, v52
	v_pk_mul_f32 v[12:13], v[48:49], v[12:13]
	v_rcp_f32_e32 v53, v53
	v_pk_mul_f32 v[12:13], v[14:15], v[12:13]
	v_max_f32_e32 v99, 0, v50
	v_fma_f32 v49, -|v50|, v12, v99
	v_max_f32_e32 v100, 0, v51
	v_fma_f32 v51, -|v51|, v13, v100
	v_mul_f32_e32 v40, v41, v41
	s_waitcnt vmcnt(0)
	v_lshlrev_b32_e32 v56, 16, v4
	v_and_b32_e32 v57, 0xffff0000, v4
	v_pk_mul_f32 v[14:15], v[10:11], v[10:11]
	v_pk_fma_f32 v[12:13], v[52:53], s[42:43], v[18:19] op_sel_hi:[1,0,0]
	v_pk_mul_f32 v[14:15], v[14:15], s[64:65] op_sel_hi:[1,0]
	v_pk_fma_f32 v[12:13], v[52:53], v[12:13], s[48:49] op_sel_hi:[1,1,0]
	v_exp_f32_e32 v14, v14
	v_exp_f32_e32 v15, v15
	v_pk_fma_f32 v[12:13], v[52:53], v[12:13], s[50:51] op_sel_hi:[1,1,0]
	v_pk_fma_f32 v[12:13], v[52:53], v[12:13], s[56:57] op_sel_hi:[1,1,0]
	v_pk_mul_f32 v[12:13], v[52:53], v[12:13]
	v_fma_f32 v58, |v56|, s40, 1.0
	v_fma_f32 v59, |v57|, s40, 1.0
	v_pk_mul_f32 v[12:13], v[14:15], v[12:13]
	v_rcp_f32_e32 v58, v58
	v_rcp_f32_e32 v59, v59
	v_max_f32_e32 v104, 0, v10
	v_fma_f32 v53, -|v10|, v12, v104
	v_max_f32_e32 v105, 0, v11
	v_fma_f32 v11, -|v11|, v13, v105
	v_lshlrev_b32_e32 v4, 16, v5
	v_and_b32_e32 v5, 0xffff0000, v5
	v_pk_mul_f32 v[14:15], v[56:57], v[56:57]
	v_pk_fma_f32 v[12:13], v[58:59], s[42:43], v[18:19] op_sel_hi:[1,0,0]
	v_pk_mul_f32 v[14:15], v[14:15], s[64:65] op_sel_hi:[1,0]
	v_pk_fma_f32 v[12:13], v[58:59], v[12:13], s[48:49] op_sel_hi:[1,1,0]
	v_exp_f32_e32 v14, v14
	v_exp_f32_e32 v15, v15
	v_pk_fma_f32 v[12:13], v[58:59], v[12:13], s[50:51] op_sel_hi:[1,1,0]
	v_fma_f32 v60, |v4|, s40, 1.0
	v_fma_f32 v61, |v5|, s40, 1.0
	v_pk_fma_f32 v[12:13], v[58:59], v[12:13], s[56:57] op_sel_hi:[1,1,0]
	v_rcp_f32_e32 v60, v60
	v_pk_mul_f32 v[12:13], v[58:59], v[12:13]
	v_rcp_f32_e32 v61, v61
	v_pk_mul_f32 v[12:13], v[14:15], v[12:13]
	v_max_f32_e32 v106, 0, v56
	v_fma_f32 v59, -|v56|, v12, v106
	v_max_f32_e32 v107, 0, v57
	v_fma_f32 v57, -|v57|, v13, v107
	v_pk_add_f32 v[24:25], v[34:35], v[36:37]
	v_mul_f32_e32 v42, v43, v43
	v_mul_f32_e32 v8, v9, v9
	v_pk_fma_f32 v[12:13], v[60:61], s[42:43], v[18:19] op_sel_hi:[1,0,0]
	v_pk_mul_f32 v[14:15], v[4:5], v[4:5]
	v_pk_fma_f32 v[12:13], v[60:61], v[12:13], s[48:49] op_sel_hi:[1,1,0]
	v_pk_mul_f32 v[14:15], v[14:15], s[64:65] op_sel_hi:[1,0]
	v_pk_fma_f32 v[12:13], v[60:61], v[12:13], s[50:51] op_sel_hi:[1,1,0]
	v_exp_f32_e32 v62, v14
	v_exp_f32_e32 v63, v15
	v_pk_fma_f32 v[64:65], v[60:61], v[12:13], s[56:57] op_sel_hi:[1,1,0]
	global_load_dwordx4 v[12:15], v[20:21], off offset:1024
	v_pk_add_f32 v[22:23], v[24:25], v[22:23]
	v_pk_add_f32 v[24:25], v[38:39], v[40:41]
	v_mul_f32_e32 v44, v45, v45
	v_mul_f32_e32 v46, v47, v47
	v_pk_add_f32 v[22:23], v[24:25], v[22:23]
	v_pk_add_f32 v[8:9], v[42:43], v[8:9]
	v_mul_f32_e32 v48, v49, v49
	v_mul_f32_e32 v50, v51, v51
	v_pk_mul_f32 v[60:61], v[60:61], v[64:65]
	v_pk_add_f32 v[8:9], v[8:9], v[22:23]
	v_pk_add_f32 v[22:23], v[44:45], v[46:47]
	v_pk_mul_f32 v[60:61], v[62:63], v[60:61]
	v_pk_add_f32 v[8:9], v[22:23], v[8:9]
	v_pk_add_f32 v[22:23], v[48:49], v[50:51]
	v_lshlrev_b32_e32 v24, 16, v6
	v_and_b32_e32 v25, 0xffff0000, v6
	v_max_f32_e32 v108, 0, v4
	v_fma_f32 v65, -|v4|, v60, v108
	v_max_f32_e32 v109, 0, v5
	v_fma_f32 v5, -|v5|, v61, v109
	v_pk_add_f32 v[8:9], v[22:23], v[8:9]
	v_mul_f32_e32 v52, v53, v53
	v_mul_f32_e32 v10, v11, v11
	v_fma_f32 v22, |v24|, s40, 1.0
	v_fma_f32 v23, |v25|, s40, 1.0
	v_mul_f32_e32 v58, v59, v59
	v_mul_f32_e32 v56, v57, v57
	v_pk_add_f32 v[10:11], v[52:53], v[10:11]
	v_rcp_f32_e32 v26, v22
	v_rcp_f32_e32 v27, v23
	v_mul_f32_e32 v64, v65, v65
	v_mul_f32_e32 v4, v5, v5
	v_pk_add_f32 v[8:9], v[10:11], v[8:9]
	v_pk_add_f32 v[10:11], v[58:59], v[56:57]
	v_pk_add_f32 v[4:5], v[64:65], v[4:5]
	v_pk_add_f32 v[8:9], v[10:11], v[8:9]
	v_cmp_gt_f32_e32 vcc, 0, v24
	v_pk_add_f32 v[22:23], v[4:5], v[8:9]
	v_pk_mul_f32 v[8:9], v[24:25], v[24:25]
	v_pk_fma_f32 v[4:5], v[26:27], s[42:43], v[18:19] op_sel_hi:[1,0,0]
	v_pk_mul_f32 v[8:9], v[8:9], s[64:65] op_sel_hi:[1,0]
	v_pk_fma_f32 v[4:5], v[26:27], v[4:5], s[48:49] op_sel_hi:[1,1,0]
	v_exp_f32_e32 v8, v8
	v_exp_f32_e32 v9, v9
	v_pk_fma_f32 v[4:5], v[26:27], v[4:5], s[50:51] op_sel_hi:[1,1,0]
	v_lshlrev_b32_e32 v6, 16, v7
	v_pk_fma_f32 v[4:5], v[26:27], v[4:5], s[56:57] op_sel_hi:[1,1,0]
	v_and_b32_e32 v7, 0xffff0000, v7
	v_pk_mul_f32 v[4:5], v[26:27], v[4:5]
	s_nop 0
	v_pk_mul_f32 v[4:5], v[8:9], v[4:5]
	s_nop 0
	v_pk_mul_f32 v[8:9], v[24:25], v[4:5]
	v_pk_fma_f32 v[4:5], v[24:25], v[4:5], v[24:25] neg_lo:[1,0,0] neg_hi:[1,0,0]
	s_nop 0
	v_cndmask_b32_e32 v11, v4, v8, vcc
	v_cmp_gt_f32_e32 vcc, 0, v25
	v_and_b32_e32 v8, 0x7fffffff, v6
	v_mul_f32_e32 v10, v11, v11
	v_cndmask_b32_e32 v5, v5, v9, vcc
	v_and_b32_e32 v9, 0x7fffffff, v7
	v_pk_fma_f32 v[8:9], v[8:9], s[40:41], 1.0 op_sel_hi:[1,0,0]
	v_mul_f32_e32 v4, v5, v5
	v_rcp_f32_e32 v8, v8
	v_rcp_f32_e32 v9, v9
	v_pk_add_f32 v[24:25], v[10:11], v[4:5]
	v_pk_mul_f32 v[10:11], v[6:7], v[6:7]
	v_cmp_gt_f32_e32 vcc, 0, v6
	v_pk_fma_f32 v[4:5], v[8:9], s[42:43], v[18:19] op_sel_hi:[1,0,0]
	v_pk_mul_f32 v[10:11], v[10:11], s[64:65] op_sel_hi:[1,0]
	v_pk_fma_f32 v[4:5], v[8:9], v[4:5], s[48:49] op_sel_hi:[1,1,0]
	v_exp_f32_e32 v10, v10
	v_exp_f32_e32 v11, v11
	v_pk_fma_f32 v[4:5], v[8:9], v[4:5], s[50:51] op_sel_hi:[1,1,0]
	v_pk_add_f32 v[22:23], v[24:25], v[22:23]
	v_pk_fma_f32 v[4:5], v[8:9], v[4:5], s[56:57] op_sel_hi:[1,1,0]
	s_nop 0
	v_pk_mul_f32 v[4:5], v[8:9], v[4:5]
	s_nop 0
	v_pk_mul_f32 v[4:5], v[10:11], v[4:5]
	global_load_dwordx4 v[8:11], v[20:21], off offset:1280
	s_waitcnt vmcnt(1)
	v_lshlrev_b32_e32 v32, 16, v12
	v_and_b32_e32 v33, 0xffff0000, v12
	v_fma_f32 v30, |v32|, s40, 1.0
	v_fma_f32 v31, |v33|, s40, 1.0
	v_pk_mul_f32 v[28:29], v[6:7], v[4:5]
	v_rcp_f32_e32 v30, v30
	v_rcp_f32_e32 v31, v31
	v_pk_fma_f32 v[4:5], v[6:7], v[4:5], v[6:7] neg_lo:[1,0,0] neg_hi:[1,0,0]
	v_lshlrev_b32_e32 v34, 16, v13
	v_cndmask_b32_e32 v27, v4, v28, vcc
	v_cmp_gt_f32_e32 vcc, 0, v7
	v_pk_mul_f32 v[6:7], v[32:33], v[32:33]
	v_and_b32_e32 v35, 0xffff0000, v13
	v_cndmask_b32_e32 v29, v5, v29, vcc
	v_pk_fma_f32 v[4:5], v[30:31], s[42:43], v[18:19] op_sel_hi:[1,0,0]
	v_pk_mul_f32 v[6:7], v[6:7], s[64:65] op_sel_hi:[1,0]
	v_pk_fma_f32 v[4:5], v[30:31], v[4:5], s[48:49] op_sel_hi:[1,1,0]
	v_exp_f32_e32 v6, v6
	v_exp_f32_e32 v7, v7
	v_pk_fma_f32 v[4:5], v[30:31], v[4:5], s[50:51] op_sel_hi:[1,1,0]
	v_pk_fma_f32 v[4:5], v[30:31], v[4:5], s[56:57] op_sel_hi:[1,1,0]
	v_fma_f32 v12, |v34|, s40, 1.0
	v_fma_f32 v13, |v35|, s40, 1.0
	v_pk_mul_f32 v[4:5], v[30:31], v[4:5]
	v_rcp_f32_e32 v36, v12
	v_rcp_f32_e32 v37, v13
	v_pk_mul_f32 v[4:5], v[6:7], v[4:5]
	v_max_f32_e32 v110, 0, v32
	v_fma_f32 v31, -|v32|, v4, v110
	v_max_f32_e32 v111, 0, v33
	v_fma_f32 v13, -|v33|, v5, v111
	v_lshlrev_b32_e32 v38, 16, v14
	v_and_b32_e32 v39, 0xffff0000, v14
	v_lshlrev_b32_e32 v40, 16, v15
	v_pk_fma_f32 v[4:5], v[36:37], s[42:43], v[18:19] op_sel_hi:[1,0,0]
	v_pk_mul_f32 v[6:7], v[34:35], v[34:35]
	v_pk_fma_f32 v[4:5], v[36:37], v[4:5], s[48:49] op_sel_hi:[1,1,0]
	v_pk_mul_f32 v[6:7], v[6:7], s[64:65] op_sel_hi:[1,0]
	v_pk_fma_f32 v[4:5], v[36:37], v[4:5], s[50:51] op_sel_hi:[1,1,0]
	v_exp_f32_e32 v6, v6
	v_exp_f32_e32 v7, v7
	v_pk_fma_f32 v[4:5], v[36:37], v[4:5], s[56:57] op_sel_hi:[1,1,0]
	v_pk_mul_f32 v[4:5], v[36:37], v[4:5]
	v_fma_f32 v36, |v38|, s40, 1.0
	v_fma_f32 v37, |v39|, s40, 1.0
	v_pk_mul_f32 v[4:5], v[6:7], v[4:5]
	v_rcp_f32_e32 v36, v36
	v_rcp_f32_e32 v37, v37
	v_max_f32_e32 v112, 0, v34
	v_fma_f32 v33, -|v34|, v4, v112
	v_max_f32_e32 v113, 0, v35
	v_fma_f32 v35, -|v35|, v5, v113
	v_and_b32_e32 v41, 0xffff0000, v15
	v_pk_mul_f32 v[6:7], v[38:39], v[38:39]
	v_pk_fma_f32 v[4:5], v[36:37], s[42:43], v[18:19] op_sel_hi:[1,0,0]
	v_pk_mul_f32 v[6:7], v[6:7], s[64:65] op_sel_hi:[1,0]
	v_pk_fma_f32 v[4:5], v[36:37], v[4:5], s[48:49] op_sel_hi:[1,1,0]
	v_exp_f32_e32 v6, v6
	v_exp_f32_e32 v7, v7
	v_pk_fma_f32 v[4:5], v[36:37], v[4:5], s[50:51] op_sel_hi:[1,1,0]
	v_fma_f32 v14, |v40|, s40, 1.0
	v_fma_f32 v15, |v41|, s40, 1.0
	v_pk_fma_f32 v[4:5], v[36:37], v[4:5], s[56:57] op_sel_hi:[1,1,0]
	v_rcp_f32_e32 v42, v14
	v_pk_mul_f32 v[4:5], v[36:37], v[4:5]
	v_rcp_f32_e32 v43, v15
	v_pk_mul_f32 v[4:5], v[6:7], v[4:5]
	v_max_f32_e32 v114, 0, v38
	v_fma_f32 v37, -|v38|, v4, v114
	v_max_f32_e32 v115, 0, v39
	v_fma_f32 v15, -|v39|, v5, v115
	v_mul_f32_e32 v26, v27, v27
	s_waitcnt vmcnt(0)
	v_lshlrev_b32_e32 v44, 16, v8
	v_and_b32_e32 v45, 0xffff0000, v8
	v_pk_fma_f32 v[4:5], v[42:43], s[42:43], v[18:19] op_sel_hi:[1,0,0]
	v_pk_mul_f32 v[6:7], v[40:41], v[40:41]
	v_pk_fma_f32 v[4:5], v[42:43], v[4:5], s[48:49] op_sel_hi:[1,1,0]
	v_pk_mul_f32 v[6:7], v[6:7], s[64:65] op_sel_hi:[1,0]
	v_pk_fma_f32 v[4:5], v[42:43], v[4:5], s[50:51] op_sel_hi:[1,1,0]
	v_exp_f32_e32 v6, v6
	v_exp_f32_e32 v7, v7
	v_pk_fma_f32 v[4:5], v[42:43], v[4:5], s[56:57] op_sel_hi:[1,1,0]
	v_pk_mul_f32 v[4:5], v[42:43], v[4:5]
	v_fma_f32 v42, |v44|, s40, 1.0
	v_fma_f32 v43, |v45|, s40, 1.0
	v_pk_mul_f32 v[4:5], v[6:7], v[4:5]
	v_rcp_f32_e32 v42, v42
	v_rcp_f32_e32 v43, v43
	v_max_f32_e32 v116, 0, v40
	v_fma_f32 v39, -|v40|, v4, v116
	v_max_f32_e32 v117, 0, v41
	v_fma_f32 v41, -|v41|, v5, v117
	v_lshlrev_b32_e32 v50, 16, v9
	v_and_b32_e32 v51, 0xffff0000, v9
	v_pk_mul_f32 v[6:7], v[44:45], v[44:45]
	v_pk_fma_f32 v[4:5], v[42:43], s[42:43], v[18:19] op_sel_hi:[1,0,0]
	v_pk_mul_f32 v[6:7], v[6:7], s[64:65] op_sel_hi:[1,0]
	v_pk_fma_f32 v[4:5], v[42:43], v[4:5], s[48:49] op_sel_hi:[1,1,0]
	v_exp_f32_e32 v6, v6
	v_exp_f32_e32 v7, v7
	v_pk_fma_f32 v[4:5], v[42:43], v[4:5], s[50:51] op_sel_hi:[1,1,0]
	v_pk_fma_f32 v[4:5], v[42:43], v[4:5], s[56:57] op_sel_hi:[1,1,0]
	v_fma_f32 v8, |v50|, s40, 1.0
	v_fma_f32 v9, |v51|, s40, 1.0
	v_pk_mul_f32 v[4:5], v[42:43], v[4:5]
	v_rcp_f32_e32 v52, v8
	v_pk_mul_f32 v[42:43], v[6:7], v[4:5]
	global_load_dwordx4 v[4:7], v[20:21], off offset:1536
	v_rcp_f32_e32 v53, v9
	v_max_f32_e32 v81, 0, v45
	v_fma_f32 v9, -|v45|, v43, v81
	v_max_f32_e32 v80, 0, v44
	v_fma_f32 v43, -|v44|, v42, v80
	v_lshlrev_b32_e32 v58, 16, v11
	v_and_b32_e32 v59, 0xffff0000, v11
	v_pk_fma_f32 v[44:45], v[52:53], s[42:43], v[18:19] op_sel_hi:[1,0,0]
	v_and_b32_e32 v11, 0x7fffffff, v59
	v_pk_fma_f32 v[44:45], v[52:53], v[44:45], s[48:49] op_sel_hi:[1,1,0]
	v_pk_mul_f32 v[46:47], v[50:51], v[50:51]
	v_pk_fma_f32 v[44:45], v[52:53], v[44:45], s[50:51] op_sel_hi:[1,1,0]
	v_pk_mul_f32 v[46:47], v[46:47], s[64:65] op_sel_hi:[1,0]
	v_pk_fma_f32 v[44:45], v[52:53], v[44:45], s[56:57] op_sel_hi:[1,1,0]
	v_exp_f32_e32 v46, v46
	v_exp_f32_e32 v47, v47
	v_pk_mul_f32 v[44:45], v[52:53], v[44:45]
	v_lshlrev_b32_e32 v52, 16, v10
	v_and_b32_e32 v53, 0xffff0000, v10
	v_fma_f32 v56, |v52|, s40, 1.0
	v_fma_f32 v57, |v53|, s40, 1.0
	v_pk_mul_f32 v[44:45], v[46:47], v[44:45]
	v_rcp_f32_e32 v56, v56
	v_rcp_f32_e32 v57, v57
	v_max_f32_e32 v83, 0, v51
	v_fma_f32 v47, -|v51|, v45, v83
	v_max_f32_e32 v82, 0, v50
	v_fma_f32 v45, -|v50|, v44, v82
	v_and_b32_e32 v10, 0x7fffffff, v58
	v_pk_fma_f32 v[10:11], v[10:11], s[40:41], 1.0 op_sel_hi:[1,0,0]
	v_pk_mul_f32 v[50:51], v[52:53], v[52:53]
	v_rcp_f32_e32 v60, v10
	v_pk_fma_f32 v[48:49], v[56:57], s[42:43], v[18:19] op_sel_hi:[1,0,0]
	v_pk_mul_f32 v[50:51], v[50:51], s[64:65] op_sel_hi:[1,0]
	v_pk_fma_f32 v[48:49], v[56:57], v[48:49], s[48:49] op_sel_hi:[1,1,0]
	v_exp_f32_e32 v50, v50
	v_exp_f32_e32 v51, v51
	v_pk_fma_f32 v[48:49], v[56:57], v[48:49], s[50:51] op_sel_hi:[1,1,0]
	v_rcp_f32_e32 v61, v11
	v_pk_fma_f32 v[48:49], v[56:57], v[48:49], s[56:57] op_sel_hi:[1,1,0]
	v_pk_mul_f32 v[48:49], v[56:57], v[48:49]
	v_mul_f32_e32 v28, v29, v29
	v_pk_mul_f32 v[48:49], v[50:51], v[48:49]
	v_mul_f32_e32 v30, v31, v31
	v_max_f32_e32 v85, 0, v53
	v_fma_f32 v11, -|v53|, v49, v85
	v_max_f32_e32 v84, 0, v52
	v_fma_f32 v49, -|v52|, v48, v84
	v_mul_f32_e32 v12, v13, v13
	v_pk_mul_f32 v[52:53], v[58:59], v[58:59]
	v_pk_add_f32 v[24:25], v[26:27], v[28:29]
	v_pk_fma_f32 v[50:51], v[60:61], s[42:43], v[18:19] op_sel_hi:[1,0,0]
	v_pk_mul_f32 v[52:53], v[52:53], s[64:65] op_sel_hi:[1,0]
	v_pk_fma_f32 v[50:51], v[60:61], v[50:51], s[48:49] op_sel_hi:[1,1,0]
	v_exp_f32_e32 v52, v52
	v_exp_f32_e32 v53, v53
	v_pk_fma_f32 v[50:51], v[60:61], v[50:51], s[50:51] op_sel_hi:[1,1,0]
	v_pk_fma_f32 v[50:51], v[60:61], v[50:51], s[56:57] op_sel_hi:[1,1,0]
	v_mul_f32_e32 v32, v33, v33
	v_pk_mul_f32 v[50:51], v[60:61], v[50:51]
	v_mul_f32_e32 v34, v35, v35
	v_pk_mul_f32 v[50:51], v[52:53], v[50:51]
	v_pk_add_f32 v[22:23], v[24:25], v[22:23]
	v_max_f32_e32 v86, 0, v58
	v_fma_f32 v63, -|v58|, v50, v86
	v_max_f32_e32 v90, 0, v59
	v_fma_f32 v57, -|v59|, v51, v90
	global_load_dwordx4 v[50:53], v[20:21], off offset:1792
	v_pk_add_f32 v[12:13], v[30:31], v[12:13]
	v_mul_f32_e32 v36, v37, v37
	s_waitcnt vmcnt(1)
	v_lshlrev_b32_e32 v20, 16, v4
	v_and_b32_e32 v21, 0xffff0000, v4
	v_fma_f32 v64, |v20|, s40, 1.0
	v_fma_f32 v65, |v21|, s40, 1.0
	v_pk_mul_f32 v[60:61], v[20:21], v[20:21]
	v_rcp_f32_e32 v64, v64
	v_rcp_f32_e32 v65, v65
	v_mul_f32_e32 v14, v15, v15
	v_pk_mul_f32 v[60:61], v[60:61], s[64:65] op_sel_hi:[1,0]
	v_pk_add_f32 v[12:13], v[12:13], v[22:23]
	v_pk_fma_f32 v[58:59], v[64:65], s[42:43], v[18:19] op_sel_hi:[1,0,0]
	v_pk_add_f32 v[22:23], v[32:33], v[34:35]
	v_mul_f32_e32 v38, v39, v39
	v_mul_f32_e32 v40, v41, v41
	v_pk_fma_f32 v[58:59], v[64:65], v[58:59], s[48:49] op_sel_hi:[1,1,0]
	v_exp_f32_e32 v60, v60
	v_exp_f32_e32 v61, v61
	v_pk_add_f32 v[12:13], v[22:23], v[12:13]
	v_pk_add_f32 v[14:15], v[36:37], v[14:15]
	v_mul_f32_e32 v42, v43, v43
	v_mul_f32_e32 v8, v9, v9
	v_pk_fma_f32 v[58:59], v[64:65], v[58:59], s[50:51] op_sel_hi:[1,1,0]
	v_pk_add_f32 v[12:13], v[14:15], v[12:13]
	v_pk_add_f32 v[14:15], v[38:39], v[40:41]
	v_mul_f32_e32 v44, v45, v45
	v_mul_f32_e32 v46, v47, v47
	v_pk_fma_f32 v[58:59], v[64:65], v[58:59], s[56:57] op_sel_hi:[1,1,0]
	v_pk_add_f32 v[12:13], v[14:15], v[12:13]
	v_pk_add_f32 v[8:9], v[42:43], v[8:9]
	v_pk_mul_f32 v[58:59], v[64:65], v[58:59]
	v_pk_add_f32 v[8:9], v[8:9], v[12:13]
	v_pk_add_f32 v[12:13], v[44:45], v[46:47]
	v_lshlrev_b32_e32 v4, 16, v5
	v_and_b32_e32 v5, 0xffff0000, v5
	v_pk_mul_f32 v[58:59], v[60:61], v[58:59]
	v_pk_add_f32 v[8:9], v[12:13], v[8:9]
	v_max_f32_e32 v91, 0, v20
	v_fma_f32 v65, -|v20|, v58, v91
	v_max_f32_e32 v92, 0, v21
	v_fma_f32 v21, -|v21|, v59, v92
	v_fma_f32 v12, |v4|, s40, 1.0
	v_fma_f32 v13, |v5|, s40, 1.0
	v_mul_f32_e32 v48, v49, v49
	v_mul_f32_e32 v10, v11, v11
	v_rcp_f32_e32 v12, v12
	v_rcp_f32_e32 v13, v13
	v_mul_f32_e32 v62, v63, v63
	v_mul_f32_e32 v56, v57, v57
	v_pk_add_f32 v[10:11], v[48:49], v[10:11]
	v_mul_f32_e32 v64, v65, v65
	v_mul_f32_e32 v20, v21, v21
	v_pk_add_f32 v[8:9], v[10:11], v[8:9]
	v_pk_add_f32 v[10:11], v[62:63], v[56:57]
	v_pk_mul_f32 v[14:15], v[4:5], v[4:5]
	v_pk_add_f32 v[8:9], v[10:11], v[8:9]
	v_pk_add_f32 v[10:11], v[64:65], v[20:21]
	v_pk_mul_f32 v[14:15], v[14:15], s[64:65] op_sel_hi:[1,0]
	v_pk_add_f32 v[8:9], v[10:11], v[8:9]
	v_pk_fma_f32 v[10:11], v[12:13], s[42:43], v[18:19] op_sel_hi:[1,0,0]
	v_exp_f32_e32 v14, v14
	v_pk_fma_f32 v[10:11], v[12:13], v[10:11], s[48:49] op_sel_hi:[1,1,0]
	v_exp_f32_e32 v15, v15
	v_pk_fma_f32 v[10:11], v[12:13], v[10:11], s[50:51] op_sel_hi:[1,1,0]
	v_pk_fma_f32 v[10:11], v[12:13], v[10:11], s[56:57] op_sel_hi:[1,1,0]
	s_waitcnt vmcnt(0)
	v_lshlrev_b32_e32 v24, 16, v50
	v_pk_mul_f32 v[10:11], v[12:13], v[10:11]
	v_and_b32_e32 v25, 0xffff0000, v50
	v_pk_mul_f32 v[10:11], v[14:15], v[10:11]
	v_and_b32_e32 v27, 0x7fffffff, v25
	v_max_f32_e32 v93, 0, v4
	v_fma_f32 v15, -|v4|, v10, v93
	v_max_f32_e32 v94, 0, v5
	v_fma_f32 v5, -|v5|, v11, v94
	v_and_b32_e32 v26, 0x7fffffff, v24
	v_lshlrev_b32_e32 v10, 16, v6
	v_and_b32_e32 v12, 0x7fffffff, v10
	v_and_b32_e32 v11, 0xffff0000, v6
	v_and_b32_e32 v13, 0x7fffffff, v11
	v_pk_fma_f32 v[12:13], v[12:13], s[40:41], 1.0 op_sel_hi:[1,0,0]
	v_mul_f32_e32 v14, v15, v15
	v_rcp_f32_e32 v12, v12
	v_rcp_f32_e32 v13, v13
	v_mul_f32_e32 v4, v5, v5
	v_pk_mul_f32 v[20:21], v[10:11], v[10:11]
	v_pk_add_f32 v[4:5], v[14:15], v[4:5]
	v_pk_fma_f32 v[14:15], v[12:13], s[42:43], v[18:19] op_sel_hi:[1,0,0]
	v_pk_mul_f32 v[20:21], v[20:21], s[64:65] op_sel_hi:[1,0]
	v_pk_fma_f32 v[14:15], v[12:13], v[14:15], s[48:49] op_sel_hi:[1,1,0]
	v_exp_f32_e32 v20, v20
	v_exp_f32_e32 v21, v21
	v_pk_fma_f32 v[14:15], v[12:13], v[14:15], s[50:51] op_sel_hi:[1,1,0]
	v_lshlrev_b32_e32 v6, 16, v7
	v_and_b32_e32 v7, 0xffff0000, v7
	v_pk_fma_f32 v[14:15], v[12:13], v[14:15], s[56:57] op_sel_hi:[1,1,0]
	v_pk_mul_f32 v[12:13], v[12:13], v[14:15]
	v_fma_f32 v22, |v6|, s40, 1.0
	v_fma_f32 v23, |v7|, s40, 1.0
	v_pk_mul_f32 v[12:13], v[20:21], v[12:13]
	v_rcp_f32_e32 v22, v22
	v_rcp_f32_e32 v23, v23
	v_max_f32_e32 v95, 0, v10
	v_fma_f32 v21, -|v10|, v12, v95
	v_max_f32_e32 v96, 0, v11
	v_fma_f32 v11, -|v11|, v13, v96
	v_pk_fma_f32 v[26:27], v[26:27], s[40:41], 1.0 op_sel_hi:[1,0,0]
	v_lshlrev_b32_e32 v28, 16, v51
	v_rcp_f32_e32 v26, v26
	v_rcp_f32_e32 v27, v27
	v_pk_mul_f32 v[14:15], v[6:7], v[6:7]
	v_pk_fma_f32 v[12:13], v[22:23], s[42:43], v[18:19] op_sel_hi:[1,0,0]
	v_pk_mul_f32 v[14:15], v[14:15], s[64:65] op_sel_hi:[1,0]
	v_pk_fma_f32 v[12:13], v[22:23], v[12:13], s[48:49] op_sel_hi:[1,1,0]
	v_exp_f32_e32 v14, v14
	v_exp_f32_e32 v15, v15
	v_pk_fma_f32 v[12:13], v[22:23], v[12:13], s[50:51] op_sel_hi:[1,1,0]
	v_pk_fma_f32 v[12:13], v[22:23], v[12:13], s[56:57] op_sel_hi:[1,1,0]
	v_and_b32_e32 v29, 0xffff0000, v51
	v_pk_mul_f32 v[12:13], v[22:23], v[12:13]
	v_pk_mul_f32 v[12:13], v[14:15], v[12:13]
	v_max_f32_e32 v97, 0, v6
	v_fma_f32 v23, -|v6|, v12, v97
	v_max_f32_e32 v98, 0, v7
	v_fma_f32 v7, -|v7|, v13, v98
	v_fma_f32 v30, |v28|, s40, 1.0
	v_fma_f32 v31, |v29|, s40, 1.0
	v_rcp_f32_e32 v30, v30
	v_rcp_f32_e32 v31, v31
	v_pk_mul_f32 v[14:15], v[24:25], v[24:25]
	v_pk_fma_f32 v[12:13], v[26:27], s[42:43], v[18:19] op_sel_hi:[1,0,0]
	v_pk_mul_f32 v[14:15], v[14:15], s[64:65] op_sel_hi:[1,0]
	v_pk_fma_f32 v[12:13], v[26:27], v[12:13], s[48:49] op_sel_hi:[1,1,0]
	v_exp_f32_e32 v14, v14
	v_exp_f32_e32 v15, v15
	v_pk_fma_f32 v[12:13], v[26:27], v[12:13], s[50:51] op_sel_hi:[1,1,0]
	v_pk_fma_f32 v[12:13], v[26:27], v[12:13], s[56:57] op_sel_hi:[1,1,0]
	v_lshlrev_b32_e32 v32, 16, v52
	v_pk_mul_f32 v[12:13], v[26:27], v[12:13]
	v_and_b32_e32 v33, 0xffff0000, v52
	v_pk_mul_f32 v[12:13], v[14:15], v[12:13]
	v_max_f32_e32 v99, 0, v24
	v_fma_f32 v27, -|v24|, v12, v99
	v_max_f32_e32 v100, 0, v25
	v_fma_f32 v13, -|v25|, v13, v100
	v_pk_mul_f32 v[24:25], v[28:29], v[28:29]
	v_fma_f32 v34, |v32|, s40, 1.0
	v_fma_f32 v35, |v33|, s40, 1.0
	v_pk_fma_f32 v[14:15], v[30:31], s[42:43], v[18:19] op_sel_hi:[1,0,0]
	v_pk_mul_f32 v[24:25], v[24:25], s[64:65] op_sel_hi:[1,0]
	v_pk_fma_f32 v[14:15], v[30:31], v[14:15], s[48:49] op_sel_hi:[1,1,0]
	v_exp_f32_e32 v24, v24
	v_exp_f32_e32 v25, v25
	v_pk_fma_f32 v[14:15], v[30:31], v[14:15], s[50:51] op_sel_hi:[1,1,0]
	v_rcp_f32_e32 v34, v34
	v_pk_fma_f32 v[14:15], v[30:31], v[14:15], s[56:57] op_sel_hi:[1,1,0]
	v_rcp_f32_e32 v35, v35
	v_pk_mul_f32 v[14:15], v[30:31], v[14:15]
	v_pk_mul_f32 v[14:15], v[24:25], v[14:15]
	v_lshlrev_b32_e32 v36, 16, v53
	v_max_f32_e32 v104, 0, v28
	v_fma_f32 v31, -|v28|, v14, v104
	v_max_f32_e32 v105, 0, v29
	v_fma_f32 v15, -|v29|, v15, v105
	v_and_b32_e32 v37, 0xffff0000, v53
	v_pk_mul_f32 v[28:29], v[32:33], v[32:33]
	v_pk_fma_f32 v[24:25], v[34:35], s[42:43], v[18:19] op_sel_hi:[1,0,0]
	v_pk_mul_f32 v[28:29], v[28:29], s[64:65] op_sel_hi:[1,0]
	v_pk_fma_f32 v[24:25], v[34:35], v[24:25], s[48:49] op_sel_hi:[1,1,0]
	v_exp_f32_e32 v28, v28
	v_exp_f32_e32 v29, v29
	v_pk_fma_f32 v[24:25], v[34:35], v[24:25], s[50:51] op_sel_hi:[1,1,0]
	v_pk_fma_f32 v[24:25], v[34:35], v[24:25], s[56:57] op_sel_hi:[1,1,0]
	v_fma_f32 v38, |v36|, s40, 1.0
	v_fma_f32 v39, |v37|, s40, 1.0
	v_pk_mul_f32 v[24:25], v[34:35], v[24:25]
	v_rcp_f32_e32 v38, v38
	v_pk_mul_f32 v[24:25], v[28:29], v[24:25]
	v_rcp_f32_e32 v39, v39
	v_max_f32_e32 v106, 0, v32
	v_fma_f32 v35, -|v32|, v24, v106
	v_max_f32_e32 v107, 0, v33
	v_fma_f32 v25, -|v33|, v25, v107
	v_pk_fma_f32 v[18:19], v[38:39], s[42:43], v[18:19] op_sel_hi:[1,0,0]
	v_mul_f32_e32 v20, v21, v21
	v_pk_fma_f32 v[18:19], v[38:39], v[18:19], s[48:49] op_sel_hi:[1,1,0]
	v_mul_f32_e32 v10, v11, v11
	v_pk_mul_f32 v[28:29], v[36:37], v[36:37]
	v_pk_fma_f32 v[18:19], v[38:39], v[18:19], s[50:51] op_sel_hi:[1,1,0]
	v_pk_mul_f32 v[28:29], v[28:29], s[64:65] op_sel_hi:[1,0]
	v_pk_fma_f32 v[18:19], v[38:39], v[18:19], s[56:57] op_sel_hi:[1,1,0]
	v_exp_f32_e32 v28, v28
	v_exp_f32_e32 v29, v29
	v_pk_mul_f32 v[18:19], v[38:39], v[18:19]
	v_mul_f32_e32 v22, v23, v23
	v_mul_f32_e32 v6, v7, v7
	v_pk_mul_f32 v[18:19], v[28:29], v[18:19]
	v_pk_add_f32 v[4:5], v[4:5], v[8:9]
	v_pk_add_f32 v[8:9], v[20:21], v[10:11]
	v_mul_f32_e32 v26, v27, v27
	v_mul_f32_e32 v12, v13, v13
	v_max_f32_e32 v108, 0, v36
	v_fma_f32 v33, -|v36|, v18, v108
	v_max_f32_e32 v109, 0, v37
	v_fma_f32 v19, -|v37|, v19, v109
	v_pk_add_f32 v[4:5], v[8:9], v[4:5]
	v_pk_add_f32 v[6:7], v[22:23], v[6:7]
	v_mul_f32_e32 v30, v31, v31
	v_mul_f32_e32 v14, v15, v15
	v_pk_add_f32 v[4:5], v[6:7], v[4:5]
	v_pk_add_f32 v[6:7], v[26:27], v[12:13]
	v_mul_f32_e32 v34, v35, v35
	v_mul_f32_e32 v24, v25, v25
	v_pk_add_f32 v[4:5], v[6:7], v[4:5]
	v_pk_add_f32 v[6:7], v[30:31], v[14:15]
	v_mul_f32_e32 v32, v33, v33
	v_mul_f32_e32 v18, v19, v19
	v_cmp_lt_i32_e32 vcc, v167, v161
	v_pk_add_f32 v[4:5], v[6:7], v[4:5]
	v_pk_add_f32 v[6:7], v[34:35], v[24:25]
	v_cndmask_b32_e32 v17, v160, v167, vcc
	v_pk_add_f32 v[4:5], v[6:7], v[4:5]
	v_pk_add_f32 v[6:7], v[32:33], v[18:19]
	v_lshlrev_b32_e32 v56, 2, v17
	v_pk_add_f32 v[4:5], v[6:7], v[4:5]
	ds_bpermute_b32 v7, v56, v5
	ds_bpermute_b32 v6, v56, v4
	v_cmp_lt_i32_e32 vcc, v166, v161
	s_waitcnt lgkmcnt(0)
	v_pk_add_f32 v[4:5], v[4:5], v[6:7]
	v_cndmask_b32_e32 v8, v160, v166, vcc
	v_lshlrev_b32_e32 v57, 2, v8
	ds_bpermute_b32 v7, v57, v5
	ds_bpermute_b32 v6, v57, v4
	v_cmp_lt_i32_e32 vcc, v165, v161
	s_waitcnt lgkmcnt(0)
	v_pk_add_f32 v[4:5], v[4:5], v[6:7]
	v_cndmask_b32_e32 v8, v160, v165, vcc
	v_lshlrev_b32_e32 v58, 2, v8
	ds_bpermute_b32 v7, v58, v5
	ds_bpermute_b32 v6, v58, v4
	v_cmp_lt_i32_e32 vcc, v164, v161
	s_waitcnt lgkmcnt(0)
	v_pk_add_f32 v[4:5], v[4:5], v[6:7]
	v_cndmask_b32_e32 v6, v160, v164, vcc
	v_lshlrev_b32_e32 v59, 2, v6
	ds_bpermute_b32 v7, v59, v5
	ds_bpermute_b32 v6, v59, v4
	v_cmp_eq_u32_e32 vcc, 0, v54
	s_and_saveexec_b64 s[8:9], vcc
	s_cbranch_execz .LBB0_445
	s_waitcnt lgkmcnt(0)
	v_pk_add_f32 v[4:5], v[4:5], v[6:7]
	s_nop 0
	v_pk_mul_f32 v[4:5], v[4:5], s[66:67] op_sel_hi:[1,0]
	s_nop 0
	v_fma_f32 v4, -v5, v5, v4
	v_max_f32_e32 v4, 0, v4
	v_add_f32_e32 v4, 0x358637bd, v4
	v_mul_f32_e32 v6, 0x4b800000, v4
	v_cmp_gt_f32_e64 s[0:1], s36, v4
	s_nop 1
	v_cndmask_b32_e64 v4, v4, v6, s[0:1]
	v_rsq_f32_e32 v4, v4
	v_lshl_add_u32 v6, v16, 2, 0
	v_add_u32_e32 v7, 0x11000, v6
	ds_write_b32 v7, v5
	v_mul_f32_e32 v5, 0x45800000, v4
	v_cndmask_b32_e64 v4, v4, v5, s[0:1]
	v_add_u32_e32 v5, 0x11200, v6
	ds_write_b32 v5, v4
.LBB0_445:
	s_or_b64 exec, exec, s[8:9]
	v_or_b32_e32 v20, 4, v16
	v_ashrrev_i32_e32 v21, 31, v20
	v_lshl_add_u64 v[4:5], s[6:7], 0, v[20:21]
	s_waitcnt lgkmcnt(0)
	v_lshlrev_b32_e32 v6, 3, v54
	v_lshlrev_b64 v[4:5], 11, v[4:5]
	v_lshl_add_u64 v[4:5], s[4:5], 0, v[4:5]
	v_lshlrev_b32_e32 v18, 1, v6
	v_mov_b32_e32 v19, v2
	v_lshl_add_u64 v[24:25], v[4:5], 0, v[18:19]
	global_load_dwordx4 v[8:11], v[24:25], off
	global_load_dwordx4 v[4:7], v[24:25], off offset:256
	v_mov_b64_e32 v[22:23], s[44:45]
	v_mov_b32_e32 v13, v2
	s_waitcnt vmcnt(1)
	v_lshlrev_b32_e32 v28, 16, v10
	v_and_b32_e32 v29, 0xffff0000, v10
	v_and_b32_e32 v15, 0xffff0000, v8
	v_and_b32_e32 v27, 0xffff0000, v9
	v_lshlrev_b32_e32 v26, 16, v9
	v_lshlrev_b32_e32 v14, 16, v8
	v_lshlrev_b32_e32 v8, 16, v11
	v_and_b32_e32 v9, 0xffff0000, v11
	v_fma_f32 v10, |v28|, s40, 1.0
	v_fma_f32 v11, |v29|, s40, 1.0
	v_fma_f32 v32, |v14|, s40, 1.0
	v_fma_f32 v33, |v15|, s40, 1.0
	v_rcp_f32_e32 v10, v10
	v_rcp_f32_e32 v11, v11
	v_fma_f32 v36, |v26|, s40, 1.0
	v_fma_f32 v37, |v27|, s40, 1.0
	v_rcp_f32_e32 v32, v32
	v_rcp_f32_e32 v33, v33
	v_rcp_f32_e32 v36, v36
	v_rcp_f32_e32 v37, v37
	v_pk_mul_f32 v[30:31], v[28:29], v[28:29]
	v_pk_mul_f32 v[34:35], v[14:15], v[14:15]
	v_pk_mul_f32 v[30:31], v[30:31], s[64:65] op_sel_hi:[1,0]
	v_pk_fma_f32 v[44:45], v[10:11], s[42:43], v[22:23] op_sel_hi:[1,0,0]
	v_pk_mul_f32 v[38:39], v[26:27], v[26:27]
	v_pk_mul_f32 v[34:35], v[34:35], s[64:65] op_sel_hi:[1,0]
	v_exp_f32_e32 v30, v30
	v_exp_f32_e32 v31, v31
	v_pk_fma_f32 v[46:47], v[32:33], s[42:43], v[22:23] op_sel_hi:[1,0,0]
	v_pk_fma_f32 v[44:45], v[10:11], v[44:45], s[48:49] op_sel_hi:[1,1,0]
	v_pk_mul_f32 v[38:39], v[38:39], s[64:65] op_sel_hi:[1,0]
	v_exp_f32_e32 v34, v34
	v_exp_f32_e32 v35, v35
	v_pk_fma_f32 v[48:49], v[36:37], s[42:43], v[22:23] op_sel_hi:[1,0,0]
	v_pk_fma_f32 v[46:47], v[32:33], v[46:47], s[48:49] op_sel_hi:[1,1,0]
	v_pk_fma_f32 v[44:45], v[10:11], v[44:45], s[50:51] op_sel_hi:[1,1,0]
	v_exp_f32_e32 v38, v38
	v_exp_f32_e32 v39, v39
	v_pk_fma_f32 v[48:49], v[36:37], v[48:49], s[48:49] op_sel_hi:[1,1,0]
	v_pk_fma_f32 v[46:47], v[32:33], v[46:47], s[50:51] op_sel_hi:[1,1,0]
	v_pk_fma_f32 v[44:45], v[10:11], v[44:45], s[56:57] op_sel_hi:[1,1,0]
	v_pk_fma_f32 v[48:49], v[36:37], v[48:49], s[50:51] op_sel_hi:[1,1,0]
	v_pk_fma_f32 v[46:47], v[32:33], v[46:47], s[56:57] op_sel_hi:[1,1,0]
	v_pk_mul_f32 v[10:11], v[10:11], v[44:45]
	v_pk_fma_f32 v[48:49], v[36:37], v[48:49], s[56:57] op_sel_hi:[1,1,0]
	v_pk_mul_f32 v[32:33], v[32:33], v[46:47]
	v_pk_mul_f32 v[10:11], v[30:31], v[10:11]
	v_pk_mul_f32 v[36:37], v[36:37], v[48:49]
	v_pk_mul_f32 v[30:31], v[34:35], v[32:33]
	v_max_f32_e32 v110, 0, v28
	v_fma_f32 v45, -|v28|, v10, v110
	v_max_f32_e32 v111, 0, v29
	v_fma_f32 v11, -|v29|, v11, v111
	v_pk_mul_f32 v[32:33], v[38:39], v[36:37]
	v_pk_mul_f32 v[36:37], v[30:31], v[14:15]
	v_max_f32_e32 v112, 0, v26
	v_fma_f32 v29, -|v26|, v32, v112
	v_max_f32_e32 v113, 0, v27
	v_fma_f32 v27, -|v27|, v33, v113
	v_pk_fma_f32 v[30:31], v[30:31], v[14:15], v[14:15] neg_lo:[1,0,0] neg_hi:[1,0,0]
	v_cmp_gt_f32_e64 s[0:1], 0, v14
	v_fma_f32 v40, |v8|, s40, 1.0
	v_fma_f32 v41, |v9|, s40, 1.0
	v_cndmask_b32_e64 v28, v30, v36, s[0:1]
	v_cmp_gt_f32_e64 s[0:1], 0, v15
	v_mul_f32_e32 v30, v28, v28
	v_mov_b32_e32 v14, v29
	v_cndmask_b32_e64 v15, v31, v37, s[0:1]
	v_mov_b32_e32 v31, v29
	v_mul_f32_e32 v26, v15, v15
	v_rcp_f32_e32 v40, v40
	v_rcp_f32_e32 v41, v41
	v_mul_f32_e32 v12, v27, v27
	v_pk_add_f32 v[26:27], v[30:31], v[26:27]
	v_pk_mul_f32 v[30:31], v[28:29], v[14:15] op_sel:[1,0] op_sel_hi:[0,1]
	v_pk_add_f32 v[14:15], v[28:29], v[14:15] op_sel:[1,0] op_sel_hi:[0,1]
	v_mov_b32_e32 v31, v15
	v_mul_f32_e32 v44, v45, v45
	v_mul_f32_e32 v10, v11, v11
	v_pk_add_f32 v[12:13], v[30:31], v[12:13]
	v_pk_mul_f32 v[42:43], v[8:9], v[8:9]
	v_pk_add_f32 v[10:11], v[44:45], v[10:11]
	v_pk_add_f32 v[12:13], v[26:27], v[12:13]
	v_pk_fma_f32 v[50:51], v[40:41], s[42:43], v[22:23] op_sel_hi:[1,0,0]
	v_pk_add_f32 v[26:27], v[10:11], v[12:13]
	v_pk_mul_f32 v[10:11], v[42:43], s[64:65] op_sel_hi:[1,0]
	v_pk_fma_f32 v[50:51], v[40:41], v[50:51], s[48:49] op_sel_hi:[1,1,0]
	v_exp_f32_e32 v10, v10
	v_exp_f32_e32 v11, v11
	v_pk_fma_f32 v[12:13], v[40:41], v[50:51], s[50:51] op_sel_hi:[1,1,0]
	v_pk_fma_f32 v[12:13], v[40:41], v[12:13], s[56:57] op_sel_hi:[1,1,0]
	s_nop 0
	v_pk_mul_f32 v[12:13], v[40:41], v[12:13]
	s_waitcnt vmcnt(0)
	v_lshlrev_b32_e32 v40, 16, v6
	v_pk_mul_f32 v[10:11], v[10:11], v[12:13]
	v_and_b32_e32 v41, 0xffff0000, v6
	v_max_f32_e32 v114, 0, v8
	v_fma_f32 v15, -|v8|, v10, v114
	v_max_f32_e32 v115, 0, v9
	v_fma_f32 v9, -|v9|, v11, v115
	v_and_b32_e32 v37, 0x7fffffff, v41
	v_lshlrev_b32_e32 v12, 16, v4
	v_and_b32_e32 v10, 0x7fffffff, v12
	v_and_b32_e32 v13, 0xffff0000, v4
	v_and_b32_e32 v11, 0x7fffffff, v13
	v_pk_fma_f32 v[10:11], v[10:11], s[40:41], 1.0 op_sel_hi:[1,0,0]
	v_mul_f32_e32 v14, v15, v15
	v_rcp_f32_e32 v10, v10
	v_rcp_f32_e32 v11, v11
	v_mul_f32_e32 v8, v9, v9
	v_pk_add_f32 v[28:29], v[14:15], v[8:9]
	v_pk_mul_f32 v[14:15], v[12:13], v[12:13]
	v_pk_fma_f32 v[8:9], v[10:11], s[42:43], v[22:23] op_sel_hi:[1,0,0]
	v_pk_mul_f32 v[14:15], v[14:15], s[64:65] op_sel_hi:[1,0]
	v_pk_fma_f32 v[8:9], v[10:11], v[8:9], s[48:49] op_sel_hi:[1,1,0]
	v_exp_f32_e32 v14, v14
	v_exp_f32_e32 v15, v15
	v_pk_fma_f32 v[8:9], v[10:11], v[8:9], s[50:51] op_sel_hi:[1,1,0]
	v_lshlrev_b32_e32 v4, 16, v5
	v_pk_fma_f32 v[8:9], v[10:11], v[8:9], s[56:57] op_sel_hi:[1,1,0]
	v_and_b32_e32 v5, 0xffff0000, v5
	v_pk_mul_f32 v[8:9], v[10:11], v[8:9]
	v_pk_mul_f32 v[14:15], v[14:15], v[8:9]
	global_load_dwordx4 v[8:11], v[24:25], off offset:512
	v_fma_f32 v34, |v4|, s40, 1.0
	v_fma_f32 v35, |v5|, s40, 1.0
	v_rcp_f32_e32 v34, v34
	v_rcp_f32_e32 v35, v35
	v_max_f32_e32 v116, 0, v12
	v_fma_f32 v31, -|v12|, v14, v116
	v_max_f32_e32 v117, 0, v13
	v_fma_f32 v33, -|v13|, v15, v117
	v_and_b32_e32 v36, 0x7fffffff, v40
	v_pk_fma_f32 v[36:37], v[36:37], s[40:41], 1.0 op_sel_hi:[1,0,0]
	v_pk_fma_f32 v[12:13], v[34:35], s[42:43], v[22:23] op_sel_hi:[1,0,0]
	v_rcp_f32_e32 v38, v36
	v_pk_mul_f32 v[14:15], v[4:5], v[4:5]
	v_pk_fma_f32 v[12:13], v[34:35], v[12:13], s[48:49] op_sel_hi:[1,1,0]
	v_pk_mul_f32 v[14:15], v[14:15], s[64:65] op_sel_hi:[1,0]
	v_pk_fma_f32 v[12:13], v[34:35], v[12:13], s[50:51] op_sel_hi:[1,1,0]
	v_exp_f32_e32 v14, v14
	v_exp_f32_e32 v15, v15
	v_pk_fma_f32 v[12:13], v[34:35], v[12:13], s[56:57] op_sel_hi:[1,1,0]
	v_rcp_f32_e32 v39, v37
	v_pk_mul_f32 v[12:13], v[34:35], v[12:13]
	v_pk_mul_f32 v[12:13], v[14:15], v[12:13]
	v_mul_f32_e32 v30, v31, v31
	v_max_f32_e32 v80, 0, v4
	v_fma_f32 v35, -|v4|, v12, v80
	v_max_f32_e32 v81, 0, v5
	v_fma_f32 v37, -|v5|, v13, v81
	v_mul_f32_e32 v32, v33, v33
	v_pk_fma_f32 v[4:5], v[38:39], s[42:43], v[22:23] op_sel_hi:[1,0,0]
	v_lshlrev_b32_e32 v14, 16, v7
	v_pk_mul_f32 v[12:13], v[40:41], v[40:41]
	v_pk_fma_f32 v[4:5], v[38:39], v[4:5], s[48:49] op_sel_hi:[1,1,0]
	v_pk_mul_f32 v[12:13], v[12:13], s[64:65] op_sel_hi:[1,0]
	v_pk_fma_f32 v[4:5], v[38:39], v[4:5], s[50:51] op_sel_hi:[1,1,0]
	v_exp_f32_e32 v12, v12
	v_exp_f32_e32 v13, v13
	v_and_b32_e32 v15, 0xffff0000, v7
	v_pk_fma_f32 v[4:5], v[38:39], v[4:5], s[56:57] op_sel_hi:[1,1,0]
	v_pk_mul_f32 v[4:5], v[38:39], v[4:5]
	v_fma_f32 v6, |v14|, s40, 1.0
	v_fma_f32 v7, |v15|, s40, 1.0
	v_pk_mul_f32 v[4:5], v[12:13], v[4:5]
	v_rcp_f32_e32 v6, v6
	v_rcp_f32_e32 v7, v7
	v_max_f32_e32 v82, 0, v40
	v_fma_f32 v39, -|v40|, v4, v82
	v_max_f32_e32 v83, 0, v41
	v_fma_f32 v41, -|v41|, v5, v83
	v_mul_f32_e32 v34, v35, v35
	v_mul_f32_e32 v36, v37, v37
	v_pk_add_f32 v[26:27], v[28:29], v[26:27]
	v_pk_add_f32 v[28:29], v[30:31], v[32:33]
	v_pk_mul_f32 v[12:13], v[14:15], v[14:15]
	v_pk_fma_f32 v[4:5], v[6:7], s[42:43], v[22:23] op_sel_hi:[1,0,0]
	v_pk_mul_f32 v[12:13], v[12:13], s[64:65] op_sel_hi:[1,0]
	v_pk_fma_f32 v[4:5], v[6:7], v[4:5], s[48:49] op_sel_hi:[1,1,0]
	v_exp_f32_e32 v12, v12
	v_exp_f32_e32 v13, v13
	v_pk_fma_f32 v[4:5], v[6:7], v[4:5], s[50:51] op_sel_hi:[1,1,0]
	v_pk_fma_f32 v[4:5], v[6:7], v[4:5], s[56:57] op_sel_hi:[1,1,0]
	v_mul_f32_e32 v38, v39, v39
	v_pk_mul_f32 v[4:5], v[6:7], v[4:5]
	v_mul_f32_e32 v40, v41, v41
	v_pk_mul_f32 v[4:5], v[12:13], v[4:5]
	v_pk_add_f32 v[26:27], v[28:29], v[26:27]
	v_max_f32_e32 v84, 0, v14
	v_fma_f32 v43, -|v14|, v4, v84
	v_max_f32_e32 v85, 0, v15
	v_fma_f32 v45, -|v15|, v5, v85
	global_load_dwordx4 v[4:7], v[24:25], off offset:768
	v_pk_add_f32 v[28:29], v[34:35], v[36:37]
	s_waitcnt vmcnt(1)
	v_lshlrev_b32_e32 v48, 16, v8
	v_and_b32_e32 v49, 0xffff0000, v8
	v_fma_f32 v46, |v48|, s40, 1.0
	v_fma_f32 v47, |v49|, s40, 1.0
	v_pk_mul_f32 v[14:15], v[48:49], v[48:49]
	v_rcp_f32_e32 v46, v46
	v_rcp_f32_e32 v47, v47
	v_pk_mul_f32 v[14:15], v[14:15], s[64:65] op_sel_hi:[1,0]
	v_lshlrev_b32_e32 v50, 16, v9
	v_pk_fma_f32 v[12:13], v[46:47], s[42:43], v[22:23] op_sel_hi:[1,0,0]
	v_exp_f32_e32 v14, v14
	v_pk_fma_f32 v[12:13], v[46:47], v[12:13], s[48:49] op_sel_hi:[1,1,0]
	v_exp_f32_e32 v15, v15
	v_and_b32_e32 v51, 0xffff0000, v9
	v_pk_fma_f32 v[12:13], v[46:47], v[12:13], s[50:51] op_sel_hi:[1,1,0]
	v_pk_fma_f32 v[12:13], v[46:47], v[12:13], s[56:57] op_sel_hi:[1,1,0]
	v_fma_f32 v8, |v50|, s40, 1.0
	v_fma_f32 v9, |v51|, s40, 1.0
	v_pk_mul_f32 v[12:13], v[46:47], v[12:13]
	v_rcp_f32_e32 v52, v8
	v_rcp_f32_e32 v53, v9
	v_pk_mul_f32 v[12:13], v[14:15], v[12:13]
	v_max_f32_e32 v86, 0, v48
	v_fma_f32 v47, -|v48|, v12, v86
	v_max_f32_e32 v90, 0, v49
	v_fma_f32 v9, -|v49|, v13, v90
	v_lshlrev_b32_e32 v60, 16, v10
	v_and_b32_e32 v61, 0xffff0000, v10
	v_lshlrev_b32_e32 v10, 16, v11
	v_pk_fma_f32 v[12:13], v[52:53], s[42:43], v[22:23] op_sel_hi:[1,0,0]
	v_pk_mul_f32 v[14:15], v[50:51], v[50:51]
	v_pk_fma_f32 v[12:13], v[52:53], v[12:13], s[48:49] op_sel_hi:[1,1,0]
	v_pk_mul_f32 v[14:15], v[14:15], s[64:65] op_sel_hi:[1,0]
	v_pk_fma_f32 v[12:13], v[52:53], v[12:13], s[50:51] op_sel_hi:[1,1,0]
	v_exp_f32_e32 v14, v14
	v_exp_f32_e32 v15, v15
	v_pk_fma_f32 v[12:13], v[52:53], v[12:13], s[56:57] op_sel_hi:[1,1,0]
	v_pk_mul_f32 v[12:13], v[52:53], v[12:13]
	v_fma_f32 v52, |v60|, s40, 1.0
	v_fma_f32 v53, |v61|, s40, 1.0
	v_pk_mul_f32 v[12:13], v[14:15], v[12:13]
	v_rcp_f32_e32 v52, v52
	v_rcp_f32_e32 v53, v53
	v_max_f32_e32 v91, 0, v50
	v_fma_f32 v49, -|v50|, v12, v91
	v_max_f32_e32 v92, 0, v51
	v_fma_f32 v51, -|v51|, v13, v92
	v_and_b32_e32 v11, 0xffff0000, v11
	v_pk_mul_f32 v[14:15], v[60:61], v[60:61]
	v_pk_fma_f32 v[12:13], v[52:53], s[42:43], v[22:23] op_sel_hi:[1,0,0]
	v_pk_mul_f32 v[14:15], v[14:15], s[64:65] op_sel_hi:[1,0]
	v_pk_fma_f32 v[12:13], v[52:53], v[12:13], s[48:49] op_sel_hi:[1,1,0]
	v_exp_f32_e32 v14, v14
	v_exp_f32_e32 v15, v15
	v_pk_fma_f32 v[12:13], v[52:53], v[12:13], s[50:51] op_sel_hi:[1,1,0]
	v_fma_f32 v62, |v10|, s40, 1.0
	v_fma_f32 v63, |v11|, s40, 1.0
	v_pk_fma_f32 v[12:13], v[52:53], v[12:13], s[56:57] op_sel_hi:[1,1,0]
	v_rcp_f32_e32 v62, v62
	v_pk_mul_f32 v[12:13], v[52:53], v[12:13]
	v_rcp_f32_e32 v63, v63
	v_pk_mul_f32 v[12:13], v[14:15], v[12:13]
	v_max_f32_e32 v93, 0, v60
	v_fma_f32 v53, -|v60|, v12, v93
	v_max_f32_e32 v94, 0, v61
	v_fma_f32 v61, -|v61|, v13, v94
	v_mul_f32_e32 v42, v43, v43
	s_waitcnt vmcnt(0)
	v_lshlrev_b32_e32 v64, 16, v4
	v_and_b32_e32 v65, 0xffff0000, v4
	v_pk_mul_f32 v[14:15], v[10:11], v[10:11]
	v_pk_fma_f32 v[12:13], v[62:63], s[42:43], v[22:23] op_sel_hi:[1,0,0]
	v_pk_mul_f32 v[14:15], v[14:15], s[64:65] op_sel_hi:[1,0]
	v_pk_fma_f32 v[12:13], v[62:63], v[12:13], s[48:49] op_sel_hi:[1,1,0]
	v_exp_f32_e32 v14, v14
	v_exp_f32_e32 v15, v15
	v_pk_fma_f32 v[12:13], v[62:63], v[12:13], s[50:51] op_sel_hi:[1,1,0]
	v_pk_fma_f32 v[12:13], v[62:63], v[12:13], s[56:57] op_sel_hi:[1,1,0]
	v_pk_mul_f32 v[12:13], v[62:63], v[12:13]
	v_fma_f32 v66, |v64|, s40, 1.0
	v_fma_f32 v67, |v65|, s40, 1.0
	v_pk_mul_f32 v[12:13], v[14:15], v[12:13]
	v_rcp_f32_e32 v66, v66
	v_rcp_f32_e32 v67, v67
	v_max_f32_e32 v95, 0, v10
	v_fma_f32 v63, -|v10|, v12, v95
	v_max_f32_e32 v96, 0, v11
	v_fma_f32 v11, -|v11|, v13, v96
	v_lshlrev_b32_e32 v4, 16, v5
	v_and_b32_e32 v5, 0xffff0000, v5
	v_pk_mul_f32 v[14:15], v[64:65], v[64:65]
	v_pk_fma_f32 v[12:13], v[66:67], s[42:43], v[22:23] op_sel_hi:[1,0,0]
	v_pk_mul_f32 v[14:15], v[14:15], s[64:65] op_sel_hi:[1,0]
	v_pk_fma_f32 v[12:13], v[66:67], v[12:13], s[48:49] op_sel_hi:[1,1,0]
	v_exp_f32_e32 v14, v14
	v_exp_f32_e32 v15, v15
	v_pk_fma_f32 v[12:13], v[66:67], v[12:13], s[50:51] op_sel_hi:[1,1,0]
	v_fma_f32 v68, |v4|, s40, 1.0
	v_fma_f32 v69, |v5|, s40, 1.0
	v_pk_fma_f32 v[12:13], v[66:67], v[12:13], s[56:57] op_sel_hi:[1,1,0]
	v_rcp_f32_e32 v68, v68
	v_pk_mul_f32 v[12:13], v[66:67], v[12:13]
	v_rcp_f32_e32 v69, v69
	v_pk_mul_f32 v[12:13], v[14:15], v[12:13]
	v_max_f32_e32 v97, 0, v64
	v_fma_f32 v67, -|v64|, v12, v97
	v_max_f32_e32 v98, 0, v65
	v_fma_f32 v65, -|v65|, v13, v98
	v_mul_f32_e32 v44, v45, v45
	v_pk_add_f32 v[26:27], v[28:29], v[26:27]
	v_pk_add_f32 v[28:29], v[38:39], v[40:41]
	v_pk_fma_f32 v[12:13], v[68:69], s[42:43], v[22:23] op_sel_hi:[1,0,0]
	v_pk_mul_f32 v[14:15], v[4:5], v[4:5]
	v_pk_fma_f32 v[12:13], v[68:69], v[12:13], s[48:49] op_sel_hi:[1,1,0]
	v_pk_mul_f32 v[14:15], v[14:15], s[64:65] op_sel_hi:[1,0]
	v_pk_fma_f32 v[12:13], v[68:69], v[12:13], s[50:51] op_sel_hi:[1,1,0]
	v_exp_f32_e32 v70, v14
	v_exp_f32_e32 v71, v15
	v_pk_fma_f32 v[72:73], v[68:69], v[12:13], s[56:57] op_sel_hi:[1,1,0]
	global_load_dwordx4 v[12:15], v[24:25], off offset:1024
	v_mul_f32_e32 v46, v47, v47
	v_mul_f32_e32 v8, v9, v9
	v_pk_add_f32 v[26:27], v[28:29], v[26:27]
	v_pk_add_f32 v[28:29], v[42:43], v[44:45]
	v_mul_f32_e32 v48, v49, v49
	v_mul_f32_e32 v50, v51, v51
	v_pk_add_f32 v[26:27], v[28:29], v[26:27]
	v_pk_add_f32 v[8:9], v[46:47], v[8:9]
	v_mul_f32_e32 v52, v53, v53
	v_mul_f32_e32 v60, v61, v61
	v_pk_mul_f32 v[68:69], v[68:69], v[72:73]
	v_pk_add_f32 v[8:9], v[8:9], v[26:27]
	v_pk_add_f32 v[26:27], v[48:49], v[50:51]
	v_pk_mul_f32 v[68:69], v[70:71], v[68:69]
	v_pk_add_f32 v[8:9], v[26:27], v[8:9]
	v_pk_add_f32 v[26:27], v[52:53], v[60:61]
	v_lshlrev_b32_e32 v28, 16, v6
	v_and_b32_e32 v29, 0xffff0000, v6
	v_max_f32_e32 v99, 0, v4
	v_fma_f32 v73, -|v4|, v68, v99
	v_max_f32_e32 v100, 0, v5
	v_fma_f32 v5, -|v5|, v69, v100
	v_pk_add_f32 v[8:9], v[26:27], v[8:9]
	v_mul_f32_e32 v62, v63, v63
	v_mul_f32_e32 v10, v11, v11
	v_fma_f32 v26, |v28|, s40, 1.0
	v_fma_f32 v27, |v29|, s40, 1.0
	v_mul_f32_e32 v66, v67, v67
	v_mul_f32_e32 v64, v65, v65
	v_pk_add_f32 v[10:11], v[62:63], v[10:11]
	v_rcp_f32_e32 v30, v26
	v_rcp_f32_e32 v31, v27
	v_mul_f32_e32 v72, v73, v73
	v_mul_f32_e32 v4, v5, v5
	v_pk_add_f32 v[8:9], v[10:11], v[8:9]
	v_pk_add_f32 v[10:11], v[66:67], v[64:65]
	v_pk_add_f32 v[4:5], v[72:73], v[4:5]
	v_pk_add_f32 v[8:9], v[10:11], v[8:9]
	v_cmp_gt_f32_e64 s[0:1], 0, v28
	v_pk_add_f32 v[26:27], v[4:5], v[8:9]
	v_pk_mul_f32 v[8:9], v[28:29], v[28:29]
	v_pk_fma_f32 v[4:5], v[30:31], s[42:43], v[22:23] op_sel_hi:[1,0,0]
	v_pk_mul_f32 v[8:9], v[8:9], s[64:65] op_sel_hi:[1,0]
	v_pk_fma_f32 v[4:5], v[30:31], v[4:5], s[48:49] op_sel_hi:[1,1,0]
	v_exp_f32_e32 v8, v8
	v_exp_f32_e32 v9, v9
	v_pk_fma_f32 v[4:5], v[30:31], v[4:5], s[50:51] op_sel_hi:[1,1,0]
	v_lshlrev_b32_e32 v6, 16, v7
	v_pk_fma_f32 v[4:5], v[30:31], v[4:5], s[56:57] op_sel_hi:[1,1,0]
	v_and_b32_e32 v7, 0xffff0000, v7
	v_pk_mul_f32 v[4:5], v[30:31], v[4:5]
	s_nop 0
	v_pk_mul_f32 v[4:5], v[8:9], v[4:5]
	s_nop 0
	v_pk_mul_f32 v[8:9], v[28:29], v[4:5]
	v_pk_fma_f32 v[4:5], v[28:29], v[4:5], v[28:29] neg_lo:[1,0,0] neg_hi:[1,0,0]
	s_nop 0
	v_cndmask_b32_e64 v11, v4, v8, s[0:1]
	v_cmp_gt_f32_e64 s[0:1], 0, v29
	v_and_b32_e32 v8, 0x7fffffff, v6
	v_mul_f32_e32 v10, v11, v11
	v_cndmask_b32_e64 v5, v5, v9, s[0:1]
	v_and_b32_e32 v9, 0x7fffffff, v7
	v_pk_fma_f32 v[8:9], v[8:9], s[40:41], 1.0 op_sel_hi:[1,0,0]
	v_mul_f32_e32 v4, v5, v5
	v_rcp_f32_e32 v8, v8
	v_rcp_f32_e32 v9, v9
	v_pk_add_f32 v[28:29], v[10:11], v[4:5]
	v_pk_mul_f32 v[10:11], v[6:7], v[6:7]
	v_cmp_gt_f32_e64 s[0:1], 0, v6
	v_pk_fma_f32 v[4:5], v[8:9], s[42:43], v[22:23] op_sel_hi:[1,0,0]
	v_pk_mul_f32 v[10:11], v[10:11], s[64:65] op_sel_hi:[1,0]
	v_pk_fma_f32 v[4:5], v[8:9], v[4:5], s[48:49] op_sel_hi:[1,1,0]
	v_exp_f32_e32 v10, v10
	v_exp_f32_e32 v11, v11
	v_pk_fma_f32 v[4:5], v[8:9], v[4:5], s[50:51] op_sel_hi:[1,1,0]
	v_pk_add_f32 v[26:27], v[28:29], v[26:27]
	v_pk_fma_f32 v[4:5], v[8:9], v[4:5], s[56:57] op_sel_hi:[1,1,0]
	s_nop 0
	v_pk_mul_f32 v[4:5], v[8:9], v[4:5]
	s_nop 0
	v_pk_mul_f32 v[4:5], v[10:11], v[4:5]
	global_load_dwordx4 v[8:11], v[24:25], off offset:1280
	s_waitcnt vmcnt(1)
	v_lshlrev_b32_e32 v36, 16, v12
	v_and_b32_e32 v37, 0xffff0000, v12
	v_fma_f32 v34, |v36|, s40, 1.0
	v_fma_f32 v35, |v37|, s40, 1.0
	v_pk_mul_f32 v[32:33], v[6:7], v[4:5]
	v_rcp_f32_e32 v34, v34
	v_rcp_f32_e32 v35, v35
	v_pk_fma_f32 v[4:5], v[6:7], v[4:5], v[6:7] neg_lo:[1,0,0] neg_hi:[1,0,0]
	v_lshlrev_b32_e32 v38, 16, v13
	v_cndmask_b32_e64 v31, v4, v32, s[0:1]
	v_cmp_gt_f32_e64 s[0:1], 0, v7
	v_pk_mul_f32 v[6:7], v[36:37], v[36:37]
	v_and_b32_e32 v39, 0xffff0000, v13
	v_cndmask_b32_e64 v33, v5, v33, s[0:1]
	v_pk_fma_f32 v[4:5], v[34:35], s[42:43], v[22:23] op_sel_hi:[1,0,0]
	v_pk_mul_f32 v[6:7], v[6:7], s[64:65] op_sel_hi:[1,0]
	v_pk_fma_f32 v[4:5], v[34:35], v[4:5], s[48:49] op_sel_hi:[1,1,0]
	v_exp_f32_e32 v6, v6
	v_exp_f32_e32 v7, v7
	v_pk_fma_f32 v[4:5], v[34:35], v[4:5], s[50:51] op_sel_hi:[1,1,0]
	v_pk_fma_f32 v[4:5], v[34:35], v[4:5], s[56:57] op_sel_hi:[1,1,0]
	v_fma_f32 v12, |v38|, s40, 1.0
	v_fma_f32 v13, |v39|, s40, 1.0
	v_pk_mul_f32 v[4:5], v[34:35], v[4:5]
	v_rcp_f32_e32 v40, v12
	v_rcp_f32_e32 v41, v13
	v_pk_mul_f32 v[4:5], v[6:7], v[4:5]
	v_max_f32_e32 v104, 0, v36
	v_fma_f32 v35, -|v36|, v4, v104
	v_max_f32_e32 v105, 0, v37
	v_fma_f32 v13, -|v37|, v5, v105
	v_lshlrev_b32_e32 v42, 16, v14
	v_and_b32_e32 v43, 0xffff0000, v14
	v_lshlrev_b32_e32 v44, 16, v15
	v_pk_fma_f32 v[4:5], v[40:41], s[42:43], v[22:23] op_sel_hi:[1,0,0]
	v_pk_mul_f32 v[6:7], v[38:39], v[38:39]
	v_pk_fma_f32 v[4:5], v[40:41], v[4:5], s[48:49] op_sel_hi:[1,1,0]
	v_pk_mul_f32 v[6:7], v[6:7], s[64:65] op_sel_hi:[1,0]
	v_pk_fma_f32 v[4:5], v[40:41], v[4:5], s[50:51] op_sel_hi:[1,1,0]
	v_exp_f32_e32 v6, v6
	v_exp_f32_e32 v7, v7
	v_pk_fma_f32 v[4:5], v[40:41], v[4:5], s[56:57] op_sel_hi:[1,1,0]
	v_pk_mul_f32 v[4:5], v[40:41], v[4:5]
	v_fma_f32 v40, |v42|, s40, 1.0
	v_fma_f32 v41, |v43|, s40, 1.0
	v_pk_mul_f32 v[4:5], v[6:7], v[4:5]
	v_rcp_f32_e32 v40, v40
	v_rcp_f32_e32 v41, v41
	v_max_f32_e32 v106, 0, v38
	v_fma_f32 v37, -|v38|, v4, v106
	v_max_f32_e32 v107, 0, v39
	v_fma_f32 v39, -|v39|, v5, v107
	v_and_b32_e32 v45, 0xffff0000, v15
	v_pk_mul_f32 v[6:7], v[42:43], v[42:43]
	v_pk_fma_f32 v[4:5], v[40:41], s[42:43], v[22:23] op_sel_hi:[1,0,0]
	v_pk_mul_f32 v[6:7], v[6:7], s[64:65] op_sel_hi:[1,0]
	v_pk_fma_f32 v[4:5], v[40:41], v[4:5], s[48:49] op_sel_hi:[1,1,0]
	v_exp_f32_e32 v6, v6
	v_exp_f32_e32 v7, v7
	v_pk_fma_f32 v[4:5], v[40:41], v[4:5], s[50:51] op_sel_hi:[1,1,0]
	v_fma_f32 v14, |v44|, s40, 1.0
	v_fma_f32 v15, |v45|, s40, 1.0
	v_pk_fma_f32 v[4:5], v[40:41], v[4:5], s[56:57] op_sel_hi:[1,1,0]
	v_rcp_f32_e32 v46, v14
	v_pk_mul_f32 v[4:5], v[40:41], v[4:5]
	v_rcp_f32_e32 v47, v15
	v_pk_mul_f32 v[4:5], v[6:7], v[4:5]
	v_max_f32_e32 v108, 0, v42
	v_fma_f32 v41, -|v42|, v4, v108
	v_max_f32_e32 v109, 0, v43
	v_fma_f32 v15, -|v43|, v5, v109
	v_mul_f32_e32 v30, v31, v31
	s_waitcnt vmcnt(0)
	v_lshlrev_b32_e32 v48, 16, v8
	v_and_b32_e32 v49, 0xffff0000, v8
	v_pk_fma_f32 v[4:5], v[46:47], s[42:43], v[22:23] op_sel_hi:[1,0,0]
	v_pk_mul_f32 v[6:7], v[44:45], v[44:45]
	v_pk_fma_f32 v[4:5], v[46:47], v[4:5], s[48:49] op_sel_hi:[1,1,0]
	v_pk_mul_f32 v[6:7], v[6:7], s[64:65] op_sel_hi:[1,0]
	v_pk_fma_f32 v[4:5], v[46:47], v[4:5], s[50:51] op_sel_hi:[1,1,0]
	v_exp_f32_e32 v6, v6
	v_exp_f32_e32 v7, v7
	v_pk_fma_f32 v[4:5], v[46:47], v[4:5], s[56:57] op_sel_hi:[1,1,0]
	v_pk_mul_f32 v[4:5], v[46:47], v[4:5]
	v_fma_f32 v46, |v48|, s40, 1.0
	v_fma_f32 v47, |v49|, s40, 1.0
	v_pk_mul_f32 v[4:5], v[6:7], v[4:5]
	v_rcp_f32_e32 v46, v46
	v_rcp_f32_e32 v47, v47
	v_max_f32_e32 v110, 0, v44
	v_fma_f32 v43, -|v44|, v4, v110
	v_max_f32_e32 v111, 0, v45
	v_fma_f32 v45, -|v45|, v5, v111
	v_lshlrev_b32_e32 v60, 16, v9
	v_and_b32_e32 v61, 0xffff0000, v9
	v_pk_mul_f32 v[6:7], v[48:49], v[48:49]
	v_pk_fma_f32 v[4:5], v[46:47], s[42:43], v[22:23] op_sel_hi:[1,0,0]
	v_pk_mul_f32 v[6:7], v[6:7], s[64:65] op_sel_hi:[1,0]
	v_pk_fma_f32 v[4:5], v[46:47], v[4:5], s[48:49] op_sel_hi:[1,1,0]
	v_exp_f32_e32 v6, v6
	v_exp_f32_e32 v7, v7
	v_pk_fma_f32 v[4:5], v[46:47], v[4:5], s[50:51] op_sel_hi:[1,1,0]
	v_pk_fma_f32 v[4:5], v[46:47], v[4:5], s[56:57] op_sel_hi:[1,1,0]
	v_fma_f32 v8, |v60|, s40, 1.0
	v_fma_f32 v9, |v61|, s40, 1.0
	v_pk_mul_f32 v[4:5], v[46:47], v[4:5]
	v_rcp_f32_e32 v62, v8
	v_pk_mul_f32 v[46:47], v[6:7], v[4:5]
	global_load_dwordx4 v[4:7], v[24:25], off offset:1536
	v_rcp_f32_e32 v63, v9
	v_max_f32_e32 v113, 0, v49
	v_fma_f32 v9, -|v49|, v47, v113
	v_max_f32_e32 v112, 0, v48
	v_fma_f32 v47, -|v48|, v46, v112
	v_lshlrev_b32_e32 v66, 16, v11
	v_and_b32_e32 v67, 0xffff0000, v11
	v_pk_fma_f32 v[48:49], v[62:63], s[42:43], v[22:23] op_sel_hi:[1,0,0]
	v_and_b32_e32 v11, 0x7fffffff, v67
	v_pk_fma_f32 v[48:49], v[62:63], v[48:49], s[48:49] op_sel_hi:[1,1,0]
	v_pk_mul_f32 v[50:51], v[60:61], v[60:61]
	v_pk_fma_f32 v[48:49], v[62:63], v[48:49], s[50:51] op_sel_hi:[1,1,0]
	v_pk_mul_f32 v[50:51], v[50:51], s[64:65] op_sel_hi:[1,0]
	v_pk_fma_f32 v[48:49], v[62:63], v[48:49], s[56:57] op_sel_hi:[1,1,0]
	v_exp_f32_e32 v50, v50
	v_exp_f32_e32 v51, v51
	v_pk_mul_f32 v[48:49], v[62:63], v[48:49]
	v_lshlrev_b32_e32 v62, 16, v10
	v_and_b32_e32 v63, 0xffff0000, v10
	v_fma_f32 v64, |v62|, s40, 1.0
	v_fma_f32 v65, |v63|, s40, 1.0
	v_pk_mul_f32 v[48:49], v[50:51], v[48:49]
	v_rcp_f32_e32 v64, v64
	v_rcp_f32_e32 v65, v65
	v_max_f32_e32 v115, 0, v61
	v_fma_f32 v51, -|v61|, v49, v115
	v_max_f32_e32 v114, 0, v60
	v_fma_f32 v49, -|v60|, v48, v114
	v_and_b32_e32 v10, 0x7fffffff, v66
	v_pk_fma_f32 v[10:11], v[10:11], s[40:41], 1.0 op_sel_hi:[1,0,0]
	v_pk_mul_f32 v[60:61], v[62:63], v[62:63]
	v_rcp_f32_e32 v68, v10
	v_pk_fma_f32 v[52:53], v[64:65], s[42:43], v[22:23] op_sel_hi:[1,0,0]
	v_pk_mul_f32 v[60:61], v[60:61], s[64:65] op_sel_hi:[1,0]
	v_pk_fma_f32 v[52:53], v[64:65], v[52:53], s[48:49] op_sel_hi:[1,1,0]
	v_exp_f32_e32 v60, v60
	v_exp_f32_e32 v61, v61
	v_pk_fma_f32 v[52:53], v[64:65], v[52:53], s[50:51] op_sel_hi:[1,1,0]
	v_rcp_f32_e32 v69, v11
	v_pk_fma_f32 v[52:53], v[64:65], v[52:53], s[56:57] op_sel_hi:[1,1,0]
	v_pk_mul_f32 v[52:53], v[64:65], v[52:53]
	v_mul_f32_e32 v32, v33, v33
	v_pk_mul_f32 v[52:53], v[60:61], v[52:53]
	v_mul_f32_e32 v34, v35, v35
	v_max_f32_e32 v117, 0, v63
	v_fma_f32 v11, -|v63|, v53, v117
	v_max_f32_e32 v116, 0, v62
	v_fma_f32 v53, -|v62|, v52, v116
	v_mul_f32_e32 v12, v13, v13
	v_pk_mul_f32 v[62:63], v[66:67], v[66:67]
	v_pk_add_f32 v[28:29], v[30:31], v[32:33]
	v_pk_fma_f32 v[60:61], v[68:69], s[42:43], v[22:23] op_sel_hi:[1,0,0]
	v_pk_mul_f32 v[62:63], v[62:63], s[64:65] op_sel_hi:[1,0]
	v_pk_fma_f32 v[60:61], v[68:69], v[60:61], s[48:49] op_sel_hi:[1,1,0]
	v_exp_f32_e32 v62, v62
	v_exp_f32_e32 v63, v63
	v_pk_fma_f32 v[60:61], v[68:69], v[60:61], s[50:51] op_sel_hi:[1,1,0]
	v_pk_fma_f32 v[60:61], v[68:69], v[60:61], s[56:57] op_sel_hi:[1,1,0]
	v_mul_f32_e32 v36, v37, v37
	v_pk_mul_f32 v[60:61], v[68:69], v[60:61]
	v_mul_f32_e32 v38, v39, v39
	v_pk_mul_f32 v[60:61], v[62:63], v[60:61]
	v_pk_add_f32 v[26:27], v[28:29], v[26:27]
	v_max_f32_e32 v80, 0, v66
	v_fma_f32 v71, -|v66|, v60, v80
	v_max_f32_e32 v81, 0, v67
	v_fma_f32 v65, -|v67|, v61, v81
	global_load_dwordx4 v[60:63], v[24:25], off offset:1792
	v_pk_add_f32 v[12:13], v[34:35], v[12:13]
	v_mul_f32_e32 v40, v41, v41
	s_waitcnt vmcnt(1)
	v_lshlrev_b32_e32 v24, 16, v4
	v_and_b32_e32 v25, 0xffff0000, v4
	v_fma_f32 v72, |v24|, s40, 1.0
	v_fma_f32 v73, |v25|, s40, 1.0
	v_pk_mul_f32 v[68:69], v[24:25], v[24:25]
	v_rcp_f32_e32 v72, v72
	v_rcp_f32_e32 v73, v73
	v_mul_f32_e32 v14, v15, v15
	v_pk_mul_f32 v[68:69], v[68:69], s[64:65] op_sel_hi:[1,0]
	v_pk_add_f32 v[12:13], v[12:13], v[26:27]
	v_pk_fma_f32 v[66:67], v[72:73], s[42:43], v[22:23] op_sel_hi:[1,0,0]
	v_pk_add_f32 v[26:27], v[36:37], v[38:39]
	v_mul_f32_e32 v42, v43, v43
	v_mul_f32_e32 v44, v45, v45
	v_pk_fma_f32 v[66:67], v[72:73], v[66:67], s[48:49] op_sel_hi:[1,1,0]
	v_exp_f32_e32 v68, v68
	v_exp_f32_e32 v69, v69
	v_pk_add_f32 v[12:13], v[26:27], v[12:13]
	v_pk_add_f32 v[14:15], v[40:41], v[14:15]
	v_mul_f32_e32 v46, v47, v47
	v_mul_f32_e32 v8, v9, v9
	v_pk_fma_f32 v[66:67], v[72:73], v[66:67], s[50:51] op_sel_hi:[1,1,0]
	v_pk_add_f32 v[12:13], v[14:15], v[12:13]
	v_pk_add_f32 v[14:15], v[42:43], v[44:45]
	v_mul_f32_e32 v48, v49, v49
	v_mul_f32_e32 v50, v51, v51
	v_pk_fma_f32 v[66:67], v[72:73], v[66:67], s[56:57] op_sel_hi:[1,1,0]
	v_pk_add_f32 v[12:13], v[14:15], v[12:13]
	v_pk_add_f32 v[8:9], v[46:47], v[8:9]
	v_pk_mul_f32 v[66:67], v[72:73], v[66:67]
	v_pk_add_f32 v[8:9], v[8:9], v[12:13]
	v_pk_add_f32 v[12:13], v[48:49], v[50:51]
	v_lshlrev_b32_e32 v4, 16, v5
	v_and_b32_e32 v5, 0xffff0000, v5
	v_pk_mul_f32 v[66:67], v[68:69], v[66:67]
	v_pk_add_f32 v[8:9], v[12:13], v[8:9]
	v_max_f32_e32 v82, 0, v24
	v_fma_f32 v73, -|v24|, v66, v82
	v_max_f32_e32 v83, 0, v25
	v_fma_f32 v25, -|v25|, v67, v83
	v_fma_f32 v12, |v4|, s40, 1.0
	v_fma_f32 v13, |v5|, s40, 1.0
	v_mul_f32_e32 v52, v53, v53
	v_mul_f32_e32 v10, v11, v11
	v_rcp_f32_e32 v12, v12
	v_rcp_f32_e32 v13, v13
	v_mul_f32_e32 v70, v71, v71
	v_mul_f32_e32 v64, v65, v65
	v_pk_add_f32 v[10:11], v[52:53], v[10:11]
	v_mul_f32_e32 v72, v73, v73
	v_mul_f32_e32 v24, v25, v25
	v_pk_add_f32 v[8:9], v[10:11], v[8:9]
	v_pk_add_f32 v[10:11], v[70:71], v[64:65]
	v_pk_mul_f32 v[14:15], v[4:5], v[4:5]
	v_pk_add_f32 v[8:9], v[10:11], v[8:9]
	v_pk_add_f32 v[10:11], v[72:73], v[24:25]
	v_pk_mul_f32 v[14:15], v[14:15], s[64:65] op_sel_hi:[1,0]
	v_pk_add_f32 v[8:9], v[10:11], v[8:9]
	v_pk_fma_f32 v[10:11], v[12:13], s[42:43], v[22:23] op_sel_hi:[1,0,0]
	v_exp_f32_e32 v14, v14
	v_pk_fma_f32 v[10:11], v[12:13], v[10:11], s[48:49] op_sel_hi:[1,1,0]
	v_exp_f32_e32 v15, v15
	v_pk_fma_f32 v[10:11], v[12:13], v[10:11], s[50:51] op_sel_hi:[1,1,0]
	v_pk_fma_f32 v[10:11], v[12:13], v[10:11], s[56:57] op_sel_hi:[1,1,0]
	s_waitcnt vmcnt(0)
	v_lshlrev_b32_e32 v28, 16, v60
	v_pk_mul_f32 v[10:11], v[12:13], v[10:11]
	v_and_b32_e32 v29, 0xffff0000, v60
	v_pk_mul_f32 v[10:11], v[14:15], v[10:11]
	v_and_b32_e32 v31, 0x7fffffff, v29
	v_max_f32_e32 v84, 0, v4
	v_fma_f32 v15, -|v4|, v10, v84
	v_max_f32_e32 v85, 0, v5
	v_fma_f32 v5, -|v5|, v11, v85
	v_and_b32_e32 v30, 0x7fffffff, v28
	v_lshlrev_b32_e32 v10, 16, v6
	v_and_b32_e32 v12, 0x7fffffff, v10
	v_and_b32_e32 v11, 0xffff0000, v6
	v_and_b32_e32 v13, 0x7fffffff, v11
	v_pk_fma_f32 v[12:13], v[12:13], s[40:41], 1.0 op_sel_hi:[1,0,0]
	v_mul_f32_e32 v14, v15, v15
	v_rcp_f32_e32 v12, v12
	v_rcp_f32_e32 v13, v13
	v_mul_f32_e32 v4, v5, v5
	v_pk_mul_f32 v[24:25], v[10:11], v[10:11]
	v_pk_add_f32 v[4:5], v[14:15], v[4:5]
	v_pk_fma_f32 v[14:15], v[12:13], s[42:43], v[22:23] op_sel_hi:[1,0,0]
	v_pk_mul_f32 v[24:25], v[24:25], s[64:65] op_sel_hi:[1,0]
	v_pk_fma_f32 v[14:15], v[12:13], v[14:15], s[48:49] op_sel_hi:[1,1,0]
	v_exp_f32_e32 v24, v24
	v_exp_f32_e32 v25, v25
	v_pk_fma_f32 v[14:15], v[12:13], v[14:15], s[50:51] op_sel_hi:[1,1,0]
	v_lshlrev_b32_e32 v6, 16, v7
	v_and_b32_e32 v7, 0xffff0000, v7
	v_pk_fma_f32 v[14:15], v[12:13], v[14:15], s[56:57] op_sel_hi:[1,1,0]
	v_pk_mul_f32 v[12:13], v[12:13], v[14:15]
	v_fma_f32 v26, |v6|, s40, 1.0
	v_fma_f32 v27, |v7|, s40, 1.0
	v_pk_mul_f32 v[12:13], v[24:25], v[12:13]
	v_rcp_f32_e32 v26, v26
	v_rcp_f32_e32 v27, v27
	v_max_f32_e32 v86, 0, v10
	v_fma_f32 v25, -|v10|, v12, v86
	v_max_f32_e32 v90, 0, v11
	v_fma_f32 v11, -|v11|, v13, v90
	v_pk_fma_f32 v[30:31], v[30:31], s[40:41], 1.0 op_sel_hi:[1,0,0]
	v_lshlrev_b32_e32 v32, 16, v61
	v_rcp_f32_e32 v30, v30
	v_rcp_f32_e32 v31, v31
	v_pk_mul_f32 v[14:15], v[6:7], v[6:7]
	v_pk_fma_f32 v[12:13], v[26:27], s[42:43], v[22:23] op_sel_hi:[1,0,0]
	v_pk_mul_f32 v[14:15], v[14:15], s[64:65] op_sel_hi:[1,0]
	v_pk_fma_f32 v[12:13], v[26:27], v[12:13], s[48:49] op_sel_hi:[1,1,0]
	v_exp_f32_e32 v14, v14
	v_exp_f32_e32 v15, v15
	v_pk_fma_f32 v[12:13], v[26:27], v[12:13], s[50:51] op_sel_hi:[1,1,0]
	v_pk_fma_f32 v[12:13], v[26:27], v[12:13], s[56:57] op_sel_hi:[1,1,0]
	v_and_b32_e32 v33, 0xffff0000, v61
	v_pk_mul_f32 v[12:13], v[26:27], v[12:13]
	v_pk_mul_f32 v[12:13], v[14:15], v[12:13]
	v_max_f32_e32 v91, 0, v6
	v_fma_f32 v27, -|v6|, v12, v91
	v_max_f32_e32 v92, 0, v7
	v_fma_f32 v7, -|v7|, v13, v92
	v_fma_f32 v34, |v32|, s40, 1.0
	v_fma_f32 v35, |v33|, s40, 1.0
	v_rcp_f32_e32 v34, v34
	v_rcp_f32_e32 v35, v35
	v_pk_mul_f32 v[14:15], v[28:29], v[28:29]
	v_pk_fma_f32 v[12:13], v[30:31], s[42:43], v[22:23] op_sel_hi:[1,0,0]
	v_pk_mul_f32 v[14:15], v[14:15], s[64:65] op_sel_hi:[1,0]
	v_pk_fma_f32 v[12:13], v[30:31], v[12:13], s[48:49] op_sel_hi:[1,1,0]
	v_exp_f32_e32 v14, v14
	v_exp_f32_e32 v15, v15
	v_pk_fma_f32 v[12:13], v[30:31], v[12:13], s[50:51] op_sel_hi:[1,1,0]
	v_pk_fma_f32 v[12:13], v[30:31], v[12:13], s[56:57] op_sel_hi:[1,1,0]
	v_lshlrev_b32_e32 v36, 16, v62
	v_pk_mul_f32 v[12:13], v[30:31], v[12:13]
	v_and_b32_e32 v37, 0xffff0000, v62
	v_pk_mul_f32 v[12:13], v[14:15], v[12:13]
	v_max_f32_e32 v93, 0, v28
	v_fma_f32 v31, -|v28|, v12, v93
	v_max_f32_e32 v94, 0, v29
	v_fma_f32 v13, -|v29|, v13, v94
	v_pk_mul_f32 v[28:29], v[32:33], v[32:33]
	v_fma_f32 v38, |v36|, s40, 1.0
	v_fma_f32 v39, |v37|, s40, 1.0
	v_pk_fma_f32 v[14:15], v[34:35], s[42:43], v[22:23] op_sel_hi:[1,0,0]
	v_pk_mul_f32 v[28:29], v[28:29], s[64:65] op_sel_hi:[1,0]
	v_pk_fma_f32 v[14:15], v[34:35], v[14:15], s[48:49] op_sel_hi:[1,1,0]
	v_exp_f32_e32 v28, v28
	v_exp_f32_e32 v29, v29
	v_pk_fma_f32 v[14:15], v[34:35], v[14:15], s[50:51] op_sel_hi:[1,1,0]
	v_rcp_f32_e32 v38, v38
	v_pk_fma_f32 v[14:15], v[34:35], v[14:15], s[56:57] op_sel_hi:[1,1,0]
	v_rcp_f32_e32 v39, v39
	v_pk_mul_f32 v[14:15], v[34:35], v[14:15]
	v_pk_mul_f32 v[14:15], v[28:29], v[14:15]
	v_lshlrev_b32_e32 v40, 16, v63
	v_max_f32_e32 v95, 0, v32
	v_fma_f32 v35, -|v32|, v14, v95
	v_max_f32_e32 v96, 0, v33
	v_fma_f32 v15, -|v33|, v15, v96
	v_and_b32_e32 v41, 0xffff0000, v63
	v_pk_mul_f32 v[32:33], v[36:37], v[36:37]
	v_pk_fma_f32 v[28:29], v[38:39], s[42:43], v[22:23] op_sel_hi:[1,0,0]
	v_pk_mul_f32 v[32:33], v[32:33], s[64:65] op_sel_hi:[1,0]
	v_pk_fma_f32 v[28:29], v[38:39], v[28:29], s[48:49] op_sel_hi:[1,1,0]
	v_exp_f32_e32 v32, v32
	v_exp_f32_e32 v33, v33
	v_pk_fma_f32 v[28:29], v[38:39], v[28:29], s[50:51] op_sel_hi:[1,1,0]
	v_pk_fma_f32 v[28:29], v[38:39], v[28:29], s[56:57] op_sel_hi:[1,1,0]
	v_fma_f32 v42, |v40|, s40, 1.0
	v_fma_f32 v43, |v41|, s40, 1.0
	v_pk_mul_f32 v[28:29], v[38:39], v[28:29]
	v_rcp_f32_e32 v42, v42
	v_pk_mul_f32 v[28:29], v[32:33], v[28:29]
	v_rcp_f32_e32 v43, v43
	v_max_f32_e32 v97, 0, v36
	v_fma_f32 v39, -|v36|, v28, v97
	v_max_f32_e32 v98, 0, v37
	v_fma_f32 v29, -|v37|, v29, v98
	v_pk_fma_f32 v[22:23], v[42:43], s[42:43], v[22:23] op_sel_hi:[1,0,0]
	v_mul_f32_e32 v24, v25, v25
	v_pk_fma_f32 v[22:23], v[42:43], v[22:23], s[48:49] op_sel_hi:[1,1,0]
	v_mul_f32_e32 v10, v11, v11
	v_pk_mul_f32 v[32:33], v[40:41], v[40:41]
	v_pk_fma_f32 v[22:23], v[42:43], v[22:23], s[50:51] op_sel_hi:[1,1,0]
	v_pk_mul_f32 v[32:33], v[32:33], s[64:65] op_sel_hi:[1,0]
	v_pk_fma_f32 v[22:23], v[42:43], v[22:23], s[56:57] op_sel_hi:[1,1,0]
	v_exp_f32_e32 v32, v32
	v_exp_f32_e32 v33, v33
	v_pk_mul_f32 v[22:23], v[42:43], v[22:23]
	v_mul_f32_e32 v26, v27, v27
	v_mul_f32_e32 v6, v7, v7
	v_pk_mul_f32 v[22:23], v[32:33], v[22:23]
	v_pk_add_f32 v[4:5], v[4:5], v[8:9]
	v_pk_add_f32 v[8:9], v[24:25], v[10:11]
	v_mul_f32_e32 v30, v31, v31
	v_mul_f32_e32 v12, v13, v13
	v_max_f32_e32 v99, 0, v40
	v_fma_f32 v37, -|v40|, v22, v99
	v_max_f32_e32 v100, 0, v41
	v_fma_f32 v23, -|v41|, v23, v100
	v_pk_add_f32 v[4:5], v[8:9], v[4:5]
	v_pk_add_f32 v[6:7], v[26:27], v[6:7]
	v_mul_f32_e32 v34, v35, v35
	v_mul_f32_e32 v14, v15, v15
	v_pk_add_f32 v[4:5], v[6:7], v[4:5]
	v_pk_add_f32 v[6:7], v[30:31], v[12:13]
	v_mul_f32_e32 v38, v39, v39
	v_mul_f32_e32 v28, v29, v29
	v_pk_add_f32 v[4:5], v[6:7], v[4:5]
	v_pk_add_f32 v[6:7], v[34:35], v[14:15]
	v_mul_f32_e32 v36, v37, v37
	v_mul_f32_e32 v22, v23, v23
	v_pk_add_f32 v[4:5], v[6:7], v[4:5]
	v_pk_add_f32 v[6:7], v[38:39], v[28:29]
	s_nop 0
	v_pk_add_f32 v[4:5], v[6:7], v[4:5]
	v_pk_add_f32 v[6:7], v[36:37], v[22:23]
	s_nop 0
	v_pk_add_f32 v[4:5], v[6:7], v[4:5]
	ds_bpermute_b32 v7, v56, v5
	ds_bpermute_b32 v6, v56, v4
	s_waitcnt lgkmcnt(0)
	v_pk_add_f32 v[4:5], v[4:5], v[6:7]
	ds_bpermute_b32 v7, v57, v5
	ds_bpermute_b32 v6, v57, v4
	s_waitcnt lgkmcnt(0)
	v_pk_add_f32 v[4:5], v[4:5], v[6:7]
	ds_bpermute_b32 v7, v58, v5
	ds_bpermute_b32 v6, v58, v4
	s_waitcnt lgkmcnt(0)
	v_pk_add_f32 v[4:5], v[4:5], v[6:7]
	ds_bpermute_b32 v7, v59, v5
	ds_bpermute_b32 v6, v59, v4
	s_and_saveexec_b64 s[8:9], vcc
	s_cbranch_execz .LBB0_447
	s_waitcnt lgkmcnt(0)
	v_pk_add_f32 v[4:5], v[4:5], v[6:7]
	s_nop 0
	v_pk_mul_f32 v[4:5], v[4:5], s[66:67] op_sel_hi:[1,0]
	s_nop 0
	v_fma_f32 v4, -v5, v5, v4
	v_max_f32_e32 v4, 0, v4
	v_add_f32_e32 v4, 0x358637bd, v4
	v_mul_f32_e32 v6, 0x4b800000, v4
	v_cmp_gt_f32_e64 s[0:1], s36, v4
	s_nop 1
	v_cndmask_b32_e64 v4, v4, v6, s[0:1]
	v_rsq_f32_e32 v4, v4
	v_lshl_add_u32 v6, v20, 2, 0
	v_add_u32_e32 v7, 0x11000, v6
	ds_write_b32 v7, v5
	v_mul_f32_e32 v5, 0x45800000, v4
	v_cndmask_b32_e64 v4, v4, v5, s[0:1]
	v_add_u32_e32 v5, 0x11200, v6
	ds_write_b32 v5, v4
.LBB0_447:
	s_or_b64 exec, exec, s[8:9]
	v_or_b32_e32 v20, 8, v16
	v_ashrrev_i32_e32 v21, 31, v20
	v_lshl_add_u64 v[4:5], s[6:7], 0, v[20:21]
	v_lshlrev_b64 v[4:5], 11, v[4:5]
	v_lshl_add_u64 v[4:5], s[4:5], 0, v[4:5]
	v_lshl_add_u64 v[24:25], v[4:5], 0, v[18:19]
	global_load_dwordx4 v[8:11], v[24:25], off
	s_waitcnt lgkmcnt(0)
	global_load_dwordx4 v[4:7], v[24:25], off offset:256
	v_mov_b64_e32 v[22:23], s[44:45]
	v_mov_b32_e32 v13, v2
	s_waitcnt vmcnt(1)
	v_lshlrev_b32_e32 v28, 16, v10
	v_and_b32_e32 v29, 0xffff0000, v10
	v_and_b32_e32 v15, 0xffff0000, v8
	v_and_b32_e32 v27, 0xffff0000, v9
	v_lshlrev_b32_e32 v26, 16, v9
	v_lshlrev_b32_e32 v14, 16, v8
	v_lshlrev_b32_e32 v8, 16, v11
	v_and_b32_e32 v9, 0xffff0000, v11
	v_fma_f32 v10, |v28|, s40, 1.0
	v_fma_f32 v11, |v29|, s40, 1.0
	v_fma_f32 v32, |v14|, s40, 1.0
	v_fma_f32 v33, |v15|, s40, 1.0
	v_rcp_f32_e32 v10, v10
	v_rcp_f32_e32 v11, v11
	v_fma_f32 v36, |v26|, s40, 1.0
	v_fma_f32 v37, |v27|, s40, 1.0
	v_rcp_f32_e32 v32, v32
	v_rcp_f32_e32 v33, v33
	v_rcp_f32_e32 v36, v36
	v_rcp_f32_e32 v37, v37
	v_pk_mul_f32 v[30:31], v[28:29], v[28:29]
	v_pk_mul_f32 v[34:35], v[14:15], v[14:15]
	v_pk_mul_f32 v[30:31], v[30:31], s[64:65] op_sel_hi:[1,0]
	v_pk_fma_f32 v[44:45], v[10:11], s[42:43], v[22:23] op_sel_hi:[1,0,0]
	v_pk_mul_f32 v[38:39], v[26:27], v[26:27]
	v_pk_mul_f32 v[34:35], v[34:35], s[64:65] op_sel_hi:[1,0]
	v_exp_f32_e32 v30, v30
	v_exp_f32_e32 v31, v31
	v_pk_fma_f32 v[46:47], v[32:33], s[42:43], v[22:23] op_sel_hi:[1,0,0]
	v_pk_fma_f32 v[44:45], v[10:11], v[44:45], s[48:49] op_sel_hi:[1,1,0]
	v_pk_mul_f32 v[38:39], v[38:39], s[64:65] op_sel_hi:[1,0]
	v_exp_f32_e32 v34, v34
	v_exp_f32_e32 v35, v35
	v_pk_fma_f32 v[48:49], v[36:37], s[42:43], v[22:23] op_sel_hi:[1,0,0]
	v_pk_fma_f32 v[46:47], v[32:33], v[46:47], s[48:49] op_sel_hi:[1,1,0]
	v_pk_fma_f32 v[44:45], v[10:11], v[44:45], s[50:51] op_sel_hi:[1,1,0]
	v_exp_f32_e32 v38, v38
	v_exp_f32_e32 v39, v39
	v_pk_fma_f32 v[48:49], v[36:37], v[48:49], s[48:49] op_sel_hi:[1,1,0]
	v_pk_fma_f32 v[46:47], v[32:33], v[46:47], s[50:51] op_sel_hi:[1,1,0]
	v_pk_fma_f32 v[44:45], v[10:11], v[44:45], s[56:57] op_sel_hi:[1,1,0]
	v_pk_fma_f32 v[48:49], v[36:37], v[48:49], s[50:51] op_sel_hi:[1,1,0]
	v_pk_fma_f32 v[46:47], v[32:33], v[46:47], s[56:57] op_sel_hi:[1,1,0]
	v_pk_mul_f32 v[10:11], v[10:11], v[44:45]
	v_pk_fma_f32 v[48:49], v[36:37], v[48:49], s[56:57] op_sel_hi:[1,1,0]
	v_pk_mul_f32 v[32:33], v[32:33], v[46:47]
	v_pk_mul_f32 v[10:11], v[30:31], v[10:11]
	v_pk_mul_f32 v[36:37], v[36:37], v[48:49]
	v_pk_mul_f32 v[30:31], v[34:35], v[32:33]
	v_max_f32_e32 v104, 0, v28
	v_fma_f32 v45, -|v28|, v10, v104
	v_max_f32_e32 v105, 0, v29
	v_fma_f32 v11, -|v29|, v11, v105
	v_pk_mul_f32 v[32:33], v[38:39], v[36:37]
	v_max_f32_e32 v106, 0, v26
	v_fma_f32 v29, -|v26|, v32, v106
	v_max_f32_e32 v107, 0, v27
	v_fma_f32 v27, -|v27|, v33, v107
	v_pk_mul_f32 v[36:37], v[30:31], v[14:15]
	v_pk_fma_f32 v[30:31], v[30:31], v[14:15], v[14:15] neg_lo:[1,0,0] neg_hi:[1,0,0]
	v_cmp_gt_f32_e64 s[0:1], 0, v14
	v_fma_f32 v40, |v8|, s40, 1.0
	v_fma_f32 v41, |v9|, s40, 1.0
	v_mov_b32_e32 v14, v29
	v_cndmask_b32_e64 v28, v30, v36, s[0:1]
	v_cmp_gt_f32_e64 s[0:1], 0, v15
	v_rcp_f32_e32 v40, v40
	v_rcp_f32_e32 v41, v41
	v_cndmask_b32_e64 v15, v31, v37, s[0:1]
	v_mul_f32_e32 v30, v28, v28
	v_mov_b32_e32 v31, v29
	v_mul_f32_e32 v26, v15, v15
	v_mul_f32_e32 v12, v27, v27
	v_pk_add_f32 v[26:27], v[30:31], v[26:27]
	v_pk_mul_f32 v[30:31], v[28:29], v[14:15] op_sel:[1,0] op_sel_hi:[0,1]
	v_pk_add_f32 v[14:15], v[28:29], v[14:15] op_sel:[1,0] op_sel_hi:[0,1]
	v_pk_mul_f32 v[42:43], v[8:9], v[8:9]
	v_mov_b32_e32 v31, v15
	v_pk_mul_f32 v[42:43], v[42:43], s[64:65] op_sel_hi:[1,0]
	v_pk_fma_f32 v[50:51], v[40:41], s[42:43], v[22:23] op_sel_hi:[1,0,0]
	v_mul_f32_e32 v44, v45, v45
	v_mul_f32_e32 v10, v11, v11
	v_pk_add_f32 v[12:13], v[30:31], v[12:13]
	v_exp_f32_e32 v42, v42
	v_exp_f32_e32 v43, v43
	v_pk_fma_f32 v[50:51], v[40:41], v[50:51], s[48:49] op_sel_hi:[1,1,0]
	v_pk_add_f32 v[10:11], v[44:45], v[10:11]
	v_pk_add_f32 v[12:13], v[26:27], v[12:13]
	v_pk_add_f32 v[26:27], v[10:11], v[12:13]
	v_pk_fma_f32 v[10:11], v[40:41], v[50:51], s[50:51] op_sel_hi:[1,1,0]
	s_nop 0
	v_pk_fma_f32 v[10:11], v[40:41], v[10:11], s[56:57] op_sel_hi:[1,1,0]
	s_nop 0
	v_pk_mul_f32 v[10:11], v[40:41], v[10:11]
	s_waitcnt vmcnt(0)
	v_lshlrev_b32_e32 v40, 16, v6
	v_pk_mul_f32 v[10:11], v[42:43], v[10:11]
	v_and_b32_e32 v41, 0xffff0000, v6
	v_max_f32_e32 v108, 0, v8
	v_fma_f32 v15, -|v8|, v10, v108
	v_max_f32_e32 v109, 0, v9
	v_fma_f32 v9, -|v9|, v11, v109
	v_and_b32_e32 v37, 0x7fffffff, v41
	v_lshlrev_b32_e32 v12, 16, v4
	v_and_b32_e32 v10, 0x7fffffff, v12
	v_and_b32_e32 v13, 0xffff0000, v4
	v_and_b32_e32 v11, 0x7fffffff, v13
	v_pk_fma_f32 v[10:11], v[10:11], s[40:41], 1.0 op_sel_hi:[1,0,0]
	v_mul_f32_e32 v14, v15, v15
	v_rcp_f32_e32 v10, v10
	v_rcp_f32_e32 v11, v11
	v_mul_f32_e32 v8, v9, v9
	v_pk_add_f32 v[28:29], v[14:15], v[8:9]
	v_pk_mul_f32 v[14:15], v[12:13], v[12:13]
	v_pk_fma_f32 v[8:9], v[10:11], s[42:43], v[22:23] op_sel_hi:[1,0,0]
	v_pk_mul_f32 v[14:15], v[14:15], s[64:65] op_sel_hi:[1,0]
	v_pk_fma_f32 v[8:9], v[10:11], v[8:9], s[48:49] op_sel_hi:[1,1,0]
	v_exp_f32_e32 v14, v14
	v_exp_f32_e32 v15, v15
	v_pk_fma_f32 v[8:9], v[10:11], v[8:9], s[50:51] op_sel_hi:[1,1,0]
	v_lshlrev_b32_e32 v4, 16, v5
	v_pk_fma_f32 v[8:9], v[10:11], v[8:9], s[56:57] op_sel_hi:[1,1,0]
	v_and_b32_e32 v5, 0xffff0000, v5
	v_pk_mul_f32 v[8:9], v[10:11], v[8:9]
	v_pk_mul_f32 v[14:15], v[14:15], v[8:9]
	global_load_dwordx4 v[8:11], v[24:25], off offset:512
	v_fma_f32 v34, |v4|, s40, 1.0
	v_fma_f32 v35, |v5|, s40, 1.0
	v_rcp_f32_e32 v34, v34
	v_rcp_f32_e32 v35, v35
	v_max_f32_e32 v110, 0, v12
	v_fma_f32 v31, -|v12|, v14, v110
	v_max_f32_e32 v111, 0, v13
	v_fma_f32 v33, -|v13|, v15, v111
	v_and_b32_e32 v36, 0x7fffffff, v40
	v_pk_fma_f32 v[36:37], v[36:37], s[40:41], 1.0 op_sel_hi:[1,0,0]
	v_pk_fma_f32 v[12:13], v[34:35], s[42:43], v[22:23] op_sel_hi:[1,0,0]
	v_rcp_f32_e32 v38, v36
	v_pk_mul_f32 v[14:15], v[4:5], v[4:5]
	v_pk_fma_f32 v[12:13], v[34:35], v[12:13], s[48:49] op_sel_hi:[1,1,0]
	v_pk_mul_f32 v[14:15], v[14:15], s[64:65] op_sel_hi:[1,0]
	v_pk_fma_f32 v[12:13], v[34:35], v[12:13], s[50:51] op_sel_hi:[1,1,0]
	v_exp_f32_e32 v14, v14
	v_exp_f32_e32 v15, v15
	v_pk_fma_f32 v[12:13], v[34:35], v[12:13], s[56:57] op_sel_hi:[1,1,0]
	v_rcp_f32_e32 v39, v37
	v_pk_mul_f32 v[12:13], v[34:35], v[12:13]
	v_pk_mul_f32 v[12:13], v[14:15], v[12:13]
	v_mul_f32_e32 v30, v31, v31
	v_max_f32_e32 v112, 0, v4
	v_fma_f32 v35, -|v4|, v12, v112
	v_max_f32_e32 v113, 0, v5
	v_fma_f32 v37, -|v5|, v13, v113
	v_mul_f32_e32 v32, v33, v33
	v_pk_fma_f32 v[4:5], v[38:39], s[42:43], v[22:23] op_sel_hi:[1,0,0]
	v_lshlrev_b32_e32 v14, 16, v7
	v_pk_mul_f32 v[12:13], v[40:41], v[40:41]
	v_pk_fma_f32 v[4:5], v[38:39], v[4:5], s[48:49] op_sel_hi:[1,1,0]
	v_pk_mul_f32 v[12:13], v[12:13], s[64:65] op_sel_hi:[1,0]
	v_pk_fma_f32 v[4:5], v[38:39], v[4:5], s[50:51] op_sel_hi:[1,1,0]
	v_exp_f32_e32 v12, v12
	v_exp_f32_e32 v13, v13
	v_and_b32_e32 v15, 0xffff0000, v7
	v_pk_fma_f32 v[4:5], v[38:39], v[4:5], s[56:57] op_sel_hi:[1,1,0]
	v_pk_mul_f32 v[4:5], v[38:39], v[4:5]
	v_fma_f32 v6, |v14|, s40, 1.0
	v_fma_f32 v7, |v15|, s40, 1.0
	v_pk_mul_f32 v[4:5], v[12:13], v[4:5]
	v_rcp_f32_e32 v6, v6
	v_rcp_f32_e32 v7, v7
	v_max_f32_e32 v114, 0, v40
	v_fma_f32 v39, -|v40|, v4, v114
	v_max_f32_e32 v115, 0, v41
	v_fma_f32 v41, -|v41|, v5, v115
	v_mul_f32_e32 v34, v35, v35
	v_mul_f32_e32 v36, v37, v37
	v_pk_add_f32 v[26:27], v[28:29], v[26:27]
	v_pk_add_f32 v[28:29], v[30:31], v[32:33]
	v_pk_mul_f32 v[12:13], v[14:15], v[14:15]
	v_pk_fma_f32 v[4:5], v[6:7], s[42:43], v[22:23] op_sel_hi:[1,0,0]
	v_pk_mul_f32 v[12:13], v[12:13], s[64:65] op_sel_hi:[1,0]
	v_pk_fma_f32 v[4:5], v[6:7], v[4:5], s[48:49] op_sel_hi:[1,1,0]
	v_exp_f32_e32 v12, v12
	v_exp_f32_e32 v13, v13
	v_pk_fma_f32 v[4:5], v[6:7], v[4:5], s[50:51] op_sel_hi:[1,1,0]
	v_pk_fma_f32 v[4:5], v[6:7], v[4:5], s[56:57] op_sel_hi:[1,1,0]
	v_mul_f32_e32 v38, v39, v39
	v_pk_mul_f32 v[4:5], v[6:7], v[4:5]
	v_mul_f32_e32 v40, v41, v41
	v_pk_mul_f32 v[4:5], v[12:13], v[4:5]
	v_pk_add_f32 v[26:27], v[28:29], v[26:27]
	v_max_f32_e32 v116, 0, v14
	v_fma_f32 v43, -|v14|, v4, v116
	v_max_f32_e32 v117, 0, v15
	v_fma_f32 v45, -|v15|, v5, v117
	global_load_dwordx4 v[4:7], v[24:25], off offset:768
	v_pk_add_f32 v[28:29], v[34:35], v[36:37]
	s_waitcnt vmcnt(1)
	v_lshlrev_b32_e32 v48, 16, v8
	v_and_b32_e32 v49, 0xffff0000, v8
	v_fma_f32 v46, |v48|, s40, 1.0
	v_fma_f32 v47, |v49|, s40, 1.0
	v_pk_mul_f32 v[14:15], v[48:49], v[48:49]
	v_rcp_f32_e32 v46, v46
	v_rcp_f32_e32 v47, v47
	v_pk_mul_f32 v[14:15], v[14:15], s[64:65] op_sel_hi:[1,0]
	v_lshlrev_b32_e32 v50, 16, v9
	v_pk_fma_f32 v[12:13], v[46:47], s[42:43], v[22:23] op_sel_hi:[1,0,0]
	v_exp_f32_e32 v14, v14
	v_pk_fma_f32 v[12:13], v[46:47], v[12:13], s[48:49] op_sel_hi:[1,1,0]
	v_exp_f32_e32 v15, v15
	v_and_b32_e32 v51, 0xffff0000, v9
	v_pk_fma_f32 v[12:13], v[46:47], v[12:13], s[50:51] op_sel_hi:[1,1,0]
	v_pk_fma_f32 v[12:13], v[46:47], v[12:13], s[56:57] op_sel_hi:[1,1,0]
	v_fma_f32 v8, |v50|, s40, 1.0
	v_fma_f32 v9, |v51|, s40, 1.0
	v_pk_mul_f32 v[12:13], v[46:47], v[12:13]
	v_rcp_f32_e32 v52, v8
	v_rcp_f32_e32 v53, v9
	v_pk_mul_f32 v[12:13], v[14:15], v[12:13]
	v_max_f32_e32 v80, 0, v48
	v_fma_f32 v47, -|v48|, v12, v80
	v_max_f32_e32 v81, 0, v49
	v_fma_f32 v9, -|v49|, v13, v81
	v_lshlrev_b32_e32 v60, 16, v10
	v_and_b32_e32 v61, 0xffff0000, v10
	v_lshlrev_b32_e32 v10, 16, v11
	v_pk_fma_f32 v[12:13], v[52:53], s[42:43], v[22:23] op_sel_hi:[1,0,0]
	v_pk_mul_f32 v[14:15], v[50:51], v[50:51]
	v_pk_fma_f32 v[12:13], v[52:53], v[12:13], s[48:49] op_sel_hi:[1,1,0]
	v_pk_mul_f32 v[14:15], v[14:15], s[64:65] op_sel_hi:[1,0]
	v_pk_fma_f32 v[12:13], v[52:53], v[12:13], s[50:51] op_sel_hi:[1,1,0]
	v_exp_f32_e32 v14, v14
	v_exp_f32_e32 v15, v15
	v_pk_fma_f32 v[12:13], v[52:53], v[12:13], s[56:57] op_sel_hi:[1,1,0]
	v_pk_mul_f32 v[12:13], v[52:53], v[12:13]
	v_fma_f32 v52, |v60|, s40, 1.0
	v_fma_f32 v53, |v61|, s40, 1.0
	v_pk_mul_f32 v[12:13], v[14:15], v[12:13]
	v_rcp_f32_e32 v52, v52
	v_rcp_f32_e32 v53, v53
	v_max_f32_e32 v82, 0, v50
	v_fma_f32 v49, -|v50|, v12, v82
	v_max_f32_e32 v83, 0, v51
	v_fma_f32 v51, -|v51|, v13, v83
	v_and_b32_e32 v11, 0xffff0000, v11
	v_pk_mul_f32 v[14:15], v[60:61], v[60:61]
	v_pk_fma_f32 v[12:13], v[52:53], s[42:43], v[22:23] op_sel_hi:[1,0,0]
	v_pk_mul_f32 v[14:15], v[14:15], s[64:65] op_sel_hi:[1,0]
	v_pk_fma_f32 v[12:13], v[52:53], v[12:13], s[48:49] op_sel_hi:[1,1,0]
	v_exp_f32_e32 v14, v14
	v_exp_f32_e32 v15, v15
	v_pk_fma_f32 v[12:13], v[52:53], v[12:13], s[50:51] op_sel_hi:[1,1,0]
	v_fma_f32 v62, |v10|, s40, 1.0
	v_fma_f32 v63, |v11|, s40, 1.0
	v_pk_fma_f32 v[12:13], v[52:53], v[12:13], s[56:57] op_sel_hi:[1,1,0]
	v_rcp_f32_e32 v62, v62
	v_pk_mul_f32 v[12:13], v[52:53], v[12:13]
	v_rcp_f32_e32 v63, v63
	v_pk_mul_f32 v[12:13], v[14:15], v[12:13]
	v_max_f32_e32 v84, 0, v60
	v_fma_f32 v53, -|v60|, v12, v84
	v_max_f32_e32 v85, 0, v61
	v_fma_f32 v61, -|v61|, v13, v85
	v_mul_f32_e32 v42, v43, v43
	s_waitcnt vmcnt(0)
	v_lshlrev_b32_e32 v64, 16, v4
	v_and_b32_e32 v65, 0xffff0000, v4
	v_pk_mul_f32 v[14:15], v[10:11], v[10:11]
	v_pk_fma_f32 v[12:13], v[62:63], s[42:43], v[22:23] op_sel_hi:[1,0,0]
	v_pk_mul_f32 v[14:15], v[14:15], s[64:65] op_sel_hi:[1,0]
	v_pk_fma_f32 v[12:13], v[62:63], v[12:13], s[48:49] op_sel_hi:[1,1,0]
	v_exp_f32_e32 v14, v14
	v_exp_f32_e32 v15, v15
	v_pk_fma_f32 v[12:13], v[62:63], v[12:13], s[50:51] op_sel_hi:[1,1,0]
	v_pk_fma_f32 v[12:13], v[62:63], v[12:13], s[56:57] op_sel_hi:[1,1,0]
	v_pk_mul_f32 v[12:13], v[62:63], v[12:13]
	v_fma_f32 v66, |v64|, s40, 1.0
	v_fma_f32 v67, |v65|, s40, 1.0
	v_pk_mul_f32 v[12:13], v[14:15], v[12:13]
	v_rcp_f32_e32 v66, v66
	v_rcp_f32_e32 v67, v67
	v_max_f32_e32 v86, 0, v10
	v_fma_f32 v63, -|v10|, v12, v86
	v_max_f32_e32 v90, 0, v11
	v_fma_f32 v11, -|v11|, v13, v90
	v_lshlrev_b32_e32 v4, 16, v5
	v_and_b32_e32 v5, 0xffff0000, v5
	v_pk_mul_f32 v[14:15], v[64:65], v[64:65]
	v_pk_fma_f32 v[12:13], v[66:67], s[42:43], v[22:23] op_sel_hi:[1,0,0]
	v_pk_mul_f32 v[14:15], v[14:15], s[64:65] op_sel_hi:[1,0]
	v_pk_fma_f32 v[12:13], v[66:67], v[12:13], s[48:49] op_sel_hi:[1,1,0]
	v_exp_f32_e32 v14, v14
	v_exp_f32_e32 v15, v15
	v_pk_fma_f32 v[12:13], v[66:67], v[12:13], s[50:51] op_sel_hi:[1,1,0]
	v_fma_f32 v68, |v4|, s40, 1.0
	v_fma_f32 v69, |v5|, s40, 1.0
	v_pk_fma_f32 v[12:13], v[66:67], v[12:13], s[56:57] op_sel_hi:[1,1,0]
	v_rcp_f32_e32 v68, v68
	v_pk_mul_f32 v[12:13], v[66:67], v[12:13]
	v_rcp_f32_e32 v69, v69
	v_pk_mul_f32 v[12:13], v[14:15], v[12:13]
	v_max_f32_e32 v91, 0, v64
	v_fma_f32 v67, -|v64|, v12, v91
	v_max_f32_e32 v92, 0, v65
	v_fma_f32 v65, -|v65|, v13, v92
	v_mul_f32_e32 v44, v45, v45
	v_pk_add_f32 v[26:27], v[28:29], v[26:27]
	v_pk_add_f32 v[28:29], v[38:39], v[40:41]
	v_pk_fma_f32 v[12:13], v[68:69], s[42:43], v[22:23] op_sel_hi:[1,0,0]
	v_pk_mul_f32 v[14:15], v[4:5], v[4:5]
	v_pk_fma_f32 v[12:13], v[68:69], v[12:13], s[48:49] op_sel_hi:[1,1,0]
	v_pk_mul_f32 v[14:15], v[14:15], s[64:65] op_sel_hi:[1,0]
	v_pk_fma_f32 v[12:13], v[68:69], v[12:13], s[50:51] op_sel_hi:[1,1,0]
	v_exp_f32_e32 v70, v14
	v_exp_f32_e32 v71, v15
	v_pk_fma_f32 v[72:73], v[68:69], v[12:13], s[56:57] op_sel_hi:[1,1,0]
	global_load_dwordx4 v[12:15], v[24:25], off offset:1024
	v_mul_f32_e32 v46, v47, v47
	v_mul_f32_e32 v8, v9, v9
	v_pk_add_f32 v[26:27], v[28:29], v[26:27]
	v_pk_add_f32 v[28:29], v[42:43], v[44:45]
	v_mul_f32_e32 v48, v49, v49
	v_mul_f32_e32 v50, v51, v51
	v_pk_add_f32 v[26:27], v[28:29], v[26:27]
	v_pk_add_f32 v[8:9], v[46:47], v[8:9]
	v_mul_f32_e32 v52, v53, v53
	v_mul_f32_e32 v60, v61, v61
	v_pk_mul_f32 v[68:69], v[68:69], v[72:73]
	v_pk_add_f32 v[8:9], v[8:9], v[26:27]
	v_pk_add_f32 v[26:27], v[48:49], v[50:51]
	v_pk_mul_f32 v[68:69], v[70:71], v[68:69]
	v_pk_add_f32 v[8:9], v[26:27], v[8:9]
	v_pk_add_f32 v[26:27], v[52:53], v[60:61]
	v_lshlrev_b32_e32 v28, 16, v6
	v_and_b32_e32 v29, 0xffff0000, v6
	v_max_f32_e32 v93, 0, v4
	v_fma_f32 v73, -|v4|, v68, v93
	v_max_f32_e32 v94, 0, v5
	v_fma_f32 v5, -|v5|, v69, v94
	v_pk_add_f32 v[8:9], v[26:27], v[8:9]
	v_mul_f32_e32 v62, v63, v63
	v_mul_f32_e32 v10, v11, v11
	v_fma_f32 v26, |v28|, s40, 1.0
	v_fma_f32 v27, |v29|, s40, 1.0
	v_mul_f32_e32 v66, v67, v67
	v_mul_f32_e32 v64, v65, v65
	v_pk_add_f32 v[10:11], v[62:63], v[10:11]
	v_rcp_f32_e32 v30, v26
	v_rcp_f32_e32 v31, v27
	v_mul_f32_e32 v72, v73, v73
	v_mul_f32_e32 v4, v5, v5
	v_pk_add_f32 v[8:9], v[10:11], v[8:9]
	v_pk_add_f32 v[10:11], v[66:67], v[64:65]
	v_pk_add_f32 v[4:5], v[72:73], v[4:5]
	v_pk_add_f32 v[8:9], v[10:11], v[8:9]
	v_cmp_gt_f32_e64 s[0:1], 0, v28
	v_pk_add_f32 v[26:27], v[4:5], v[8:9]
	v_pk_mul_f32 v[8:9], v[28:29], v[28:29]
	v_pk_fma_f32 v[4:5], v[30:31], s[42:43], v[22:23] op_sel_hi:[1,0,0]
	v_pk_mul_f32 v[8:9], v[8:9], s[64:65] op_sel_hi:[1,0]
	v_pk_fma_f32 v[4:5], v[30:31], v[4:5], s[48:49] op_sel_hi:[1,1,0]
	v_exp_f32_e32 v8, v8
	v_exp_f32_e32 v9, v9
	v_pk_fma_f32 v[4:5], v[30:31], v[4:5], s[50:51] op_sel_hi:[1,1,0]
	v_lshlrev_b32_e32 v6, 16, v7
	v_pk_fma_f32 v[4:5], v[30:31], v[4:5], s[56:57] op_sel_hi:[1,1,0]
	v_and_b32_e32 v7, 0xffff0000, v7
	v_pk_mul_f32 v[4:5], v[30:31], v[4:5]
	s_nop 0
	v_pk_mul_f32 v[4:5], v[8:9], v[4:5]
	s_nop 0
	v_pk_mul_f32 v[8:9], v[28:29], v[4:5]
	v_pk_fma_f32 v[4:5], v[28:29], v[4:5], v[28:29] neg_lo:[1,0,0] neg_hi:[1,0,0]
	s_nop 0
	v_cndmask_b32_e64 v11, v4, v8, s[0:1]
	v_cmp_gt_f32_e64 s[0:1], 0, v29
	v_and_b32_e32 v8, 0x7fffffff, v6
	v_mul_f32_e32 v10, v11, v11
	v_cndmask_b32_e64 v5, v5, v9, s[0:1]
	v_and_b32_e32 v9, 0x7fffffff, v7
	v_pk_fma_f32 v[8:9], v[8:9], s[40:41], 1.0 op_sel_hi:[1,0,0]
	v_mul_f32_e32 v4, v5, v5
	v_rcp_f32_e32 v8, v8
	v_rcp_f32_e32 v9, v9
	v_pk_add_f32 v[28:29], v[10:11], v[4:5]
	v_pk_mul_f32 v[10:11], v[6:7], v[6:7]
	v_cmp_gt_f32_e64 s[0:1], 0, v6
	v_pk_fma_f32 v[4:5], v[8:9], s[42:43], v[22:23] op_sel_hi:[1,0,0]
	v_pk_mul_f32 v[10:11], v[10:11], s[64:65] op_sel_hi:[1,0]
	v_pk_fma_f32 v[4:5], v[8:9], v[4:5], s[48:49] op_sel_hi:[1,1,0]
	v_exp_f32_e32 v10, v10
	v_exp_f32_e32 v11, v11
	v_pk_fma_f32 v[4:5], v[8:9], v[4:5], s[50:51] op_sel_hi:[1,1,0]
	v_pk_add_f32 v[26:27], v[28:29], v[26:27]
	v_pk_fma_f32 v[4:5], v[8:9], v[4:5], s[56:57] op_sel_hi:[1,1,0]
	s_nop 0
	v_pk_mul_f32 v[4:5], v[8:9], v[4:5]
	s_nop 0
	v_pk_mul_f32 v[4:5], v[10:11], v[4:5]
	global_load_dwordx4 v[8:11], v[24:25], off offset:1280
	s_waitcnt vmcnt(1)
	v_lshlrev_b32_e32 v36, 16, v12
	v_and_b32_e32 v37, 0xffff0000, v12
	v_fma_f32 v34, |v36|, s40, 1.0
	v_fma_f32 v35, |v37|, s40, 1.0
	v_pk_mul_f32 v[32:33], v[6:7], v[4:5]
	v_rcp_f32_e32 v34, v34
	v_rcp_f32_e32 v35, v35
	v_pk_fma_f32 v[4:5], v[6:7], v[4:5], v[6:7] neg_lo:[1,0,0] neg_hi:[1,0,0]
	v_lshlrev_b32_e32 v38, 16, v13
	v_cndmask_b32_e64 v31, v4, v32, s[0:1]
	v_cmp_gt_f32_e64 s[0:1], 0, v7
	v_pk_mul_f32 v[6:7], v[36:37], v[36:37]
	v_and_b32_e32 v39, 0xffff0000, v13
	v_cndmask_b32_e64 v33, v5, v33, s[0:1]
	v_pk_fma_f32 v[4:5], v[34:35], s[42:43], v[22:23] op_sel_hi:[1,0,0]
	v_pk_mul_f32 v[6:7], v[6:7], s[64:65] op_sel_hi:[1,0]
	v_pk_fma_f32 v[4:5], v[34:35], v[4:5], s[48:49] op_sel_hi:[1,1,0]
	v_exp_f32_e32 v6, v6
	v_exp_f32_e32 v7, v7
	v_pk_fma_f32 v[4:5], v[34:35], v[4:5], s[50:51] op_sel_hi:[1,1,0]
	v_pk_fma_f32 v[4:5], v[34:35], v[4:5], s[56:57] op_sel_hi:[1,1,0]
	v_fma_f32 v12, |v38|, s40, 1.0
	v_fma_f32 v13, |v39|, s40, 1.0
	v_pk_mul_f32 v[4:5], v[34:35], v[4:5]
	v_rcp_f32_e32 v40, v12
	v_rcp_f32_e32 v41, v13
	v_pk_mul_f32 v[4:5], v[6:7], v[4:5]
	v_max_f32_e32 v95, 0, v36
	v_fma_f32 v35, -|v36|, v4, v95
	v_max_f32_e32 v96, 0, v37
	v_fma_f32 v13, -|v37|, v5, v96
	v_lshlrev_b32_e32 v42, 16, v14
	v_and_b32_e32 v43, 0xffff0000, v14
	v_lshlrev_b32_e32 v44, 16, v15
	v_pk_fma_f32 v[4:5], v[40:41], s[42:43], v[22:23] op_sel_hi:[1,0,0]
	v_pk_mul_f32 v[6:7], v[38:39], v[38:39]
	v_pk_fma_f32 v[4:5], v[40:41], v[4:5], s[48:49] op_sel_hi:[1,1,0]
	v_pk_mul_f32 v[6:7], v[6:7], s[64:65] op_sel_hi:[1,0]
	v_pk_fma_f32 v[4:5], v[40:41], v[4:5], s[50:51] op_sel_hi:[1,1,0]
	v_exp_f32_e32 v6, v6
	v_exp_f32_e32 v7, v7
	v_pk_fma_f32 v[4:5], v[40:41], v[4:5], s[56:57] op_sel_hi:[1,1,0]
	v_pk_mul_f32 v[4:5], v[40:41], v[4:5]
	v_fma_f32 v40, |v42|, s40, 1.0
	v_fma_f32 v41, |v43|, s40, 1.0
	v_pk_mul_f32 v[4:5], v[6:7], v[4:5]
	v_rcp_f32_e32 v40, v40
	v_rcp_f32_e32 v41, v41
	v_max_f32_e32 v97, 0, v38
	v_fma_f32 v37, -|v38|, v4, v97
	v_max_f32_e32 v98, 0, v39
	v_fma_f32 v39, -|v39|, v5, v98
	v_and_b32_e32 v45, 0xffff0000, v15
	v_pk_mul_f32 v[6:7], v[42:43], v[42:43]
	v_pk_fma_f32 v[4:5], v[40:41], s[42:43], v[22:23] op_sel_hi:[1,0,0]
	v_pk_mul_f32 v[6:7], v[6:7], s[64:65] op_sel_hi:[1,0]
	v_pk_fma_f32 v[4:5], v[40:41], v[4:5], s[48:49] op_sel_hi:[1,1,0]
	v_exp_f32_e32 v6, v6
	v_exp_f32_e32 v7, v7
	v_pk_fma_f32 v[4:5], v[40:41], v[4:5], s[50:51] op_sel_hi:[1,1,0]
	v_fma_f32 v14, |v44|, s40, 1.0
	v_fma_f32 v15, |v45|, s40, 1.0
	v_pk_fma_f32 v[4:5], v[40:41], v[4:5], s[56:57] op_sel_hi:[1,1,0]
	v_rcp_f32_e32 v46, v14
	v_pk_mul_f32 v[4:5], v[40:41], v[4:5]
	v_rcp_f32_e32 v47, v15
	v_pk_mul_f32 v[4:5], v[6:7], v[4:5]
	v_max_f32_e32 v99, 0, v42
	v_fma_f32 v41, -|v42|, v4, v99
	v_max_f32_e32 v100, 0, v43
	v_fma_f32 v15, -|v43|, v5, v100
	v_mul_f32_e32 v30, v31, v31
	s_waitcnt vmcnt(0)
	v_lshlrev_b32_e32 v48, 16, v8
	v_and_b32_e32 v49, 0xffff0000, v8
	v_pk_fma_f32 v[4:5], v[46:47], s[42:43], v[22:23] op_sel_hi:[1,0,0]
	v_pk_mul_f32 v[6:7], v[44:45], v[44:45]
	v_pk_fma_f32 v[4:5], v[46:47], v[4:5], s[48:49] op_sel_hi:[1,1,0]
	v_pk_mul_f32 v[6:7], v[6:7], s[64:65] op_sel_hi:[1,0]
	v_pk_fma_f32 v[4:5], v[46:47], v[4:5], s[50:51] op_sel_hi:[1,1,0]
	v_exp_f32_e32 v6, v6
	v_exp_f32_e32 v7, v7
	v_pk_fma_f32 v[4:5], v[46:47], v[4:5], s[56:57] op_sel_hi:[1,1,0]
	v_pk_mul_f32 v[4:5], v[46:47], v[4:5]
	v_fma_f32 v46, |v48|, s40, 1.0
	v_fma_f32 v47, |v49|, s40, 1.0
	v_pk_mul_f32 v[4:5], v[6:7], v[4:5]
	v_rcp_f32_e32 v46, v46
	v_rcp_f32_e32 v47, v47
	v_max_f32_e32 v104, 0, v44
	v_fma_f32 v43, -|v44|, v4, v104
	v_max_f32_e32 v105, 0, v45
	v_fma_f32 v45, -|v45|, v5, v105
	v_lshlrev_b32_e32 v60, 16, v9
	v_and_b32_e32 v61, 0xffff0000, v9
	v_pk_mul_f32 v[6:7], v[48:49], v[48:49]
	v_pk_fma_f32 v[4:5], v[46:47], s[42:43], v[22:23] op_sel_hi:[1,0,0]
	v_pk_mul_f32 v[6:7], v[6:7], s[64:65] op_sel_hi:[1,0]
	v_pk_fma_f32 v[4:5], v[46:47], v[4:5], s[48:49] op_sel_hi:[1,1,0]
	v_exp_f32_e32 v6, v6
	v_exp_f32_e32 v7, v7
	v_pk_fma_f32 v[4:5], v[46:47], v[4:5], s[50:51] op_sel_hi:[1,1,0]
	v_pk_fma_f32 v[4:5], v[46:47], v[4:5], s[56:57] op_sel_hi:[1,1,0]
	v_fma_f32 v8, |v60|, s40, 1.0
	v_fma_f32 v9, |v61|, s40, 1.0
	v_pk_mul_f32 v[4:5], v[46:47], v[4:5]
	v_rcp_f32_e32 v62, v8
	v_pk_mul_f32 v[46:47], v[6:7], v[4:5]
	global_load_dwordx4 v[4:7], v[24:25], off offset:1536
	v_rcp_f32_e32 v63, v9
	v_max_f32_e32 v107, 0, v49
	v_fma_f32 v9, -|v49|, v47, v107
	v_max_f32_e32 v106, 0, v48
	v_fma_f32 v47, -|v48|, v46, v106
	v_lshlrev_b32_e32 v66, 16, v11
	v_and_b32_e32 v67, 0xffff0000, v11
	v_pk_fma_f32 v[48:49], v[62:63], s[42:43], v[22:23] op_sel_hi:[1,0,0]
	v_and_b32_e32 v11, 0x7fffffff, v67
	v_pk_fma_f32 v[48:49], v[62:63], v[48:49], s[48:49] op_sel_hi:[1,1,0]
	v_pk_mul_f32 v[50:51], v[60:61], v[60:61]
	v_pk_fma_f32 v[48:49], v[62:63], v[48:49], s[50:51] op_sel_hi:[1,1,0]
	v_pk_mul_f32 v[50:51], v[50:51], s[64:65] op_sel_hi:[1,0]
	v_pk_fma_f32 v[48:49], v[62:63], v[48:49], s[56:57] op_sel_hi:[1,1,0]
	v_exp_f32_e32 v50, v50
	v_exp_f32_e32 v51, v51
	v_pk_mul_f32 v[48:49], v[62:63], v[48:49]
	v_lshlrev_b32_e32 v62, 16, v10
	v_and_b32_e32 v63, 0xffff0000, v10
	v_fma_f32 v64, |v62|, s40, 1.0
	v_fma_f32 v65, |v63|, s40, 1.0
	v_pk_mul_f32 v[48:49], v[50:51], v[48:49]
	v_rcp_f32_e32 v64, v64
	v_rcp_f32_e32 v65, v65
	v_max_f32_e32 v109, 0, v61
	v_fma_f32 v51, -|v61|, v49, v109
	v_max_f32_e32 v108, 0, v60
	v_fma_f32 v49, -|v60|, v48, v108
	v_and_b32_e32 v10, 0x7fffffff, v66
	v_pk_fma_f32 v[10:11], v[10:11], s[40:41], 1.0 op_sel_hi:[1,0,0]
	v_pk_mul_f32 v[60:61], v[62:63], v[62:63]
	v_rcp_f32_e32 v68, v10
	v_pk_fma_f32 v[52:53], v[64:65], s[42:43], v[22:23] op_sel_hi:[1,0,0]
	v_pk_mul_f32 v[60:61], v[60:61], s[64:65] op_sel_hi:[1,0]
	v_pk_fma_f32 v[52:53], v[64:65], v[52:53], s[48:49] op_sel_hi:[1,1,0]
	v_exp_f32_e32 v60, v60
	v_exp_f32_e32 v61, v61
	v_pk_fma_f32 v[52:53], v[64:65], v[52:53], s[50:51] op_sel_hi:[1,1,0]
	v_rcp_f32_e32 v69, v11
	v_pk_fma_f32 v[52:53], v[64:65], v[52:53], s[56:57] op_sel_hi:[1,1,0]
	v_pk_mul_f32 v[52:53], v[64:65], v[52:53]
	v_mul_f32_e32 v32, v33, v33
	v_pk_mul_f32 v[52:53], v[60:61], v[52:53]
	v_mul_f32_e32 v34, v35, v35
	v_max_f32_e32 v111, 0, v63
	v_fma_f32 v11, -|v63|, v53, v111
	v_max_f32_e32 v110, 0, v62
	v_fma_f32 v53, -|v62|, v52, v110
	v_mul_f32_e32 v12, v13, v13
	v_pk_mul_f32 v[62:63], v[66:67], v[66:67]
	v_pk_add_f32 v[28:29], v[30:31], v[32:33]
	v_pk_fma_f32 v[60:61], v[68:69], s[42:43], v[22:23] op_sel_hi:[1,0,0]
	v_pk_mul_f32 v[62:63], v[62:63], s[64:65] op_sel_hi:[1,0]
	v_pk_fma_f32 v[60:61], v[68:69], v[60:61], s[48:49] op_sel_hi:[1,1,0]
	v_exp_f32_e32 v62, v62
	v_exp_f32_e32 v63, v63
	v_pk_fma_f32 v[60:61], v[68:69], v[60:61], s[50:51] op_sel_hi:[1,1,0]
	v_pk_fma_f32 v[60:61], v[68:69], v[60:61], s[56:57] op_sel_hi:[1,1,0]
	v_mul_f32_e32 v36, v37, v37
	v_pk_mul_f32 v[60:61], v[68:69], v[60:61]
	v_mul_f32_e32 v38, v39, v39
	v_pk_mul_f32 v[60:61], v[62:63], v[60:61]
	v_pk_add_f32 v[26:27], v[28:29], v[26:27]
	v_max_f32_e32 v112, 0, v66
	v_fma_f32 v71, -|v66|, v60, v112
	v_max_f32_e32 v113, 0, v67
	v_fma_f32 v65, -|v67|, v61, v113
	global_load_dwordx4 v[60:63], v[24:25], off offset:1792
	v_pk_add_f32 v[12:13], v[34:35], v[12:13]
	v_mul_f32_e32 v40, v41, v41
	s_waitcnt vmcnt(1)
	v_lshlrev_b32_e32 v24, 16, v4
	v_and_b32_e32 v25, 0xffff0000, v4
	v_fma_f32 v72, |v24|, s40, 1.0
	v_fma_f32 v73, |v25|, s40, 1.0
	v_pk_mul_f32 v[68:69], v[24:25], v[24:25]
	v_rcp_f32_e32 v72, v72
	v_rcp_f32_e32 v73, v73
	v_mul_f32_e32 v14, v15, v15
	v_pk_mul_f32 v[68:69], v[68:69], s[64:65] op_sel_hi:[1,0]
	v_pk_add_f32 v[12:13], v[12:13], v[26:27]
	v_pk_fma_f32 v[66:67], v[72:73], s[42:43], v[22:23] op_sel_hi:[1,0,0]
	v_pk_add_f32 v[26:27], v[36:37], v[38:39]
	v_mul_f32_e32 v42, v43, v43
	v_mul_f32_e32 v44, v45, v45
	v_pk_fma_f32 v[66:67], v[72:73], v[66:67], s[48:49] op_sel_hi:[1,1,0]
	v_exp_f32_e32 v68, v68
	v_exp_f32_e32 v69, v69
	v_pk_add_f32 v[12:13], v[26:27], v[12:13]
	v_pk_add_f32 v[14:15], v[40:41], v[14:15]
	v_mul_f32_e32 v46, v47, v47
	v_mul_f32_e32 v8, v9, v9
	v_pk_fma_f32 v[66:67], v[72:73], v[66:67], s[50:51] op_sel_hi:[1,1,0]
	v_pk_add_f32 v[12:13], v[14:15], v[12:13]
	v_pk_add_f32 v[14:15], v[42:43], v[44:45]
	v_mul_f32_e32 v48, v49, v49
	v_mul_f32_e32 v50, v51, v51
	v_pk_fma_f32 v[66:67], v[72:73], v[66:67], s[56:57] op_sel_hi:[1,1,0]
	v_pk_add_f32 v[12:13], v[14:15], v[12:13]
	v_pk_add_f32 v[8:9], v[46:47], v[8:9]
	v_pk_mul_f32 v[66:67], v[72:73], v[66:67]
	v_pk_add_f32 v[8:9], v[8:9], v[12:13]
	v_pk_add_f32 v[12:13], v[48:49], v[50:51]
	v_lshlrev_b32_e32 v4, 16, v5
	v_and_b32_e32 v5, 0xffff0000, v5
	v_pk_mul_f32 v[66:67], v[68:69], v[66:67]
	v_pk_add_f32 v[8:9], v[12:13], v[8:9]
	v_max_f32_e32 v114, 0, v24
	v_fma_f32 v73, -|v24|, v66, v114
	v_max_f32_e32 v115, 0, v25
	v_fma_f32 v25, -|v25|, v67, v115
	v_fma_f32 v12, |v4|, s40, 1.0
	v_fma_f32 v13, |v5|, s40, 1.0
	v_mul_f32_e32 v52, v53, v53
	v_mul_f32_e32 v10, v11, v11
	v_rcp_f32_e32 v12, v12
	v_rcp_f32_e32 v13, v13
	v_mul_f32_e32 v70, v71, v71
	v_mul_f32_e32 v64, v65, v65
	v_pk_add_f32 v[10:11], v[52:53], v[10:11]
	v_mul_f32_e32 v72, v73, v73
	v_mul_f32_e32 v24, v25, v25
	v_pk_add_f32 v[8:9], v[10:11], v[8:9]
	v_pk_add_f32 v[10:11], v[70:71], v[64:65]
	v_pk_mul_f32 v[14:15], v[4:5], v[4:5]
	v_pk_add_f32 v[8:9], v[10:11], v[8:9]
	v_pk_add_f32 v[10:11], v[72:73], v[24:25]
	v_pk_mul_f32 v[14:15], v[14:15], s[64:65] op_sel_hi:[1,0]
	v_pk_add_f32 v[8:9], v[10:11], v[8:9]
	v_pk_fma_f32 v[10:11], v[12:13], s[42:43], v[22:23] op_sel_hi:[1,0,0]
	v_exp_f32_e32 v14, v14
	v_pk_fma_f32 v[10:11], v[12:13], v[10:11], s[48:49] op_sel_hi:[1,1,0]
	v_exp_f32_e32 v15, v15
	v_pk_fma_f32 v[10:11], v[12:13], v[10:11], s[50:51] op_sel_hi:[1,1,0]
	v_pk_fma_f32 v[10:11], v[12:13], v[10:11], s[56:57] op_sel_hi:[1,1,0]
	s_waitcnt vmcnt(0)
	v_lshlrev_b32_e32 v28, 16, v60
	v_pk_mul_f32 v[10:11], v[12:13], v[10:11]
	v_and_b32_e32 v29, 0xffff0000, v60
	v_pk_mul_f32 v[10:11], v[14:15], v[10:11]
	v_and_b32_e32 v31, 0x7fffffff, v29
	v_max_f32_e32 v116, 0, v4
	v_fma_f32 v15, -|v4|, v10, v116
	v_max_f32_e32 v117, 0, v5
	v_fma_f32 v5, -|v5|, v11, v117
	v_and_b32_e32 v30, 0x7fffffff, v28
	v_lshlrev_b32_e32 v10, 16, v6
	v_and_b32_e32 v12, 0x7fffffff, v10
	v_and_b32_e32 v11, 0xffff0000, v6
	v_and_b32_e32 v13, 0x7fffffff, v11
	v_pk_fma_f32 v[12:13], v[12:13], s[40:41], 1.0 op_sel_hi:[1,0,0]
	v_mul_f32_e32 v14, v15, v15
	v_rcp_f32_e32 v12, v12
	v_rcp_f32_e32 v13, v13
	v_mul_f32_e32 v4, v5, v5
	v_pk_mul_f32 v[24:25], v[10:11], v[10:11]
	v_pk_add_f32 v[4:5], v[14:15], v[4:5]
	v_pk_fma_f32 v[14:15], v[12:13], s[42:43], v[22:23] op_sel_hi:[1,0,0]
	v_pk_mul_f32 v[24:25], v[24:25], s[64:65] op_sel_hi:[1,0]
	v_pk_fma_f32 v[14:15], v[12:13], v[14:15], s[48:49] op_sel_hi:[1,1,0]
	v_exp_f32_e32 v24, v24
	v_exp_f32_e32 v25, v25
	v_pk_fma_f32 v[14:15], v[12:13], v[14:15], s[50:51] op_sel_hi:[1,1,0]
	v_lshlrev_b32_e32 v6, 16, v7
	v_and_b32_e32 v7, 0xffff0000, v7
	v_pk_fma_f32 v[14:15], v[12:13], v[14:15], s[56:57] op_sel_hi:[1,1,0]
	v_pk_mul_f32 v[12:13], v[12:13], v[14:15]
	v_fma_f32 v26, |v6|, s40, 1.0
	v_fma_f32 v27, |v7|, s40, 1.0
	v_pk_mul_f32 v[12:13], v[24:25], v[12:13]
	v_rcp_f32_e32 v26, v26
	v_rcp_f32_e32 v27, v27
	v_max_f32_e32 v80, 0, v10
	v_fma_f32 v25, -|v10|, v12, v80
	v_max_f32_e32 v81, 0, v11
	v_fma_f32 v11, -|v11|, v13, v81
	v_pk_fma_f32 v[30:31], v[30:31], s[40:41], 1.0 op_sel_hi:[1,0,0]
	v_lshlrev_b32_e32 v32, 16, v61
	v_rcp_f32_e32 v30, v30
	v_rcp_f32_e32 v31, v31
	v_pk_mul_f32 v[14:15], v[6:7], v[6:7]
	v_pk_fma_f32 v[12:13], v[26:27], s[42:43], v[22:23] op_sel_hi:[1,0,0]
	v_pk_mul_f32 v[14:15], v[14:15], s[64:65] op_sel_hi:[1,0]
	v_pk_fma_f32 v[12:13], v[26:27], v[12:13], s[48:49] op_sel_hi:[1,1,0]
	v_exp_f32_e32 v14, v14
	v_exp_f32_e32 v15, v15
	v_pk_fma_f32 v[12:13], v[26:27], v[12:13], s[50:51] op_sel_hi:[1,1,0]
	v_pk_fma_f32 v[12:13], v[26:27], v[12:13], s[56:57] op_sel_hi:[1,1,0]
	v_and_b32_e32 v33, 0xffff0000, v61
	v_pk_mul_f32 v[12:13], v[26:27], v[12:13]
	v_pk_mul_f32 v[12:13], v[14:15], v[12:13]
	v_max_f32_e32 v82, 0, v6
	v_fma_f32 v27, -|v6|, v12, v82
	v_max_f32_e32 v83, 0, v7
	v_fma_f32 v7, -|v7|, v13, v83
	v_fma_f32 v34, |v32|, s40, 1.0
	v_fma_f32 v35, |v33|, s40, 1.0
	v_rcp_f32_e32 v34, v34
	v_rcp_f32_e32 v35, v35
	v_pk_mul_f32 v[14:15], v[28:29], v[28:29]
	v_pk_fma_f32 v[12:13], v[30:31], s[42:43], v[22:23] op_sel_hi:[1,0,0]
	v_pk_mul_f32 v[14:15], v[14:15], s[64:65] op_sel_hi:[1,0]
	v_pk_fma_f32 v[12:13], v[30:31], v[12:13], s[48:49] op_sel_hi:[1,1,0]
	v_exp_f32_e32 v14, v14
	v_exp_f32_e32 v15, v15
	v_pk_fma_f32 v[12:13], v[30:31], v[12:13], s[50:51] op_sel_hi:[1,1,0]
	v_pk_fma_f32 v[12:13], v[30:31], v[12:13], s[56:57] op_sel_hi:[1,1,0]
	v_lshlrev_b32_e32 v36, 16, v62
	v_pk_mul_f32 v[12:13], v[30:31], v[12:13]
	v_and_b32_e32 v37, 0xffff0000, v62
	v_pk_mul_f32 v[12:13], v[14:15], v[12:13]
	v_max_f32_e32 v84, 0, v28
	v_fma_f32 v31, -|v28|, v12, v84
	v_max_f32_e32 v85, 0, v29
	v_fma_f32 v13, -|v29|, v13, v85
	v_pk_mul_f32 v[28:29], v[32:33], v[32:33]
	v_fma_f32 v38, |v36|, s40, 1.0
	v_fma_f32 v39, |v37|, s40, 1.0
	v_pk_fma_f32 v[14:15], v[34:35], s[42:43], v[22:23] op_sel_hi:[1,0,0]
	v_pk_mul_f32 v[28:29], v[28:29], s[64:65] op_sel_hi:[1,0]
	v_pk_fma_f32 v[14:15], v[34:35], v[14:15], s[48:49] op_sel_hi:[1,1,0]
	v_exp_f32_e32 v28, v28
	v_exp_f32_e32 v29, v29
	v_pk_fma_f32 v[14:15], v[34:35], v[14:15], s[50:51] op_sel_hi:[1,1,0]
	v_rcp_f32_e32 v38, v38
	v_pk_fma_f32 v[14:15], v[34:35], v[14:15], s[56:57] op_sel_hi:[1,1,0]
	v_rcp_f32_e32 v39, v39
	v_pk_mul_f32 v[14:15], v[34:35], v[14:15]
	v_pk_mul_f32 v[14:15], v[28:29], v[14:15]
	v_lshlrev_b32_e32 v40, 16, v63
	v_max_f32_e32 v86, 0, v32
	v_fma_f32 v35, -|v32|, v14, v86
	v_max_f32_e32 v90, 0, v33
	v_fma_f32 v15, -|v33|, v15, v90
	v_and_b32_e32 v41, 0xffff0000, v63
	v_pk_mul_f32 v[32:33], v[36:37], v[36:37]
	v_pk_fma_f32 v[28:29], v[38:39], s[42:43], v[22:23] op_sel_hi:[1,0,0]
	v_pk_mul_f32 v[32:33], v[32:33], s[64:65] op_sel_hi:[1,0]
	v_pk_fma_f32 v[28:29], v[38:39], v[28:29], s[48:49] op_sel_hi:[1,1,0]
	v_exp_f32_e32 v32, v32
	v_exp_f32_e32 v33, v33
	v_pk_fma_f32 v[28:29], v[38:39], v[28:29], s[50:51] op_sel_hi:[1,1,0]
	v_pk_fma_f32 v[28:29], v[38:39], v[28:29], s[56:57] op_sel_hi:[1,1,0]
	v_fma_f32 v42, |v40|, s40, 1.0
	v_fma_f32 v43, |v41|, s40, 1.0
	v_pk_mul_f32 v[28:29], v[38:39], v[28:29]
	v_rcp_f32_e32 v42, v42
	v_pk_mul_f32 v[28:29], v[32:33], v[28:29]
	v_rcp_f32_e32 v43, v43
	v_max_f32_e32 v91, 0, v36
	v_fma_f32 v39, -|v36|, v28, v91
	v_max_f32_e32 v92, 0, v37
	v_fma_f32 v29, -|v37|, v29, v92
	v_pk_fma_f32 v[22:23], v[42:43], s[42:43], v[22:23] op_sel_hi:[1,0,0]
	v_mul_f32_e32 v24, v25, v25
	v_pk_fma_f32 v[22:23], v[42:43], v[22:23], s[48:49] op_sel_hi:[1,1,0]
	v_mul_f32_e32 v10, v11, v11
	v_pk_mul_f32 v[32:33], v[40:41], v[40:41]
	v_pk_fma_f32 v[22:23], v[42:43], v[22:23], s[50:51] op_sel_hi:[1,1,0]
	v_pk_mul_f32 v[32:33], v[32:33], s[64:65] op_sel_hi:[1,0]
	v_pk_fma_f32 v[22:23], v[42:43], v[22:23], s[56:57] op_sel_hi:[1,1,0]
	v_exp_f32_e32 v32, v32
	v_exp_f32_e32 v33, v33
	v_pk_mul_f32 v[22:23], v[42:43], v[22:23]
	v_mul_f32_e32 v26, v27, v27
	v_mul_f32_e32 v6, v7, v7
	v_pk_mul_f32 v[22:23], v[32:33], v[22:23]
	v_pk_add_f32 v[4:5], v[4:5], v[8:9]
	v_pk_add_f32 v[8:9], v[24:25], v[10:11]
	v_mul_f32_e32 v30, v31, v31
	v_mul_f32_e32 v12, v13, v13
	v_max_f32_e32 v93, 0, v40
	v_fma_f32 v37, -|v40|, v22, v93
	v_max_f32_e32 v94, 0, v41
	v_fma_f32 v23, -|v41|, v23, v94
	v_pk_add_f32 v[4:5], v[8:9], v[4:5]
	v_pk_add_f32 v[6:7], v[26:27], v[6:7]
	v_mul_f32_e32 v34, v35, v35
	v_mul_f32_e32 v14, v15, v15
	v_pk_add_f32 v[4:5], v[6:7], v[4:5]
	v_pk_add_f32 v[6:7], v[30:31], v[12:13]
	v_mul_f32_e32 v38, v39, v39
	v_mul_f32_e32 v28, v29, v29
	v_pk_add_f32 v[4:5], v[6:7], v[4:5]
	v_pk_add_f32 v[6:7], v[34:35], v[14:15]
	v_mul_f32_e32 v36, v37, v37
	v_mul_f32_e32 v22, v23, v23
	v_pk_add_f32 v[4:5], v[6:7], v[4:5]
	v_pk_add_f32 v[6:7], v[38:39], v[28:29]
	s_nop 0
	v_pk_add_f32 v[4:5], v[6:7], v[4:5]
	v_pk_add_f32 v[6:7], v[36:37], v[22:23]
	s_nop 0
	v_pk_add_f32 v[4:5], v[6:7], v[4:5]
	ds_bpermute_b32 v7, v56, v5
	ds_bpermute_b32 v6, v56, v4
	s_waitcnt lgkmcnt(0)
	v_pk_add_f32 v[4:5], v[4:5], v[6:7]
	ds_bpermute_b32 v7, v57, v5
	ds_bpermute_b32 v6, v57, v4
	s_waitcnt lgkmcnt(0)
	v_pk_add_f32 v[4:5], v[4:5], v[6:7]
	ds_bpermute_b32 v7, v58, v5
	ds_bpermute_b32 v6, v58, v4
	s_waitcnt lgkmcnt(0)
	v_pk_add_f32 v[4:5], v[4:5], v[6:7]
	ds_bpermute_b32 v7, v59, v5
	ds_bpermute_b32 v6, v59, v4
	s_and_saveexec_b64 s[8:9], vcc
	s_cbranch_execz .LBB0_449
	s_waitcnt lgkmcnt(0)
	v_pk_add_f32 v[4:5], v[4:5], v[6:7]
	s_nop 0
	v_pk_mul_f32 v[4:5], v[4:5], s[66:67] op_sel_hi:[1,0]
	s_nop 0
	v_fma_f32 v4, -v5, v5, v4
	v_max_f32_e32 v4, 0, v4
	v_add_f32_e32 v4, 0x358637bd, v4
	v_mul_f32_e32 v6, 0x4b800000, v4
	v_cmp_gt_f32_e64 s[0:1], s36, v4
	s_nop 1
	v_cndmask_b32_e64 v4, v4, v6, s[0:1]
	v_rsq_f32_e32 v4, v4
	v_lshl_add_u32 v6, v20, 2, 0
	v_add_u32_e32 v7, 0x11000, v6
	ds_write_b32 v7, v5
	v_mul_f32_e32 v5, 0x45800000, v4
	v_cndmask_b32_e64 v4, v4, v5, s[0:1]
	v_add_u32_e32 v5, 0x11200, v6
	ds_write_b32 v5, v4
.LBB0_449:
	s_or_b64 exec, exec, s[8:9]
	v_or_b32_e32 v16, 12, v16
	v_ashrrev_i32_e32 v17, 31, v16
	v_lshl_add_u64 v[4:5], s[6:7], 0, v[16:17]
	v_lshlrev_b64 v[4:5], 11, v[4:5]
	v_lshl_add_u64 v[4:5], s[4:5], 0, v[4:5]
	v_mov_b32_e32 v19, v2
	v_lshl_add_u64 v[20:21], v[4:5], 0, v[18:19]
	global_load_dwordx4 v[8:11], v[20:21], off
	s_waitcnt lgkmcnt(0)
	global_load_dwordx4 v[4:7], v[20:21], off offset:256
	v_mov_b64_e32 v[18:19], s[44:45]
	v_mov_b32_e32 v13, v2
	s_waitcnt vmcnt(1)
	v_lshlrev_b32_e32 v24, 16, v10
	v_and_b32_e32 v25, 0xffff0000, v10
	v_and_b32_e32 v15, 0xffff0000, v8
	v_and_b32_e32 v23, 0xffff0000, v9
	v_lshlrev_b32_e32 v22, 16, v9
	v_lshlrev_b32_e32 v14, 16, v8
	v_lshlrev_b32_e32 v8, 16, v11
	v_and_b32_e32 v9, 0xffff0000, v11
	v_fma_f32 v10, |v24|, s40, 1.0
	v_fma_f32 v11, |v25|, s40, 1.0
	v_fma_f32 v28, |v14|, s40, 1.0
	v_fma_f32 v29, |v15|, s40, 1.0
	v_rcp_f32_e32 v10, v10
	v_rcp_f32_e32 v11, v11
	v_fma_f32 v32, |v22|, s40, 1.0
	v_fma_f32 v33, |v23|, s40, 1.0
	v_rcp_f32_e32 v28, v28
	v_rcp_f32_e32 v29, v29
	v_rcp_f32_e32 v32, v32
	v_rcp_f32_e32 v33, v33
	v_pk_mul_f32 v[26:27], v[24:25], v[24:25]
	v_pk_mul_f32 v[30:31], v[14:15], v[14:15]
	v_pk_mul_f32 v[26:27], v[26:27], s[64:65] op_sel_hi:[1,0]
	v_pk_fma_f32 v[40:41], v[10:11], s[42:43], v[18:19] op_sel_hi:[1,0,0]
	v_pk_mul_f32 v[34:35], v[22:23], v[22:23]
	v_pk_mul_f32 v[30:31], v[30:31], s[64:65] op_sel_hi:[1,0]
	v_exp_f32_e32 v26, v26
	v_exp_f32_e32 v27, v27
	v_pk_fma_f32 v[42:43], v[28:29], s[42:43], v[18:19] op_sel_hi:[1,0,0]
	v_pk_fma_f32 v[40:41], v[10:11], v[40:41], s[48:49] op_sel_hi:[1,1,0]
	v_pk_mul_f32 v[34:35], v[34:35], s[64:65] op_sel_hi:[1,0]
	v_exp_f32_e32 v30, v30
	v_exp_f32_e32 v31, v31
	v_pk_fma_f32 v[44:45], v[32:33], s[42:43], v[18:19] op_sel_hi:[1,0,0]
	v_pk_fma_f32 v[42:43], v[28:29], v[42:43], s[48:49] op_sel_hi:[1,1,0]
	v_pk_fma_f32 v[40:41], v[10:11], v[40:41], s[50:51] op_sel_hi:[1,1,0]
	v_exp_f32_e32 v34, v34
	v_exp_f32_e32 v35, v35
	v_pk_fma_f32 v[44:45], v[32:33], v[44:45], s[48:49] op_sel_hi:[1,1,0]
	v_pk_fma_f32 v[42:43], v[28:29], v[42:43], s[50:51] op_sel_hi:[1,1,0]
	v_pk_fma_f32 v[40:41], v[10:11], v[40:41], s[56:57] op_sel_hi:[1,1,0]
	v_pk_fma_f32 v[44:45], v[32:33], v[44:45], s[50:51] op_sel_hi:[1,1,0]
	v_pk_fma_f32 v[42:43], v[28:29], v[42:43], s[56:57] op_sel_hi:[1,1,0]
	v_pk_mul_f32 v[10:11], v[10:11], v[40:41]
	v_pk_fma_f32 v[44:45], v[32:33], v[44:45], s[56:57] op_sel_hi:[1,1,0]
	v_pk_mul_f32 v[28:29], v[28:29], v[42:43]
	v_pk_mul_f32 v[10:11], v[26:27], v[10:11]
	v_pk_mul_f32 v[32:33], v[32:33], v[44:45]
	v_pk_mul_f32 v[26:27], v[30:31], v[28:29]
	v_max_f32_e32 v95, 0, v24
	v_fma_f32 v41, -|v24|, v10, v95
	v_max_f32_e32 v96, 0, v25
	v_fma_f32 v11, -|v25|, v11, v96
	v_pk_mul_f32 v[28:29], v[34:35], v[32:33]
	v_max_f32_e32 v97, 0, v22
	v_fma_f32 v25, -|v22|, v28, v97
	v_max_f32_e32 v98, 0, v23
	v_fma_f32 v23, -|v23|, v29, v98
	v_pk_mul_f32 v[32:33], v[26:27], v[14:15]
	v_pk_fma_f32 v[26:27], v[26:27], v[14:15], v[14:15] neg_lo:[1,0,0] neg_hi:[1,0,0]
	v_cmp_gt_f32_e64 s[0:1], 0, v14
	v_fma_f32 v36, |v8|, s40, 1.0
	v_fma_f32 v37, |v9|, s40, 1.0
	v_mov_b32_e32 v14, v25
	v_cndmask_b32_e64 v24, v26, v32, s[0:1]
	v_cmp_gt_f32_e64 s[0:1], 0, v15
	v_rcp_f32_e32 v36, v36
	v_rcp_f32_e32 v37, v37
	v_cndmask_b32_e64 v15, v27, v33, s[0:1]
	v_mul_f32_e32 v26, v24, v24
	v_mov_b32_e32 v27, v25
	v_mul_f32_e32 v22, v15, v15
	v_mul_f32_e32 v12, v23, v23
	v_pk_add_f32 v[22:23], v[26:27], v[22:23]
	v_pk_mul_f32 v[26:27], v[24:25], v[14:15] op_sel:[1,0] op_sel_hi:[0,1]
	v_pk_add_f32 v[14:15], v[24:25], v[14:15] op_sel:[1,0] op_sel_hi:[0,1]
	v_pk_mul_f32 v[38:39], v[8:9], v[8:9]
	v_mov_b32_e32 v27, v15
	v_pk_mul_f32 v[38:39], v[38:39], s[64:65] op_sel_hi:[1,0]
	v_pk_fma_f32 v[46:47], v[36:37], s[42:43], v[18:19] op_sel_hi:[1,0,0]
	v_mul_f32_e32 v40, v41, v41
	v_mul_f32_e32 v10, v11, v11
	v_pk_add_f32 v[12:13], v[26:27], v[12:13]
	v_exp_f32_e32 v38, v38
	v_pk_fma_f32 v[46:47], v[36:37], v[46:47], s[48:49] op_sel_hi:[1,1,0]
	v_pk_add_f32 v[10:11], v[40:41], v[10:11]
	v_pk_add_f32 v[12:13], v[22:23], v[12:13]
	v_exp_f32_e32 v39, v39
	v_pk_add_f32 v[22:23], v[10:11], v[12:13]
	v_pk_fma_f32 v[10:11], v[36:37], v[46:47], s[50:51] op_sel_hi:[1,1,0]
	v_pk_fma_f32 v[10:11], v[36:37], v[10:11], s[56:57] op_sel_hi:[1,1,0]
	s_nop 0
	v_pk_mul_f32 v[10:11], v[36:37], v[10:11]
	s_waitcnt vmcnt(0)
	v_lshlrev_b32_e32 v36, 16, v6
	v_pk_mul_f32 v[10:11], v[38:39], v[10:11]
	v_and_b32_e32 v37, 0xffff0000, v6
	v_max_f32_e32 v99, 0, v8
	v_fma_f32 v15, -|v8|, v10, v99
	v_max_f32_e32 v100, 0, v9
	v_fma_f32 v9, -|v9|, v11, v100
	v_and_b32_e32 v33, 0x7fffffff, v37
	v_lshlrev_b32_e32 v12, 16, v4
	v_and_b32_e32 v10, 0x7fffffff, v12
	v_and_b32_e32 v13, 0xffff0000, v4
	v_and_b32_e32 v11, 0x7fffffff, v13
	v_pk_fma_f32 v[10:11], v[10:11], s[40:41], 1.0 op_sel_hi:[1,0,0]
	v_mul_f32_e32 v14, v15, v15
	v_rcp_f32_e32 v10, v10
	v_rcp_f32_e32 v11, v11
	v_mul_f32_e32 v8, v9, v9
	v_pk_add_f32 v[24:25], v[14:15], v[8:9]
	v_pk_mul_f32 v[14:15], v[12:13], v[12:13]
	v_pk_fma_f32 v[8:9], v[10:11], s[42:43], v[18:19] op_sel_hi:[1,0,0]
	v_pk_mul_f32 v[14:15], v[14:15], s[64:65] op_sel_hi:[1,0]
	v_pk_fma_f32 v[8:9], v[10:11], v[8:9], s[48:49] op_sel_hi:[1,1,0]
	v_exp_f32_e32 v14, v14
	v_exp_f32_e32 v15, v15
	v_pk_fma_f32 v[8:9], v[10:11], v[8:9], s[50:51] op_sel_hi:[1,1,0]
	v_lshlrev_b32_e32 v4, 16, v5
	v_pk_fma_f32 v[8:9], v[10:11], v[8:9], s[56:57] op_sel_hi:[1,1,0]
	v_and_b32_e32 v5, 0xffff0000, v5
	v_pk_mul_f32 v[8:9], v[10:11], v[8:9]
	v_pk_mul_f32 v[14:15], v[14:15], v[8:9]
	global_load_dwordx4 v[8:11], v[20:21], off offset:512
	v_fma_f32 v30, |v4|, s40, 1.0
	v_fma_f32 v31, |v5|, s40, 1.0
	v_rcp_f32_e32 v30, v30
	v_rcp_f32_e32 v31, v31
	v_max_f32_e32 v104, 0, v12
	v_fma_f32 v27, -|v12|, v14, v104
	v_max_f32_e32 v105, 0, v13
	v_fma_f32 v29, -|v13|, v15, v105
	v_and_b32_e32 v32, 0x7fffffff, v36
	v_pk_fma_f32 v[32:33], v[32:33], s[40:41], 1.0 op_sel_hi:[1,0,0]
	v_pk_fma_f32 v[12:13], v[30:31], s[42:43], v[18:19] op_sel_hi:[1,0,0]
	v_rcp_f32_e32 v34, v32
	v_pk_mul_f32 v[14:15], v[4:5], v[4:5]
	v_pk_fma_f32 v[12:13], v[30:31], v[12:13], s[48:49] op_sel_hi:[1,1,0]
	v_pk_mul_f32 v[14:15], v[14:15], s[64:65] op_sel_hi:[1,0]
	v_pk_fma_f32 v[12:13], v[30:31], v[12:13], s[50:51] op_sel_hi:[1,1,0]
	v_exp_f32_e32 v14, v14
	v_exp_f32_e32 v15, v15
	v_pk_fma_f32 v[12:13], v[30:31], v[12:13], s[56:57] op_sel_hi:[1,1,0]
	v_rcp_f32_e32 v35, v33
	v_pk_mul_f32 v[12:13], v[30:31], v[12:13]
	v_pk_mul_f32 v[12:13], v[14:15], v[12:13]
	v_mul_f32_e32 v26, v27, v27
	v_max_f32_e32 v106, 0, v4
	v_fma_f32 v31, -|v4|, v12, v106
	v_max_f32_e32 v107, 0, v5
	v_fma_f32 v33, -|v5|, v13, v107
	v_mul_f32_e32 v28, v29, v29
	v_pk_fma_f32 v[4:5], v[34:35], s[42:43], v[18:19] op_sel_hi:[1,0,0]
	v_lshlrev_b32_e32 v14, 16, v7
	v_pk_mul_f32 v[12:13], v[36:37], v[36:37]
	v_pk_fma_f32 v[4:5], v[34:35], v[4:5], s[48:49] op_sel_hi:[1,1,0]
	v_pk_mul_f32 v[12:13], v[12:13], s[64:65] op_sel_hi:[1,0]
	v_pk_fma_f32 v[4:5], v[34:35], v[4:5], s[50:51] op_sel_hi:[1,1,0]
	v_exp_f32_e32 v12, v12
	v_exp_f32_e32 v13, v13
	v_and_b32_e32 v15, 0xffff0000, v7
	v_pk_fma_f32 v[4:5], v[34:35], v[4:5], s[56:57] op_sel_hi:[1,1,0]
	v_pk_mul_f32 v[4:5], v[34:35], v[4:5]
	v_fma_f32 v6, |v14|, s40, 1.0
	v_fma_f32 v7, |v15|, s40, 1.0
	v_pk_mul_f32 v[4:5], v[12:13], v[4:5]
	v_rcp_f32_e32 v6, v6
	v_rcp_f32_e32 v7, v7
	v_max_f32_e32 v108, 0, v36
	v_fma_f32 v35, -|v36|, v4, v108
	v_max_f32_e32 v109, 0, v37
	v_fma_f32 v37, -|v37|, v5, v109
	v_mul_f32_e32 v30, v31, v31
	v_mul_f32_e32 v32, v33, v33
	v_pk_add_f32 v[22:23], v[24:25], v[22:23]
	v_pk_add_f32 v[24:25], v[26:27], v[28:29]
	v_pk_mul_f32 v[12:13], v[14:15], v[14:15]
	v_pk_fma_f32 v[4:5], v[6:7], s[42:43], v[18:19] op_sel_hi:[1,0,0]
	v_pk_mul_f32 v[12:13], v[12:13], s[64:65] op_sel_hi:[1,0]
	v_pk_fma_f32 v[4:5], v[6:7], v[4:5], s[48:49] op_sel_hi:[1,1,0]
	v_exp_f32_e32 v12, v12
	v_exp_f32_e32 v13, v13
	v_pk_fma_f32 v[4:5], v[6:7], v[4:5], s[50:51] op_sel_hi:[1,1,0]
	v_pk_fma_f32 v[4:5], v[6:7], v[4:5], s[56:57] op_sel_hi:[1,1,0]
	v_mul_f32_e32 v34, v35, v35
	v_pk_mul_f32 v[4:5], v[6:7], v[4:5]
	v_mul_f32_e32 v36, v37, v37
	v_pk_mul_f32 v[4:5], v[12:13], v[4:5]
	v_pk_add_f32 v[22:23], v[24:25], v[22:23]
	v_max_f32_e32 v110, 0, v14
	v_fma_f32 v39, -|v14|, v4, v110
	v_max_f32_e32 v111, 0, v15
	v_fma_f32 v41, -|v15|, v5, v111
	global_load_dwordx4 v[4:7], v[20:21], off offset:768
	v_pk_add_f32 v[24:25], v[30:31], v[32:33]
	s_waitcnt vmcnt(1)
	v_lshlrev_b32_e32 v44, 16, v8
	v_and_b32_e32 v45, 0xffff0000, v8
	v_fma_f32 v42, |v44|, s40, 1.0
	v_fma_f32 v43, |v45|, s40, 1.0
	v_pk_mul_f32 v[14:15], v[44:45], v[44:45]
	v_rcp_f32_e32 v42, v42
	v_rcp_f32_e32 v43, v43
	v_pk_mul_f32 v[14:15], v[14:15], s[64:65] op_sel_hi:[1,0]
	v_lshlrev_b32_e32 v46, 16, v9
	v_pk_fma_f32 v[12:13], v[42:43], s[42:43], v[18:19] op_sel_hi:[1,0,0]
	v_exp_f32_e32 v14, v14
	v_pk_fma_f32 v[12:13], v[42:43], v[12:13], s[48:49] op_sel_hi:[1,1,0]
	v_exp_f32_e32 v15, v15
	v_and_b32_e32 v47, 0xffff0000, v9
	v_pk_fma_f32 v[12:13], v[42:43], v[12:13], s[50:51] op_sel_hi:[1,1,0]
	v_pk_fma_f32 v[12:13], v[42:43], v[12:13], s[56:57] op_sel_hi:[1,1,0]
	v_fma_f32 v8, |v46|, s40, 1.0
	v_fma_f32 v9, |v47|, s40, 1.0
	v_pk_mul_f32 v[12:13], v[42:43], v[12:13]
	v_rcp_f32_e32 v48, v8
	v_rcp_f32_e32 v49, v9
	v_pk_mul_f32 v[12:13], v[14:15], v[12:13]
	v_max_f32_e32 v112, 0, v44
	v_fma_f32 v43, -|v44|, v12, v112
	v_max_f32_e32 v113, 0, v45
	v_fma_f32 v9, -|v45|, v13, v113
	v_lshlrev_b32_e32 v50, 16, v10
	v_and_b32_e32 v51, 0xffff0000, v10
	v_lshlrev_b32_e32 v10, 16, v11
	v_pk_fma_f32 v[12:13], v[48:49], s[42:43], v[18:19] op_sel_hi:[1,0,0]
	v_pk_mul_f32 v[14:15], v[46:47], v[46:47]
	v_pk_fma_f32 v[12:13], v[48:49], v[12:13], s[48:49] op_sel_hi:[1,1,0]
	v_pk_mul_f32 v[14:15], v[14:15], s[64:65] op_sel_hi:[1,0]
	v_pk_fma_f32 v[12:13], v[48:49], v[12:13], s[50:51] op_sel_hi:[1,1,0]
	v_exp_f32_e32 v14, v14
	v_exp_f32_e32 v15, v15
	v_pk_fma_f32 v[12:13], v[48:49], v[12:13], s[56:57] op_sel_hi:[1,1,0]
	v_pk_mul_f32 v[12:13], v[48:49], v[12:13]
	v_fma_f32 v48, |v50|, s40, 1.0
	v_fma_f32 v49, |v51|, s40, 1.0
	v_pk_mul_f32 v[12:13], v[14:15], v[12:13]
	v_rcp_f32_e32 v48, v48
	v_rcp_f32_e32 v49, v49
	v_max_f32_e32 v114, 0, v46
	v_fma_f32 v45, -|v46|, v12, v114
	v_max_f32_e32 v115, 0, v47
	v_fma_f32 v47, -|v47|, v13, v115
	v_and_b32_e32 v11, 0xffff0000, v11
	v_pk_mul_f32 v[14:15], v[50:51], v[50:51]
	v_pk_fma_f32 v[12:13], v[48:49], s[42:43], v[18:19] op_sel_hi:[1,0,0]
	v_pk_mul_f32 v[14:15], v[14:15], s[64:65] op_sel_hi:[1,0]
	v_pk_fma_f32 v[12:13], v[48:49], v[12:13], s[48:49] op_sel_hi:[1,1,0]
	v_exp_f32_e32 v14, v14
	v_exp_f32_e32 v15, v15
	v_pk_fma_f32 v[12:13], v[48:49], v[12:13], s[50:51] op_sel_hi:[1,1,0]
	v_fma_f32 v52, |v10|, s40, 1.0
	v_fma_f32 v53, |v11|, s40, 1.0
	v_pk_fma_f32 v[12:13], v[48:49], v[12:13], s[56:57] op_sel_hi:[1,1,0]
	v_rcp_f32_e32 v52, v52
	v_pk_mul_f32 v[12:13], v[48:49], v[12:13]
	v_rcp_f32_e32 v53, v53
	v_pk_mul_f32 v[12:13], v[14:15], v[12:13]
	v_max_f32_e32 v116, 0, v50
	v_fma_f32 v49, -|v50|, v12, v116
	v_max_f32_e32 v117, 0, v51
	v_fma_f32 v51, -|v51|, v13, v117
	v_mul_f32_e32 v38, v39, v39
	s_waitcnt vmcnt(0)
	v_lshlrev_b32_e32 v60, 16, v4
	v_and_b32_e32 v61, 0xffff0000, v4
	v_pk_mul_f32 v[14:15], v[10:11], v[10:11]
	v_pk_fma_f32 v[12:13], v[52:53], s[42:43], v[18:19] op_sel_hi:[1,0,0]
	v_pk_mul_f32 v[14:15], v[14:15], s[64:65] op_sel_hi:[1,0]
	v_pk_fma_f32 v[12:13], v[52:53], v[12:13], s[48:49] op_sel_hi:[1,1,0]
	v_exp_f32_e32 v14, v14
	v_exp_f32_e32 v15, v15
	v_pk_fma_f32 v[12:13], v[52:53], v[12:13], s[50:51] op_sel_hi:[1,1,0]
	v_pk_fma_f32 v[12:13], v[52:53], v[12:13], s[56:57] op_sel_hi:[1,1,0]
	v_pk_mul_f32 v[12:13], v[52:53], v[12:13]
	v_fma_f32 v62, |v60|, s40, 1.0
	v_fma_f32 v63, |v61|, s40, 1.0
	v_pk_mul_f32 v[12:13], v[14:15], v[12:13]
	v_rcp_f32_e32 v62, v62
	v_rcp_f32_e32 v63, v63
	v_max_f32_e32 v80, 0, v10
	v_fma_f32 v53, -|v10|, v12, v80
	v_max_f32_e32 v81, 0, v11
	v_fma_f32 v11, -|v11|, v13, v81
	v_lshlrev_b32_e32 v4, 16, v5
	v_and_b32_e32 v5, 0xffff0000, v5
	v_pk_mul_f32 v[14:15], v[60:61], v[60:61]
	v_pk_fma_f32 v[12:13], v[62:63], s[42:43], v[18:19] op_sel_hi:[1,0,0]
	v_pk_mul_f32 v[14:15], v[14:15], s[64:65] op_sel_hi:[1,0]
	v_pk_fma_f32 v[12:13], v[62:63], v[12:13], s[48:49] op_sel_hi:[1,1,0]
	v_exp_f32_e32 v14, v14
	v_exp_f32_e32 v15, v15
	v_pk_fma_f32 v[12:13], v[62:63], v[12:13], s[50:51] op_sel_hi:[1,1,0]
	v_fma_f32 v64, |v4|, s40, 1.0
	v_fma_f32 v65, |v5|, s40, 1.0
	v_pk_fma_f32 v[12:13], v[62:63], v[12:13], s[56:57] op_sel_hi:[1,1,0]
	v_rcp_f32_e32 v64, v64
	v_pk_mul_f32 v[12:13], v[62:63], v[12:13]
	v_rcp_f32_e32 v65, v65
	v_pk_mul_f32 v[12:13], v[14:15], v[12:13]
	v_max_f32_e32 v82, 0, v60
	v_fma_f32 v63, -|v60|, v12, v82
	v_max_f32_e32 v83, 0, v61
	v_fma_f32 v61, -|v61|, v13, v83
	v_mul_f32_e32 v40, v41, v41
	v_pk_add_f32 v[22:23], v[24:25], v[22:23]
	v_pk_add_f32 v[24:25], v[34:35], v[36:37]
	v_pk_fma_f32 v[12:13], v[64:65], s[42:43], v[18:19] op_sel_hi:[1,0,0]
	v_pk_mul_f32 v[14:15], v[4:5], v[4:5]
	v_pk_fma_f32 v[12:13], v[64:65], v[12:13], s[48:49] op_sel_hi:[1,1,0]
	v_pk_mul_f32 v[14:15], v[14:15], s[64:65] op_sel_hi:[1,0]
	v_pk_fma_f32 v[12:13], v[64:65], v[12:13], s[50:51] op_sel_hi:[1,1,0]
	v_exp_f32_e32 v66, v14
	v_exp_f32_e32 v67, v15
	v_pk_fma_f32 v[68:69], v[64:65], v[12:13], s[56:57] op_sel_hi:[1,1,0]
	global_load_dwordx4 v[12:15], v[20:21], off offset:1024
	v_mul_f32_e32 v42, v43, v43
	v_mul_f32_e32 v8, v9, v9
	v_pk_add_f32 v[22:23], v[24:25], v[22:23]
	v_pk_add_f32 v[24:25], v[38:39], v[40:41]
	v_mul_f32_e32 v44, v45, v45
	v_mul_f32_e32 v46, v47, v47
	v_pk_add_f32 v[22:23], v[24:25], v[22:23]
	v_pk_add_f32 v[8:9], v[42:43], v[8:9]
	v_mul_f32_e32 v48, v49, v49
	v_mul_f32_e32 v50, v51, v51
	v_pk_mul_f32 v[64:65], v[64:65], v[68:69]
	v_pk_add_f32 v[8:9], v[8:9], v[22:23]
	v_pk_add_f32 v[22:23], v[44:45], v[46:47]
	v_pk_mul_f32 v[64:65], v[66:67], v[64:65]
	v_pk_add_f32 v[8:9], v[22:23], v[8:9]
	v_pk_add_f32 v[22:23], v[48:49], v[50:51]
	v_lshlrev_b32_e32 v24, 16, v6
	v_and_b32_e32 v25, 0xffff0000, v6
	v_max_f32_e32 v84, 0, v4
	v_fma_f32 v69, -|v4|, v64, v84
	v_max_f32_e32 v85, 0, v5
	v_fma_f32 v5, -|v5|, v65, v85
	v_pk_add_f32 v[8:9], v[22:23], v[8:9]
	v_mul_f32_e32 v52, v53, v53
	v_mul_f32_e32 v10, v11, v11
	v_fma_f32 v22, |v24|, s40, 1.0
	v_fma_f32 v23, |v25|, s40, 1.0
	v_mul_f32_e32 v62, v63, v63
	v_mul_f32_e32 v60, v61, v61
	v_pk_add_f32 v[10:11], v[52:53], v[10:11]
	v_rcp_f32_e32 v26, v22
	v_rcp_f32_e32 v27, v23
	v_mul_f32_e32 v68, v69, v69
	v_mul_f32_e32 v4, v5, v5
	v_pk_add_f32 v[8:9], v[10:11], v[8:9]
	v_pk_add_f32 v[10:11], v[62:63], v[60:61]
	v_pk_add_f32 v[4:5], v[68:69], v[4:5]
	v_pk_add_f32 v[8:9], v[10:11], v[8:9]
	v_cmp_gt_f32_e64 s[0:1], 0, v24
	v_pk_add_f32 v[22:23], v[4:5], v[8:9]
	v_pk_mul_f32 v[8:9], v[24:25], v[24:25]
	v_pk_fma_f32 v[4:5], v[26:27], s[42:43], v[18:19] op_sel_hi:[1,0,0]
	v_pk_mul_f32 v[8:9], v[8:9], s[64:65] op_sel_hi:[1,0]
	v_pk_fma_f32 v[4:5], v[26:27], v[4:5], s[48:49] op_sel_hi:[1,1,0]
	v_exp_f32_e32 v8, v8
	v_exp_f32_e32 v9, v9
	v_pk_fma_f32 v[4:5], v[26:27], v[4:5], s[50:51] op_sel_hi:[1,1,0]
	v_lshlrev_b32_e32 v6, 16, v7
	v_pk_fma_f32 v[4:5], v[26:27], v[4:5], s[56:57] op_sel_hi:[1,1,0]
	v_and_b32_e32 v7, 0xffff0000, v7
	v_pk_mul_f32 v[4:5], v[26:27], v[4:5]
	s_nop 0
	v_pk_mul_f32 v[4:5], v[8:9], v[4:5]
	s_nop 0
	v_pk_mul_f32 v[8:9], v[24:25], v[4:5]
	v_pk_fma_f32 v[4:5], v[24:25], v[4:5], v[24:25] neg_lo:[1,0,0] neg_hi:[1,0,0]
	s_nop 0
	v_cndmask_b32_e64 v11, v4, v8, s[0:1]
	v_cmp_gt_f32_e64 s[0:1], 0, v25
	v_and_b32_e32 v8, 0x7fffffff, v6
	v_mul_f32_e32 v10, v11, v11
	v_cndmask_b32_e64 v5, v5, v9, s[0:1]
	v_and_b32_e32 v9, 0x7fffffff, v7
	v_pk_fma_f32 v[8:9], v[8:9], s[40:41], 1.0 op_sel_hi:[1,0,0]
	v_mul_f32_e32 v4, v5, v5
	v_rcp_f32_e32 v8, v8
	v_rcp_f32_e32 v9, v9
	v_pk_add_f32 v[24:25], v[10:11], v[4:5]
	v_pk_mul_f32 v[10:11], v[6:7], v[6:7]
	v_cmp_gt_f32_e64 s[0:1], 0, v6
	v_pk_fma_f32 v[4:5], v[8:9], s[42:43], v[18:19] op_sel_hi:[1,0,0]
	v_pk_mul_f32 v[10:11], v[10:11], s[64:65] op_sel_hi:[1,0]
	v_pk_fma_f32 v[4:5], v[8:9], v[4:5], s[48:49] op_sel_hi:[1,1,0]
	v_exp_f32_e32 v10, v10
	v_exp_f32_e32 v11, v11
	v_pk_fma_f32 v[4:5], v[8:9], v[4:5], s[50:51] op_sel_hi:[1,1,0]
	v_pk_add_f32 v[22:23], v[24:25], v[22:23]
	v_pk_fma_f32 v[4:5], v[8:9], v[4:5], s[56:57] op_sel_hi:[1,1,0]
	s_nop 0
	v_pk_mul_f32 v[4:5], v[8:9], v[4:5]
	s_nop 0
	v_pk_mul_f32 v[4:5], v[10:11], v[4:5]
	global_load_dwordx4 v[8:11], v[20:21], off offset:1280
	s_waitcnt vmcnt(1)
	v_lshlrev_b32_e32 v32, 16, v12
	v_and_b32_e32 v33, 0xffff0000, v12
	v_fma_f32 v30, |v32|, s40, 1.0
	v_fma_f32 v31, |v33|, s40, 1.0
	v_pk_mul_f32 v[28:29], v[6:7], v[4:5]
	v_rcp_f32_e32 v30, v30
	v_rcp_f32_e32 v31, v31
	v_pk_fma_f32 v[4:5], v[6:7], v[4:5], v[6:7] neg_lo:[1,0,0] neg_hi:[1,0,0]
	v_lshlrev_b32_e32 v34, 16, v13
	v_cndmask_b32_e64 v27, v4, v28, s[0:1]
	v_cmp_gt_f32_e64 s[0:1], 0, v7
	v_pk_mul_f32 v[6:7], v[32:33], v[32:33]
	v_and_b32_e32 v35, 0xffff0000, v13
	v_cndmask_b32_e64 v29, v5, v29, s[0:1]
	v_pk_fma_f32 v[4:5], v[30:31], s[42:43], v[18:19] op_sel_hi:[1,0,0]
	v_pk_mul_f32 v[6:7], v[6:7], s[64:65] op_sel_hi:[1,0]
	v_pk_fma_f32 v[4:5], v[30:31], v[4:5], s[48:49] op_sel_hi:[1,1,0]
	v_exp_f32_e32 v6, v6
	v_exp_f32_e32 v7, v7
	v_pk_fma_f32 v[4:5], v[30:31], v[4:5], s[50:51] op_sel_hi:[1,1,0]
	v_pk_fma_f32 v[4:5], v[30:31], v[4:5], s[56:57] op_sel_hi:[1,1,0]
	v_fma_f32 v12, |v34|, s40, 1.0
	v_fma_f32 v13, |v35|, s40, 1.0
	v_pk_mul_f32 v[4:5], v[30:31], v[4:5]
	v_rcp_f32_e32 v36, v12
	v_rcp_f32_e32 v37, v13
	v_pk_mul_f32 v[4:5], v[6:7], v[4:5]
	v_max_f32_e32 v86, 0, v32
	v_fma_f32 v31, -|v32|, v4, v86
	v_max_f32_e32 v90, 0, v33
	v_fma_f32 v13, -|v33|, v5, v90
	v_lshlrev_b32_e32 v38, 16, v14
	v_and_b32_e32 v39, 0xffff0000, v14
	v_lshlrev_b32_e32 v40, 16, v15
	v_pk_fma_f32 v[4:5], v[36:37], s[42:43], v[18:19] op_sel_hi:[1,0,0]
	v_pk_mul_f32 v[6:7], v[34:35], v[34:35]
	v_pk_fma_f32 v[4:5], v[36:37], v[4:5], s[48:49] op_sel_hi:[1,1,0]
	v_pk_mul_f32 v[6:7], v[6:7], s[64:65] op_sel_hi:[1,0]
	v_pk_fma_f32 v[4:5], v[36:37], v[4:5], s[50:51] op_sel_hi:[1,1,0]
	v_exp_f32_e32 v6, v6
	v_exp_f32_e32 v7, v7
	v_pk_fma_f32 v[4:5], v[36:37], v[4:5], s[56:57] op_sel_hi:[1,1,0]
	v_pk_mul_f32 v[4:5], v[36:37], v[4:5]
	v_fma_f32 v36, |v38|, s40, 1.0
	v_fma_f32 v37, |v39|, s40, 1.0
	v_pk_mul_f32 v[4:5], v[6:7], v[4:5]
	v_rcp_f32_e32 v36, v36
	v_rcp_f32_e32 v37, v37
	v_max_f32_e32 v91, 0, v34
	v_fma_f32 v33, -|v34|, v4, v91
	v_max_f32_e32 v92, 0, v35
	v_fma_f32 v35, -|v35|, v5, v92
	v_and_b32_e32 v41, 0xffff0000, v15
	v_pk_mul_f32 v[6:7], v[38:39], v[38:39]
	v_pk_fma_f32 v[4:5], v[36:37], s[42:43], v[18:19] op_sel_hi:[1,0,0]
	v_pk_mul_f32 v[6:7], v[6:7], s[64:65] op_sel_hi:[1,0]
	v_pk_fma_f32 v[4:5], v[36:37], v[4:5], s[48:49] op_sel_hi:[1,1,0]
	v_exp_f32_e32 v6, v6
	v_exp_f32_e32 v7, v7
	v_pk_fma_f32 v[4:5], v[36:37], v[4:5], s[50:51] op_sel_hi:[1,1,0]
	v_fma_f32 v14, |v40|, s40, 1.0
	v_fma_f32 v15, |v41|, s40, 1.0
	v_pk_fma_f32 v[4:5], v[36:37], v[4:5], s[56:57] op_sel_hi:[1,1,0]
	v_rcp_f32_e32 v42, v14
	v_pk_mul_f32 v[4:5], v[36:37], v[4:5]
	v_rcp_f32_e32 v43, v15
	v_pk_mul_f32 v[4:5], v[6:7], v[4:5]
	v_max_f32_e32 v93, 0, v38
	v_fma_f32 v37, -|v38|, v4, v93
	v_max_f32_e32 v94, 0, v39
	v_fma_f32 v15, -|v39|, v5, v94
	v_mul_f32_e32 v26, v27, v27
	s_waitcnt vmcnt(0)
	v_lshlrev_b32_e32 v44, 16, v8
	v_and_b32_e32 v45, 0xffff0000, v8
	v_pk_fma_f32 v[4:5], v[42:43], s[42:43], v[18:19] op_sel_hi:[1,0,0]
	v_pk_mul_f32 v[6:7], v[40:41], v[40:41]
	v_pk_fma_f32 v[4:5], v[42:43], v[4:5], s[48:49] op_sel_hi:[1,1,0]
	v_pk_mul_f32 v[6:7], v[6:7], s[64:65] op_sel_hi:[1,0]
	v_pk_fma_f32 v[4:5], v[42:43], v[4:5], s[50:51] op_sel_hi:[1,1,0]
	v_exp_f32_e32 v6, v6
	v_exp_f32_e32 v7, v7
	v_pk_fma_f32 v[4:5], v[42:43], v[4:5], s[56:57] op_sel_hi:[1,1,0]
	v_pk_mul_f32 v[4:5], v[42:43], v[4:5]
	v_fma_f32 v42, |v44|, s40, 1.0
	v_fma_f32 v43, |v45|, s40, 1.0
	v_pk_mul_f32 v[4:5], v[6:7], v[4:5]
	v_rcp_f32_e32 v42, v42
	v_rcp_f32_e32 v43, v43
	v_max_f32_e32 v95, 0, v40
	v_fma_f32 v39, -|v40|, v4, v95
	v_max_f32_e32 v96, 0, v41
	v_fma_f32 v41, -|v41|, v5, v96
	v_lshlrev_b32_e32 v50, 16, v9
	v_and_b32_e32 v51, 0xffff0000, v9
	v_pk_mul_f32 v[6:7], v[44:45], v[44:45]
	v_pk_fma_f32 v[4:5], v[42:43], s[42:43], v[18:19] op_sel_hi:[1,0,0]
	v_pk_mul_f32 v[6:7], v[6:7], s[64:65] op_sel_hi:[1,0]
	v_pk_fma_f32 v[4:5], v[42:43], v[4:5], s[48:49] op_sel_hi:[1,1,0]
	v_exp_f32_e32 v6, v6
	v_exp_f32_e32 v7, v7
	v_pk_fma_f32 v[4:5], v[42:43], v[4:5], s[50:51] op_sel_hi:[1,1,0]
	v_pk_fma_f32 v[4:5], v[42:43], v[4:5], s[56:57] op_sel_hi:[1,1,0]
	v_fma_f32 v8, |v50|, s40, 1.0
	v_fma_f32 v9, |v51|, s40, 1.0
	v_pk_mul_f32 v[4:5], v[42:43], v[4:5]
	v_rcp_f32_e32 v52, v8
	v_pk_mul_f32 v[42:43], v[6:7], v[4:5]
	global_load_dwordx4 v[4:7], v[20:21], off offset:1536
	v_rcp_f32_e32 v53, v9
	v_max_f32_e32 v98, 0, v45
	v_fma_f32 v9, -|v45|, v43, v98
	v_max_f32_e32 v97, 0, v44
	v_fma_f32 v43, -|v44|, v42, v97
	v_lshlrev_b32_e32 v62, 16, v11
	v_and_b32_e32 v63, 0xffff0000, v11
	v_pk_fma_f32 v[44:45], v[52:53], s[42:43], v[18:19] op_sel_hi:[1,0,0]
	v_and_b32_e32 v11, 0x7fffffff, v63
	v_pk_fma_f32 v[44:45], v[52:53], v[44:45], s[48:49] op_sel_hi:[1,1,0]
	v_pk_mul_f32 v[46:47], v[50:51], v[50:51]
	v_pk_fma_f32 v[44:45], v[52:53], v[44:45], s[50:51] op_sel_hi:[1,1,0]
	v_pk_mul_f32 v[46:47], v[46:47], s[64:65] op_sel_hi:[1,0]
	v_pk_fma_f32 v[44:45], v[52:53], v[44:45], s[56:57] op_sel_hi:[1,1,0]
	v_exp_f32_e32 v46, v46
	v_exp_f32_e32 v47, v47
	v_pk_mul_f32 v[44:45], v[52:53], v[44:45]
	v_lshlrev_b32_e32 v52, 16, v10
	v_and_b32_e32 v53, 0xffff0000, v10
	v_fma_f32 v60, |v52|, s40, 1.0
	v_fma_f32 v61, |v53|, s40, 1.0
	v_pk_mul_f32 v[44:45], v[46:47], v[44:45]
	v_rcp_f32_e32 v60, v60
	v_rcp_f32_e32 v61, v61
	v_max_f32_e32 v100, 0, v51
	v_fma_f32 v47, -|v51|, v45, v100
	v_max_f32_e32 v99, 0, v50
	v_fma_f32 v45, -|v50|, v44, v99
	v_and_b32_e32 v10, 0x7fffffff, v62
	v_pk_fma_f32 v[10:11], v[10:11], s[40:41], 1.0 op_sel_hi:[1,0,0]
	v_pk_mul_f32 v[50:51], v[52:53], v[52:53]
	v_rcp_f32_e32 v64, v10
	v_pk_fma_f32 v[48:49], v[60:61], s[42:43], v[18:19] op_sel_hi:[1,0,0]
	v_pk_mul_f32 v[50:51], v[50:51], s[64:65] op_sel_hi:[1,0]
	v_pk_fma_f32 v[48:49], v[60:61], v[48:49], s[48:49] op_sel_hi:[1,1,0]
	v_exp_f32_e32 v50, v50
	v_exp_f32_e32 v51, v51
	v_pk_fma_f32 v[48:49], v[60:61], v[48:49], s[50:51] op_sel_hi:[1,1,0]
	v_rcp_f32_e32 v65, v11
	v_pk_fma_f32 v[48:49], v[60:61], v[48:49], s[56:57] op_sel_hi:[1,1,0]
	v_pk_mul_f32 v[48:49], v[60:61], v[48:49]
	v_mul_f32_e32 v28, v29, v29
	v_pk_mul_f32 v[48:49], v[50:51], v[48:49]
	v_mul_f32_e32 v30, v31, v31
	v_max_f32_e32 v105, 0, v53
	v_fma_f32 v11, -|v53|, v49, v105
	v_max_f32_e32 v104, 0, v52
	v_fma_f32 v49, -|v52|, v48, v104
	v_mul_f32_e32 v12, v13, v13
	v_pk_mul_f32 v[52:53], v[62:63], v[62:63]
	v_pk_add_f32 v[24:25], v[26:27], v[28:29]
	v_pk_fma_f32 v[50:51], v[64:65], s[42:43], v[18:19] op_sel_hi:[1,0,0]
	v_pk_mul_f32 v[52:53], v[52:53], s[64:65] op_sel_hi:[1,0]
	v_pk_fma_f32 v[50:51], v[64:65], v[50:51], s[48:49] op_sel_hi:[1,1,0]
	v_exp_f32_e32 v52, v52
	v_exp_f32_e32 v53, v53
	v_pk_fma_f32 v[50:51], v[64:65], v[50:51], s[50:51] op_sel_hi:[1,1,0]
	v_pk_fma_f32 v[50:51], v[64:65], v[50:51], s[56:57] op_sel_hi:[1,1,0]
	v_mul_f32_e32 v32, v33, v33
	v_pk_mul_f32 v[50:51], v[64:65], v[50:51]
	v_mul_f32_e32 v34, v35, v35
	v_pk_mul_f32 v[50:51], v[52:53], v[50:51]
	v_pk_add_f32 v[22:23], v[24:25], v[22:23]
	v_max_f32_e32 v106, 0, v62
	v_fma_f32 v67, -|v62|, v50, v106
	v_max_f32_e32 v107, 0, v63
	v_fma_f32 v61, -|v63|, v51, v107
	global_load_dwordx4 v[50:53], v[20:21], off offset:1792
	v_pk_add_f32 v[12:13], v[30:31], v[12:13]
	v_mul_f32_e32 v36, v37, v37
	s_waitcnt vmcnt(1)
	v_lshlrev_b32_e32 v20, 16, v4
	v_and_b32_e32 v21, 0xffff0000, v4
	v_fma_f32 v68, |v20|, s40, 1.0
	v_fma_f32 v69, |v21|, s40, 1.0
	v_pk_mul_f32 v[64:65], v[20:21], v[20:21]
	v_rcp_f32_e32 v68, v68
	v_rcp_f32_e32 v69, v69
	v_mul_f32_e32 v14, v15, v15
	v_pk_mul_f32 v[64:65], v[64:65], s[64:65] op_sel_hi:[1,0]
	v_pk_add_f32 v[12:13], v[12:13], v[22:23]
	v_pk_fma_f32 v[62:63], v[68:69], s[42:43], v[18:19] op_sel_hi:[1,0,0]
	v_pk_add_f32 v[22:23], v[32:33], v[34:35]
	v_mul_f32_e32 v38, v39, v39
	v_mul_f32_e32 v40, v41, v41
	v_pk_fma_f32 v[62:63], v[68:69], v[62:63], s[48:49] op_sel_hi:[1,1,0]
	v_exp_f32_e32 v64, v64
	v_exp_f32_e32 v65, v65
	v_pk_add_f32 v[12:13], v[22:23], v[12:13]
	v_pk_add_f32 v[14:15], v[36:37], v[14:15]
	v_mul_f32_e32 v42, v43, v43
	v_mul_f32_e32 v8, v9, v9
	v_pk_fma_f32 v[62:63], v[68:69], v[62:63], s[50:51] op_sel_hi:[1,1,0]
	v_pk_add_f32 v[12:13], v[14:15], v[12:13]
	v_pk_add_f32 v[14:15], v[38:39], v[40:41]
	v_mul_f32_e32 v44, v45, v45
	v_mul_f32_e32 v46, v47, v47
	v_pk_fma_f32 v[62:63], v[68:69], v[62:63], s[56:57] op_sel_hi:[1,1,0]
	v_pk_add_f32 v[12:13], v[14:15], v[12:13]
	v_pk_add_f32 v[8:9], v[42:43], v[8:9]
	v_pk_mul_f32 v[62:63], v[68:69], v[62:63]
	v_pk_add_f32 v[8:9], v[8:9], v[12:13]
	v_pk_add_f32 v[12:13], v[44:45], v[46:47]
	v_lshlrev_b32_e32 v4, 16, v5
	v_and_b32_e32 v5, 0xffff0000, v5
	v_pk_mul_f32 v[62:63], v[64:65], v[62:63]
	v_pk_add_f32 v[8:9], v[12:13], v[8:9]
	v_max_f32_e32 v108, 0, v20
	v_fma_f32 v69, -|v20|, v62, v108
	v_max_f32_e32 v109, 0, v21
	v_fma_f32 v21, -|v21|, v63, v109
	v_fma_f32 v12, |v4|, s40, 1.0
	v_fma_f32 v13, |v5|, s40, 1.0
	v_mul_f32_e32 v48, v49, v49
	v_mul_f32_e32 v10, v11, v11
	v_rcp_f32_e32 v12, v12
	v_rcp_f32_e32 v13, v13
	v_mul_f32_e32 v66, v67, v67
	v_mul_f32_e32 v60, v61, v61
	v_pk_add_f32 v[10:11], v[48:49], v[10:11]
	v_mul_f32_e32 v68, v69, v69
	v_mul_f32_e32 v20, v21, v21
	v_pk_add_f32 v[8:9], v[10:11], v[8:9]
	v_pk_add_f32 v[10:11], v[66:67], v[60:61]
	v_pk_mul_f32 v[14:15], v[4:5], v[4:5]
	v_pk_add_f32 v[8:9], v[10:11], v[8:9]
	v_pk_add_f32 v[10:11], v[68:69], v[20:21]
	v_pk_mul_f32 v[14:15], v[14:15], s[64:65] op_sel_hi:[1,0]
	v_pk_add_f32 v[8:9], v[10:11], v[8:9]
	v_pk_fma_f32 v[10:11], v[12:13], s[42:43], v[18:19] op_sel_hi:[1,0,0]
	v_exp_f32_e32 v14, v14
	v_pk_fma_f32 v[10:11], v[12:13], v[10:11], s[48:49] op_sel_hi:[1,1,0]
	v_exp_f32_e32 v15, v15
	v_pk_fma_f32 v[10:11], v[12:13], v[10:11], s[50:51] op_sel_hi:[1,1,0]
	v_pk_fma_f32 v[10:11], v[12:13], v[10:11], s[56:57] op_sel_hi:[1,1,0]
	s_waitcnt vmcnt(0)
	v_lshlrev_b32_e32 v24, 16, v50
	v_pk_mul_f32 v[10:11], v[12:13], v[10:11]
	v_and_b32_e32 v25, 0xffff0000, v50
	v_pk_mul_f32 v[10:11], v[14:15], v[10:11]
	v_and_b32_e32 v27, 0x7fffffff, v25
	v_max_f32_e32 v110, 0, v4
	v_fma_f32 v15, -|v4|, v10, v110
	v_max_f32_e32 v111, 0, v5
	v_fma_f32 v5, -|v5|, v11, v111
	v_and_b32_e32 v26, 0x7fffffff, v24
	v_lshlrev_b32_e32 v10, 16, v6
	v_and_b32_e32 v12, 0x7fffffff, v10
	v_and_b32_e32 v11, 0xffff0000, v6
	v_and_b32_e32 v13, 0x7fffffff, v11
	v_pk_fma_f32 v[12:13], v[12:13], s[40:41], 1.0 op_sel_hi:[1,0,0]
	v_mul_f32_e32 v14, v15, v15
	v_rcp_f32_e32 v12, v12
	v_rcp_f32_e32 v13, v13
	v_mul_f32_e32 v4, v5, v5
	v_pk_mul_f32 v[20:21], v[10:11], v[10:11]
	v_pk_add_f32 v[4:5], v[14:15], v[4:5]
	v_pk_fma_f32 v[14:15], v[12:13], s[42:43], v[18:19] op_sel_hi:[1,0,0]
	v_pk_mul_f32 v[20:21], v[20:21], s[64:65] op_sel_hi:[1,0]
	v_pk_fma_f32 v[14:15], v[12:13], v[14:15], s[48:49] op_sel_hi:[1,1,0]
	v_exp_f32_e32 v20, v20
	v_exp_f32_e32 v21, v21
	v_pk_fma_f32 v[14:15], v[12:13], v[14:15], s[50:51] op_sel_hi:[1,1,0]
	v_lshlrev_b32_e32 v6, 16, v7
	v_and_b32_e32 v7, 0xffff0000, v7
	v_pk_fma_f32 v[14:15], v[12:13], v[14:15], s[56:57] op_sel_hi:[1,1,0]
	v_pk_mul_f32 v[12:13], v[12:13], v[14:15]
	v_fma_f32 v22, |v6|, s40, 1.0
	v_fma_f32 v23, |v7|, s40, 1.0
	v_pk_mul_f32 v[12:13], v[20:21], v[12:13]
	v_rcp_f32_e32 v22, v22
	v_rcp_f32_e32 v23, v23
	v_max_f32_e32 v112, 0, v10
	v_fma_f32 v21, -|v10|, v12, v112
	v_max_f32_e32 v113, 0, v11
	v_fma_f32 v11, -|v11|, v13, v113
	v_pk_fma_f32 v[26:27], v[26:27], s[40:41], 1.0 op_sel_hi:[1,0,0]
	v_lshlrev_b32_e32 v28, 16, v51
	v_rcp_f32_e32 v26, v26
	v_rcp_f32_e32 v27, v27
	v_pk_mul_f32 v[14:15], v[6:7], v[6:7]
	v_pk_fma_f32 v[12:13], v[22:23], s[42:43], v[18:19] op_sel_hi:[1,0,0]
	v_pk_mul_f32 v[14:15], v[14:15], s[64:65] op_sel_hi:[1,0]
	v_pk_fma_f32 v[12:13], v[22:23], v[12:13], s[48:49] op_sel_hi:[1,1,0]
	v_exp_f32_e32 v14, v14
	v_exp_f32_e32 v15, v15
	v_pk_fma_f32 v[12:13], v[22:23], v[12:13], s[50:51] op_sel_hi:[1,1,0]
	v_pk_fma_f32 v[12:13], v[22:23], v[12:13], s[56:57] op_sel_hi:[1,1,0]
	v_and_b32_e32 v29, 0xffff0000, v51
	v_pk_mul_f32 v[12:13], v[22:23], v[12:13]
	v_pk_mul_f32 v[12:13], v[14:15], v[12:13]
	v_max_f32_e32 v114, 0, v6
	v_fma_f32 v23, -|v6|, v12, v114
	v_max_f32_e32 v115, 0, v7
	v_fma_f32 v7, -|v7|, v13, v115
	v_fma_f32 v30, |v28|, s40, 1.0
	v_fma_f32 v31, |v29|, s40, 1.0
	v_rcp_f32_e32 v30, v30
	v_rcp_f32_e32 v31, v31
	v_pk_mul_f32 v[14:15], v[24:25], v[24:25]
	v_pk_fma_f32 v[12:13], v[26:27], s[42:43], v[18:19] op_sel_hi:[1,0,0]
	v_pk_mul_f32 v[14:15], v[14:15], s[64:65] op_sel_hi:[1,0]
	v_pk_fma_f32 v[12:13], v[26:27], v[12:13], s[48:49] op_sel_hi:[1,1,0]
	v_exp_f32_e32 v14, v14
	v_exp_f32_e32 v15, v15
	v_pk_fma_f32 v[12:13], v[26:27], v[12:13], s[50:51] op_sel_hi:[1,1,0]
	v_pk_fma_f32 v[12:13], v[26:27], v[12:13], s[56:57] op_sel_hi:[1,1,0]
	v_lshlrev_b32_e32 v32, 16, v52
	v_pk_mul_f32 v[12:13], v[26:27], v[12:13]
	v_and_b32_e32 v33, 0xffff0000, v52
	v_pk_mul_f32 v[12:13], v[14:15], v[12:13]
	v_max_f32_e32 v116, 0, v24
	v_fma_f32 v27, -|v24|, v12, v116
	v_max_f32_e32 v117, 0, v25
	v_fma_f32 v13, -|v25|, v13, v117
	v_pk_mul_f32 v[24:25], v[28:29], v[28:29]
	v_fma_f32 v34, |v32|, s40, 1.0
	v_fma_f32 v35, |v33|, s40, 1.0
	v_pk_fma_f32 v[14:15], v[30:31], s[42:43], v[18:19] op_sel_hi:[1,0,0]
	v_pk_mul_f32 v[24:25], v[24:25], s[64:65] op_sel_hi:[1,0]
	v_pk_fma_f32 v[14:15], v[30:31], v[14:15], s[48:49] op_sel_hi:[1,1,0]
	v_exp_f32_e32 v24, v24
	v_exp_f32_e32 v25, v25
	v_pk_fma_f32 v[14:15], v[30:31], v[14:15], s[50:51] op_sel_hi:[1,1,0]
	v_rcp_f32_e32 v34, v34
	v_pk_fma_f32 v[14:15], v[30:31], v[14:15], s[56:57] op_sel_hi:[1,1,0]
	v_rcp_f32_e32 v35, v35
	v_pk_mul_f32 v[14:15], v[30:31], v[14:15]
	v_pk_mul_f32 v[14:15], v[24:25], v[14:15]
	v_lshlrev_b32_e32 v36, 16, v53
	v_max_f32_e32 v80, 0, v28
	v_fma_f32 v31, -|v28|, v14, v80
	v_max_f32_e32 v81, 0, v29
	v_fma_f32 v15, -|v29|, v15, v81
	v_and_b32_e32 v37, 0xffff0000, v53
	v_pk_mul_f32 v[28:29], v[32:33], v[32:33]
	v_pk_fma_f32 v[24:25], v[34:35], s[42:43], v[18:19] op_sel_hi:[1,0,0]
	v_pk_mul_f32 v[28:29], v[28:29], s[64:65] op_sel_hi:[1,0]
	v_pk_fma_f32 v[24:25], v[34:35], v[24:25], s[48:49] op_sel_hi:[1,1,0]
	v_exp_f32_e32 v28, v28
	v_exp_f32_e32 v29, v29
	v_pk_fma_f32 v[24:25], v[34:35], v[24:25], s[50:51] op_sel_hi:[1,1,0]
	v_pk_fma_f32 v[24:25], v[34:35], v[24:25], s[56:57] op_sel_hi:[1,1,0]
	v_fma_f32 v38, |v36|, s40, 1.0
	v_fma_f32 v39, |v37|, s40, 1.0
	v_pk_mul_f32 v[24:25], v[34:35], v[24:25]
	v_rcp_f32_e32 v38, v38
	v_pk_mul_f32 v[24:25], v[28:29], v[24:25]
	v_rcp_f32_e32 v39, v39
	v_max_f32_e32 v82, 0, v32
	v_fma_f32 v35, -|v32|, v24, v82
	v_max_f32_e32 v83, 0, v33
	v_fma_f32 v25, -|v33|, v25, v83
	v_pk_fma_f32 v[18:19], v[38:39], s[42:43], v[18:19] op_sel_hi:[1,0,0]
	v_mul_f32_e32 v20, v21, v21
	v_pk_fma_f32 v[18:19], v[38:39], v[18:19], s[48:49] op_sel_hi:[1,1,0]
	v_mul_f32_e32 v10, v11, v11
	v_pk_mul_f32 v[28:29], v[36:37], v[36:37]
	v_pk_fma_f32 v[18:19], v[38:39], v[18:19], s[50:51] op_sel_hi:[1,1,0]
	v_pk_mul_f32 v[28:29], v[28:29], s[64:65] op_sel_hi:[1,0]
	v_pk_fma_f32 v[18:19], v[38:39], v[18:19], s[56:57] op_sel_hi:[1,1,0]
	v_exp_f32_e32 v28, v28
	v_exp_f32_e32 v29, v29
	v_pk_mul_f32 v[18:19], v[38:39], v[18:19]
	v_mul_f32_e32 v22, v23, v23
	v_mul_f32_e32 v6, v7, v7
	v_pk_mul_f32 v[18:19], v[28:29], v[18:19]
	v_pk_add_f32 v[4:5], v[4:5], v[8:9]
	v_pk_add_f32 v[8:9], v[20:21], v[10:11]
	v_mul_f32_e32 v26, v27, v27
	v_mul_f32_e32 v12, v13, v13
	v_max_f32_e32 v84, 0, v36
	v_fma_f32 v33, -|v36|, v18, v84
	v_max_f32_e32 v85, 0, v37
	v_fma_f32 v19, -|v37|, v19, v85
	v_pk_add_f32 v[4:5], v[8:9], v[4:5]
	v_pk_add_f32 v[6:7], v[22:23], v[6:7]
	v_mul_f32_e32 v30, v31, v31
	v_mul_f32_e32 v14, v15, v15
	v_pk_add_f32 v[4:5], v[6:7], v[4:5]
	v_pk_add_f32 v[6:7], v[26:27], v[12:13]
	v_mul_f32_e32 v34, v35, v35
	v_mul_f32_e32 v24, v25, v25
	v_pk_add_f32 v[4:5], v[6:7], v[4:5]
	v_pk_add_f32 v[6:7], v[30:31], v[14:15]
	v_mul_f32_e32 v32, v33, v33
	v_mul_f32_e32 v18, v19, v19
	v_pk_add_f32 v[4:5], v[6:7], v[4:5]
	v_pk_add_f32 v[6:7], v[34:35], v[24:25]
	s_nop 0
	v_pk_add_f32 v[4:5], v[6:7], v[4:5]
	v_pk_add_f32 v[6:7], v[32:33], v[18:19]
	s_nop 0
	v_pk_add_f32 v[4:5], v[6:7], v[4:5]
	ds_bpermute_b32 v7, v56, v5
	ds_bpermute_b32 v6, v56, v4
	s_waitcnt lgkmcnt(0)
	v_pk_add_f32 v[4:5], v[4:5], v[6:7]
	ds_bpermute_b32 v7, v57, v5
	ds_bpermute_b32 v6, v57, v4
	s_waitcnt lgkmcnt(0)
	v_pk_add_f32 v[4:5], v[4:5], v[6:7]
	ds_bpermute_b32 v7, v58, v5
	ds_bpermute_b32 v6, v58, v4
	s_waitcnt lgkmcnt(0)
	v_pk_add_f32 v[4:5], v[4:5], v[6:7]
	ds_bpermute_b32 v7, v59, v5
	ds_bpermute_b32 v6, v59, v4
	s_and_saveexec_b64 s[0:1], vcc
	s_cbranch_execz .LBB0_451
	s_waitcnt lgkmcnt(0)
	v_pk_add_f32 v[4:5], v[4:5], v[6:7]
	s_nop 0
	v_pk_mul_f32 v[4:5], v[4:5], s[66:67] op_sel_hi:[1,0]
	s_nop 0
	v_fma_f32 v4, -v5, v5, v4
	v_max_f32_e32 v4, 0, v4
	v_add_f32_e32 v4, 0x358637bd, v4
	v_mul_f32_e32 v6, 0x4b800000, v4
	v_cmp_gt_f32_e32 vcc, s36, v4
	s_nop 1
	v_cndmask_b32_e32 v4, v4, v6, vcc
	v_rsq_f32_e32 v4, v4
	v_lshl_add_u32 v6, v16, 2, 0
	v_add_u32_e32 v7, 0x11000, v6
	ds_write_b32 v7, v5
	v_mul_f32_e32 v5, 0x45800000, v4
	v_cndmask_b32_e32 v4, v4, v5, vcc
	v_add_u32_e32 v5, 0x11200, v6
	ds_write_b32 v5, v4

.LBB0_453:
	v_lshl_add_u64 v[4:5], s[12:13], 0, v[32:33]
	v_add_co_u32_e32 v18, vcc, 0x696e000, v4
	s_add_u32 s0, s16, s70
	s_nop 0
	v_addc_co_u32_e32 v19, vcc, 0, v5, vcc
	global_load_dwordx4 v[8:11], v[18:19], off
	global_load_dwordx4 v[4:7], v[18:19], off offset:2048
	s_addc_u32 s1, s38, s71
	s_add_u32 s4, s88, s70
	s_addc_u32 s5, s89, s71
	global_load_dwordx2 v[20:21], v2, s[0:1]
	global_load_dwordx2 v[22:23], v2, s[4:5]
	v_mov_b64_e32 v[16:17], s[44:45]
	ds_read_b64 v[14:15], v68
	ds_read_b64 v[12:13], v69
	s_waitcnt vmcnt(3)
	v_lshlrev_b32_e32 v24, 16, v8
	v_and_b32_e32 v25, 0xffff0000, v8
	s_waitcnt vmcnt(2)
	v_lshlrev_b32_e32 v34, 16, v4
	v_and_b32_e32 v35, 0xffff0000, v4
	v_fma_f32 v36, |v24|, s40, 1.0
	v_fma_f32 v37, |v25|, s40, 1.0
	v_fma_f32 v40, |v34|, s40, 1.0
	v_fma_f32 v41, |v35|, s40, 1.0
	v_rcp_f32_e32 v36, v36
	v_rcp_f32_e32 v37, v37
	v_rcp_f32_e32 v40, v40
	v_rcp_f32_e32 v41, v41
	v_pk_mul_f32 v[38:39], v[24:25], v[24:25]
	v_pk_mul_f32 v[42:43], v[34:35], v[34:35]
	v_pk_mul_f32 v[38:39], v[38:39], s[64:65] op_sel_hi:[1,0]
	v_pk_fma_f32 v[44:45], v[36:37], s[42:43], v[16:17] op_sel_hi:[1,0,0]
	v_pk_mul_f32 v[42:43], v[42:43], s[64:65] op_sel_hi:[1,0]
	v_exp_f32_e32 v38, v38
	v_exp_f32_e32 v39, v39
	v_pk_fma_f32 v[46:47], v[40:41], s[42:43], v[16:17] op_sel_hi:[1,0,0]
	v_pk_fma_f32 v[44:45], v[36:37], v[44:45], s[48:49] op_sel_hi:[1,1,0]
	v_exp_f32_e32 v42, v42
	v_exp_f32_e32 v43, v43
	v_pk_fma_f32 v[46:47], v[40:41], v[46:47], s[48:49] op_sel_hi:[1,1,0]
	v_pk_fma_f32 v[44:45], v[36:37], v[44:45], s[50:51] op_sel_hi:[1,1,0]
	v_pk_fma_f32 v[46:47], v[40:41], v[46:47], s[50:51] op_sel_hi:[1,1,0]
	v_pk_fma_f32 v[44:45], v[36:37], v[44:45], s[56:57] op_sel_hi:[1,1,0]
	v_pk_fma_f32 v[46:47], v[40:41], v[46:47], s[56:57] op_sel_hi:[1,1,0]
	v_pk_mul_f32 v[36:37], v[36:37], v[44:45]
	v_pk_mul_f32 v[40:41], v[40:41], v[46:47]
	v_pk_mul_f32 v[36:37], v[38:39], v[36:37]
	v_pk_mul_f32 v[38:39], v[42:43], v[40:41]
	v_max_f32_e32 v86, 0, v24
	v_fma_f32 v3, -|v24|, v36, v86
	v_max_f32_e32 v90, 0, v25
	v_fma_f32 v4, -|v25|, v37, v90
	v_max_f32_e32 v91, 0, v34
	v_fma_f32 v8, -|v34|, v38, v91
	v_max_f32_e32 v92, 0, v35
	v_fma_f32 v24, -|v35|, v39, v92
	s_waitcnt lgkmcnt(1)
	v_sub_f32_e32 v3, v3, v14
	s_waitcnt lgkmcnt(0)
	v_mul_f32_e32 v3, v12, v3
	v_sub_f32_e32 v4, v4, v14
	v_mul_f32_e32 v4, v12, v4
	v_sub_f32_e32 v8, v8, v15
	v_mul_f32_e32 v8, v13, v8
	v_sub_f32_e32 v24, v24, v15
	v_mul_f32_e32 v24, v13, v24
	s_waitcnt vmcnt(0)
	v_fma_f32 v3, v20, v3, v22
	v_fma_f32 v4, v21, v4, v23
	v_fma_f32 v8, v20, v8, v22
	v_fmac_f32_e32 v23, v21, v24
	v_cvt_pk_bf16_f32 v3, v3, v8
	ds_write_b32 v70, v3
	v_cvt_pk_bf16_f32 v3, v4, v23
	global_load_dwordx2 v[22:23], v2, s[0:1] offset:8
	global_load_dwordx2 v[20:21], v2, s[4:5] offset:8
	v_lshlrev_b32_e32 v8, 16, v9
	v_and_b32_e32 v9, 0xffff0000, v9
	v_lshlrev_b32_e32 v4, 16, v5
	v_and_b32_e32 v5, 0xffff0000, v5
	v_fma_f32 v24, |v8|, s40, 1.0
	v_fma_f32 v25, |v9|, s40, 1.0
	v_fma_f32 v36, |v4|, s40, 1.0
	v_fma_f32 v37, |v5|, s40, 1.0
	v_rcp_f32_e32 v24, v24
	v_rcp_f32_e32 v25, v25
	v_rcp_f32_e32 v36, v36
	v_rcp_f32_e32 v37, v37
	v_pk_mul_f32 v[34:35], v[8:9], v[8:9]
	v_pk_mul_f32 v[38:39], v[4:5], v[4:5]
	v_pk_mul_f32 v[34:35], v[34:35], s[64:65] op_sel_hi:[1,0]
	v_pk_fma_f32 v[40:41], v[24:25], s[42:43], v[16:17] op_sel_hi:[1,0,0]
	v_pk_mul_f32 v[38:39], v[38:39], s[64:65] op_sel_hi:[1,0]
	v_exp_f32_e32 v34, v34
	v_exp_f32_e32 v35, v35
	v_pk_fma_f32 v[42:43], v[36:37], s[42:43], v[16:17] op_sel_hi:[1,0,0]
	v_pk_fma_f32 v[40:41], v[24:25], v[40:41], s[48:49] op_sel_hi:[1,1,0]
	v_exp_f32_e32 v38, v38
	v_exp_f32_e32 v39, v39
	v_pk_fma_f32 v[42:43], v[36:37], v[42:43], s[48:49] op_sel_hi:[1,1,0]
	v_pk_fma_f32 v[40:41], v[24:25], v[40:41], s[50:51] op_sel_hi:[1,1,0]
	v_pk_fma_f32 v[42:43], v[36:37], v[42:43], s[50:51] op_sel_hi:[1,1,0]
	v_pk_fma_f32 v[40:41], v[24:25], v[40:41], s[56:57] op_sel_hi:[1,1,0]
	v_pk_fma_f32 v[42:43], v[36:37], v[42:43], s[56:57] op_sel_hi:[1,1,0]
	v_pk_mul_f32 v[24:25], v[24:25], v[40:41]
	v_pk_mul_f32 v[36:37], v[36:37], v[42:43]
	v_pk_mul_f32 v[24:25], v[34:35], v[24:25]
	v_pk_mul_f32 v[34:35], v[38:39], v[36:37]
	v_max_f32_e32 v93, 0, v8
	v_fma_f32 v8, -|v8|, v24, v93
	v_max_f32_e32 v94, 0, v9
	v_fma_f32 v9, -|v9|, v25, v94
	v_max_f32_e32 v95, 0, v4
	v_fma_f32 v4, -|v4|, v34, v95
	v_max_f32_e32 v96, 0, v5
	v_fma_f32 v5, -|v5|, v35, v96
	v_sub_f32_e32 v8, v8, v14
	v_mul_f32_e32 v8, v12, v8
	v_sub_f32_e32 v9, v9, v14
	v_mul_f32_e32 v9, v12, v9
	v_sub_f32_e32 v4, v4, v15
	v_mul_f32_e32 v4, v13, v4
	v_sub_f32_e32 v5, v5, v15
	ds_write_b32 v70, v3 offset:272
	v_mul_f32_e32 v5, v13, v5
	s_waitcnt vmcnt(0)
	v_fma_f32 v3, v22, v8, v20
	v_fma_f32 v8, v23, v9, v21
	v_fma_f32 v4, v22, v4, v20
	v_cvt_pk_bf16_f32 v3, v3, v4
	v_fmac_f32_e32 v21, v23, v5
	ds_write_b32 v70, v3 offset:544
	v_cvt_pk_bf16_f32 v3, v8, v21
	global_load_dwordx2 v[8:9], v2, s[0:1] offset:16
	global_load_dwordx2 v[4:5], v2, s[4:5] offset:16
	v_lshlrev_b32_e32 v20, 16, v10
	v_and_b32_e32 v21, 0xffff0000, v10
	v_lshlrev_b32_e32 v22, 16, v6
	v_and_b32_e32 v23, 0xffff0000, v6
	v_fma_f32 v24, |v20|, s40, 1.0
	v_fma_f32 v25, |v21|, s40, 1.0
	v_fma_f32 v36, |v22|, s40, 1.0
	v_fma_f32 v37, |v23|, s40, 1.0
	v_rcp_f32_e32 v24, v24
	v_rcp_f32_e32 v25, v25
	v_rcp_f32_e32 v36, v36
	v_rcp_f32_e32 v37, v37
	v_pk_mul_f32 v[34:35], v[20:21], v[20:21]
	v_pk_mul_f32 v[38:39], v[22:23], v[22:23]
	v_pk_mul_f32 v[34:35], v[34:35], s[64:65] op_sel_hi:[1,0]
	v_pk_fma_f32 v[40:41], v[24:25], s[42:43], v[16:17] op_sel_hi:[1,0,0]
	v_pk_mul_f32 v[38:39], v[38:39], s[64:65] op_sel_hi:[1,0]
	v_exp_f32_e32 v34, v34
	v_exp_f32_e32 v35, v35
	v_pk_fma_f32 v[42:43], v[36:37], s[42:43], v[16:17] op_sel_hi:[1,0,0]
	v_pk_fma_f32 v[40:41], v[24:25], v[40:41], s[48:49] op_sel_hi:[1,1,0]
	v_exp_f32_e32 v38, v38
	v_exp_f32_e32 v39, v39
	v_pk_fma_f32 v[42:43], v[36:37], v[42:43], s[48:49] op_sel_hi:[1,1,0]
	v_pk_fma_f32 v[40:41], v[24:25], v[40:41], s[50:51] op_sel_hi:[1,1,0]
	v_pk_fma_f32 v[42:43], v[36:37], v[42:43], s[50:51] op_sel_hi:[1,1,0]
	v_pk_fma_f32 v[40:41], v[24:25], v[40:41], s[56:57] op_sel_hi:[1,1,0]
	v_pk_fma_f32 v[42:43], v[36:37], v[42:43], s[56:57] op_sel_hi:[1,1,0]
	v_pk_mul_f32 v[24:25], v[24:25], v[40:41]
	v_pk_mul_f32 v[36:37], v[36:37], v[42:43]
	v_pk_mul_f32 v[24:25], v[34:35], v[24:25]
	v_pk_mul_f32 v[34:35], v[38:39], v[36:37]
	v_max_f32_e32 v97, 0, v20
	v_fma_f32 v6, -|v20|, v24, v97
	v_max_f32_e32 v98, 0, v21
	v_fma_f32 v10, -|v21|, v25, v98
	v_max_f32_e32 v99, 0, v22
	v_fma_f32 v20, -|v22|, v34, v99
	v_max_f32_e32 v100, 0, v23
	v_fma_f32 v21, -|v23|, v35, v100
	v_sub_f32_e32 v6, v6, v14
	v_mul_f32_e32 v6, v12, v6
	v_sub_f32_e32 v10, v10, v14
	v_mul_f32_e32 v10, v12, v10
	v_sub_f32_e32 v20, v20, v15
	v_mul_f32_e32 v20, v13, v20
	v_sub_f32_e32 v21, v21, v15
	v_mul_f32_e32 v21, v13, v21
	ds_write_b32 v70, v3 offset:816
	s_waitcnt vmcnt(0)
	v_fma_f32 v3, v8, v6, v4
	v_fma_f32 v6, v9, v10, v5
	v_fma_f32 v4, v8, v20, v4
	v_fmac_f32_e32 v5, v9, v21
	v_cvt_pk_bf16_f32 v3, v3, v4
	ds_write_b32 v70, v3 offset:1088
	v_cvt_pk_bf16_f32 v3, v6, v5
	global_load_dwordx2 v[8:9], v2, s[0:1] offset:24
	global_load_dwordx2 v[4:5], v2, s[4:5] offset:24
	v_lshlrev_b32_e32 v10, 16, v11
	v_and_b32_e32 v11, 0xffff0000, v11
	v_lshlrev_b32_e32 v6, 16, v7
	v_and_b32_e32 v7, 0xffff0000, v7
	v_fma_f32 v20, |v10|, s40, 1.0
	v_fma_f32 v21, |v11|, s40, 1.0
	v_fma_f32 v24, |v6|, s40, 1.0
	v_fma_f32 v25, |v7|, s40, 1.0
	v_rcp_f32_e32 v20, v20
	v_rcp_f32_e32 v21, v21
	v_rcp_f32_e32 v24, v24
	v_rcp_f32_e32 v25, v25
	v_pk_mul_f32 v[22:23], v[10:11], v[10:11]
	v_pk_mul_f32 v[34:35], v[6:7], v[6:7]
	v_pk_mul_f32 v[22:23], v[22:23], s[64:65] op_sel_hi:[1,0]
	v_pk_fma_f32 v[36:37], v[20:21], s[42:43], v[16:17] op_sel_hi:[1,0,0]
	v_pk_mul_f32 v[34:35], v[34:35], s[64:65] op_sel_hi:[1,0]
	v_exp_f32_e32 v22, v22
	v_exp_f32_e32 v23, v23
	v_pk_fma_f32 v[38:39], v[24:25], s[42:43], v[16:17] op_sel_hi:[1,0,0]
	v_pk_fma_f32 v[36:37], v[20:21], v[36:37], s[48:49] op_sel_hi:[1,1,0]
	v_exp_f32_e32 v34, v34
	v_exp_f32_e32 v35, v35
	v_pk_fma_f32 v[38:39], v[24:25], v[38:39], s[48:49] op_sel_hi:[1,1,0]
	v_pk_fma_f32 v[36:37], v[20:21], v[36:37], s[50:51] op_sel_hi:[1,1,0]
	v_pk_fma_f32 v[38:39], v[24:25], v[38:39], s[50:51] op_sel_hi:[1,1,0]
	v_pk_fma_f32 v[36:37], v[20:21], v[36:37], s[56:57] op_sel_hi:[1,1,0]
	v_pk_fma_f32 v[38:39], v[24:25], v[38:39], s[56:57] op_sel_hi:[1,1,0]
	v_pk_mul_f32 v[20:21], v[20:21], v[36:37]
	v_pk_mul_f32 v[24:25], v[24:25], v[38:39]
	v_pk_mul_f32 v[20:21], v[22:23], v[20:21]
	v_pk_mul_f32 v[22:23], v[34:35], v[24:25]
	v_max_f32_e32 v104, 0, v10
	v_fma_f32 v10, -|v10|, v20, v104
	v_max_f32_e32 v105, 0, v11
	v_fma_f32 v11, -|v11|, v21, v105
	v_max_f32_e32 v106, 0, v6
	v_fma_f32 v6, -|v6|, v22, v106
	v_max_f32_e32 v107, 0, v7
	v_fma_f32 v7, -|v7|, v23, v107
	v_sub_f32_e32 v10, v10, v14
	v_mul_f32_e32 v10, v12, v10
	v_sub_f32_e32 v11, v11, v14
	v_mul_f32_e32 v11, v12, v11
	v_sub_f32_e32 v6, v6, v15
	v_mul_f32_e32 v6, v13, v6
	v_sub_f32_e32 v7, v7, v15
	v_mul_f32_e32 v7, v13, v7
	ds_write_b32 v70, v3 offset:1360
	s_waitcnt vmcnt(0)
	v_fma_f32 v3, v8, v10, v4
	v_fma_f32 v10, v9, v11, v5
	v_fma_f32 v4, v8, v6, v4
	v_fmac_f32_e32 v5, v9, v7
	v_cvt_pk_bf16_f32 v3, v3, v4
	ds_write_b32 v70, v3 offset:1632
	v_cvt_pk_bf16_f32 v3, v10, v5
	global_load_dwordx4 v[8:11], v[18:19], off offset:16
	global_load_dwordx4 v[4:7], v[18:19], off offset:2064
	global_load_dwordx2 v[22:23], v2, s[0:1] offset:32
	global_load_dwordx2 v[20:21], v2, s[4:5] offset:32
	ds_write_b32 v70, v3 offset:1904
	s_waitcnt vmcnt(3)
	v_lshlrev_b32_e32 v24, 16, v8
	v_and_b32_e32 v25, 0xffff0000, v8
	s_waitcnt vmcnt(2)
	v_lshlrev_b32_e32 v34, 16, v4
	v_and_b32_e32 v35, 0xffff0000, v4
	v_fma_f32 v36, |v24|, s40, 1.0
	v_fma_f32 v37, |v25|, s40, 1.0
	v_fma_f32 v40, |v34|, s40, 1.0
	v_fma_f32 v41, |v35|, s40, 1.0
	v_rcp_f32_e32 v36, v36
	v_rcp_f32_e32 v37, v37
	v_rcp_f32_e32 v40, v40
	v_rcp_f32_e32 v41, v41
	v_pk_mul_f32 v[38:39], v[24:25], v[24:25]
	v_pk_mul_f32 v[42:43], v[34:35], v[34:35]
	v_pk_mul_f32 v[38:39], v[38:39], s[64:65] op_sel_hi:[1,0]
	v_pk_fma_f32 v[44:45], v[36:37], s[42:43], v[16:17] op_sel_hi:[1,0,0]
	v_pk_mul_f32 v[42:43], v[42:43], s[64:65] op_sel_hi:[1,0]
	v_exp_f32_e32 v38, v38
	v_exp_f32_e32 v39, v39
	v_pk_fma_f32 v[46:47], v[40:41], s[42:43], v[16:17] op_sel_hi:[1,0,0]
	v_pk_fma_f32 v[44:45], v[36:37], v[44:45], s[48:49] op_sel_hi:[1,1,0]
	v_exp_f32_e32 v42, v42
	v_exp_f32_e32 v43, v43
	v_pk_fma_f32 v[46:47], v[40:41], v[46:47], s[48:49] op_sel_hi:[1,1,0]
	v_pk_fma_f32 v[44:45], v[36:37], v[44:45], s[50:51] op_sel_hi:[1,1,0]
	v_pk_fma_f32 v[46:47], v[40:41], v[46:47], s[50:51] op_sel_hi:[1,1,0]
	v_pk_fma_f32 v[44:45], v[36:37], v[44:45], s[56:57] op_sel_hi:[1,1,0]
	v_pk_fma_f32 v[46:47], v[40:41], v[46:47], s[56:57] op_sel_hi:[1,1,0]
	v_pk_mul_f32 v[36:37], v[36:37], v[44:45]
	v_pk_mul_f32 v[40:41], v[40:41], v[46:47]
	v_pk_mul_f32 v[36:37], v[38:39], v[36:37]
	v_pk_mul_f32 v[38:39], v[42:43], v[40:41]
	v_max_f32_e32 v108, 0, v24
	v_fma_f32 v3, -|v24|, v36, v108
	v_max_f32_e32 v109, 0, v25
	v_fma_f32 v4, -|v25|, v37, v109
	v_max_f32_e32 v110, 0, v34
	v_fma_f32 v8, -|v34|, v38, v110
	v_max_f32_e32 v111, 0, v35
	v_fma_f32 v24, -|v35|, v39, v111
	v_sub_f32_e32 v3, v3, v14
	v_mul_f32_e32 v3, v12, v3
	v_sub_f32_e32 v4, v4, v14
	v_mul_f32_e32 v4, v12, v4
	v_sub_f32_e32 v8, v8, v15
	v_mul_f32_e32 v8, v13, v8
	v_sub_f32_e32 v24, v24, v15
	v_mul_f32_e32 v24, v13, v24
	s_waitcnt vmcnt(0)
	v_fma_f32 v3, v22, v3, v20
	v_fma_f32 v4, v23, v4, v21
	v_fma_f32 v8, v22, v8, v20
	v_fmac_f32_e32 v21, v23, v24
	v_cvt_pk_bf16_f32 v3, v3, v8
	ds_write_b32 v70, v3 offset:2176
	v_cvt_pk_bf16_f32 v3, v4, v21
	global_load_dwordx2 v[22:23], v2, s[0:1] offset:40
	global_load_dwordx2 v[20:21], v2, s[4:5] offset:40
	v_lshlrev_b32_e32 v8, 16, v9
	v_and_b32_e32 v9, 0xffff0000, v9
	v_lshlrev_b32_e32 v4, 16, v5
	v_and_b32_e32 v5, 0xffff0000, v5
	v_fma_f32 v24, |v8|, s40, 1.0
	v_fma_f32 v25, |v9|, s40, 1.0
	v_fma_f32 v36, |v4|, s40, 1.0
	v_fma_f32 v37, |v5|, s40, 1.0
	v_rcp_f32_e32 v24, v24
	v_rcp_f32_e32 v25, v25
	v_rcp_f32_e32 v36, v36
	v_rcp_f32_e32 v37, v37
	v_pk_mul_f32 v[34:35], v[8:9], v[8:9]
	v_pk_mul_f32 v[38:39], v[4:5], v[4:5]
	v_pk_mul_f32 v[34:35], v[34:35], s[64:65] op_sel_hi:[1,0]
	v_pk_fma_f32 v[40:41], v[24:25], s[42:43], v[16:17] op_sel_hi:[1,0,0]
	v_pk_mul_f32 v[38:39], v[38:39], s[64:65] op_sel_hi:[1,0]
	v_exp_f32_e32 v34, v34
	v_exp_f32_e32 v35, v35
	v_pk_fma_f32 v[42:43], v[36:37], s[42:43], v[16:17] op_sel_hi:[1,0,0]
	v_pk_fma_f32 v[40:41], v[24:25], v[40:41], s[48:49] op_sel_hi:[1,1,0]
	v_exp_f32_e32 v38, v38
	v_exp_f32_e32 v39, v39
	v_pk_fma_f32 v[42:43], v[36:37], v[42:43], s[48:49] op_sel_hi:[1,1,0]
	v_pk_fma_f32 v[40:41], v[24:25], v[40:41], s[50:51] op_sel_hi:[1,1,0]
	v_pk_fma_f32 v[42:43], v[36:37], v[42:43], s[50:51] op_sel_hi:[1,1,0]
	v_pk_fma_f32 v[40:41], v[24:25], v[40:41], s[56:57] op_sel_hi:[1,1,0]
	v_pk_fma_f32 v[42:43], v[36:37], v[42:43], s[56:57] op_sel_hi:[1,1,0]
	v_pk_mul_f32 v[24:25], v[24:25], v[40:41]
	v_pk_mul_f32 v[36:37], v[36:37], v[42:43]
	v_pk_mul_f32 v[24:25], v[34:35], v[24:25]
	v_pk_mul_f32 v[34:35], v[38:39], v[36:37]
	v_max_f32_e32 v112, 0, v8
	v_fma_f32 v8, -|v8|, v24, v112
	v_max_f32_e32 v113, 0, v9
	v_fma_f32 v9, -|v9|, v25, v113
	v_max_f32_e32 v114, 0, v4
	v_fma_f32 v4, -|v4|, v34, v114
	v_max_f32_e32 v115, 0, v5
	v_fma_f32 v5, -|v5|, v35, v115
	v_sub_f32_e32 v8, v8, v14
	v_mul_f32_e32 v8, v12, v8
	v_sub_f32_e32 v9, v9, v14
	v_mul_f32_e32 v9, v12, v9
	v_sub_f32_e32 v4, v4, v15
	v_mul_f32_e32 v4, v13, v4
	v_sub_f32_e32 v5, v5, v15
	ds_write_b32 v70, v3 offset:2448
	v_mul_f32_e32 v5, v13, v5
	s_waitcnt vmcnt(0)
	v_fma_f32 v3, v22, v8, v20
	v_fma_f32 v8, v23, v9, v21
	v_fma_f32 v4, v22, v4, v20
	v_cvt_pk_bf16_f32 v3, v3, v4
	v_fmac_f32_e32 v21, v23, v5
	ds_write_b32 v70, v3 offset:2720
	v_cvt_pk_bf16_f32 v3, v8, v21
	global_load_dwordx2 v[8:9], v2, s[0:1] offset:48
	global_load_dwordx2 v[4:5], v2, s[4:5] offset:48
	v_lshlrev_b32_e32 v20, 16, v10
	v_and_b32_e32 v21, 0xffff0000, v10
	v_lshlrev_b32_e32 v22, 16, v6
	v_and_b32_e32 v23, 0xffff0000, v6
	v_fma_f32 v24, |v20|, s40, 1.0
	v_fma_f32 v25, |v21|, s40, 1.0
	v_fma_f32 v36, |v22|, s40, 1.0
	v_fma_f32 v37, |v23|, s40, 1.0
	v_rcp_f32_e32 v24, v24
	v_rcp_f32_e32 v25, v25
	v_rcp_f32_e32 v36, v36
	v_rcp_f32_e32 v37, v37
	v_pk_mul_f32 v[34:35], v[20:21], v[20:21]
	v_pk_mul_f32 v[38:39], v[22:23], v[22:23]
	v_pk_mul_f32 v[34:35], v[34:35], s[64:65] op_sel_hi:[1,0]
	v_pk_fma_f32 v[40:41], v[24:25], s[42:43], v[16:17] op_sel_hi:[1,0,0]
	v_pk_mul_f32 v[38:39], v[38:39], s[64:65] op_sel_hi:[1,0]
	v_exp_f32_e32 v34, v34
	v_exp_f32_e32 v35, v35
	v_pk_fma_f32 v[42:43], v[36:37], s[42:43], v[16:17] op_sel_hi:[1,0,0]
	v_pk_fma_f32 v[40:41], v[24:25], v[40:41], s[48:49] op_sel_hi:[1,1,0]
	v_exp_f32_e32 v38, v38
	v_exp_f32_e32 v39, v39
	v_pk_fma_f32 v[42:43], v[36:37], v[42:43], s[48:49] op_sel_hi:[1,1,0]
	v_pk_fma_f32 v[40:41], v[24:25], v[40:41], s[50:51] op_sel_hi:[1,1,0]
	v_pk_fma_f32 v[42:43], v[36:37], v[42:43], s[50:51] op_sel_hi:[1,1,0]
	v_pk_fma_f32 v[40:41], v[24:25], v[40:41], s[56:57] op_sel_hi:[1,1,0]
	v_pk_fma_f32 v[42:43], v[36:37], v[42:43], s[56:57] op_sel_hi:[1,1,0]
	v_pk_mul_f32 v[24:25], v[24:25], v[40:41]
	v_pk_mul_f32 v[36:37], v[36:37], v[42:43]
	v_pk_mul_f32 v[24:25], v[34:35], v[24:25]
	v_pk_mul_f32 v[34:35], v[38:39], v[36:37]
	v_max_f32_e32 v116, 0, v20
	v_fma_f32 v6, -|v20|, v24, v116
	v_max_f32_e32 v117, 0, v21
	v_fma_f32 v10, -|v21|, v25, v117
	v_max_f32_e32 v80, 0, v22
	v_fma_f32 v20, -|v22|, v34, v80
	v_max_f32_e32 v81, 0, v23
	v_fma_f32 v21, -|v23|, v35, v81
	v_sub_f32_e32 v6, v6, v14
	v_mul_f32_e32 v6, v12, v6
	v_sub_f32_e32 v10, v10, v14
	v_mul_f32_e32 v10, v12, v10
	v_sub_f32_e32 v20, v20, v15
	v_mul_f32_e32 v20, v13, v20
	v_sub_f32_e32 v21, v21, v15
	v_mul_f32_e32 v21, v13, v21
	ds_write_b32 v70, v3 offset:2992
	s_waitcnt vmcnt(0)
	v_fma_f32 v3, v8, v6, v4
	v_fma_f32 v6, v9, v10, v5
	v_fma_f32 v4, v8, v20, v4
	v_fmac_f32_e32 v5, v9, v21
	v_cvt_pk_bf16_f32 v3, v3, v4
	ds_write_b32 v70, v3 offset:3264
	v_cvt_pk_bf16_f32 v3, v6, v5
	global_load_dwordx2 v[8:9], v2, s[0:1] offset:56
	global_load_dwordx2 v[4:5], v2, s[4:5] offset:56
	v_lshlrev_b32_e32 v10, 16, v11
	v_and_b32_e32 v11, 0xffff0000, v11
	v_lshlrev_b32_e32 v6, 16, v7
	v_and_b32_e32 v7, 0xffff0000, v7
	v_fma_f32 v20, |v10|, s40, 1.0
	v_fma_f32 v21, |v11|, s40, 1.0
	v_fma_f32 v24, |v6|, s40, 1.0
	v_fma_f32 v25, |v7|, s40, 1.0
	v_rcp_f32_e32 v20, v20
	v_rcp_f32_e32 v21, v21
	v_rcp_f32_e32 v24, v24
	v_rcp_f32_e32 v25, v25
	v_pk_mul_f32 v[22:23], v[10:11], v[10:11]
	v_pk_mul_f32 v[34:35], v[6:7], v[6:7]
	v_pk_mul_f32 v[22:23], v[22:23], s[64:65] op_sel_hi:[1,0]
	v_pk_fma_f32 v[36:37], v[20:21], s[42:43], v[16:17] op_sel_hi:[1,0,0]
	v_pk_mul_f32 v[34:35], v[34:35], s[64:65] op_sel_hi:[1,0]
	v_exp_f32_e32 v22, v22
	v_exp_f32_e32 v23, v23
	v_pk_fma_f32 v[38:39], v[24:25], s[42:43], v[16:17] op_sel_hi:[1,0,0]
	v_pk_fma_f32 v[36:37], v[20:21], v[36:37], s[48:49] op_sel_hi:[1,1,0]
	v_exp_f32_e32 v34, v34
	v_exp_f32_e32 v35, v35
	v_pk_fma_f32 v[38:39], v[24:25], v[38:39], s[48:49] op_sel_hi:[1,1,0]
	v_pk_fma_f32 v[36:37], v[20:21], v[36:37], s[50:51] op_sel_hi:[1,1,0]
	v_pk_fma_f32 v[38:39], v[24:25], v[38:39], s[50:51] op_sel_hi:[1,1,0]
	v_pk_fma_f32 v[36:37], v[20:21], v[36:37], s[56:57] op_sel_hi:[1,1,0]
	v_pk_fma_f32 v[38:39], v[24:25], v[38:39], s[56:57] op_sel_hi:[1,1,0]
	v_pk_mul_f32 v[20:21], v[20:21], v[36:37]
	v_pk_mul_f32 v[24:25], v[24:25], v[38:39]
	v_pk_mul_f32 v[20:21], v[22:23], v[20:21]
	v_pk_mul_f32 v[22:23], v[34:35], v[24:25]
	v_max_f32_e32 v82, 0, v10
	v_fma_f32 v10, -|v10|, v20, v82
	v_max_f32_e32 v83, 0, v11
	v_fma_f32 v11, -|v11|, v21, v83
	v_max_f32_e32 v84, 0, v6
	v_fma_f32 v6, -|v6|, v22, v84
	v_max_f32_e32 v85, 0, v7
	v_fma_f32 v7, -|v7|, v23, v85
	v_sub_f32_e32 v10, v10, v14
	v_mul_f32_e32 v10, v12, v10
	v_sub_f32_e32 v11, v11, v14
	v_mul_f32_e32 v11, v12, v11
	v_sub_f32_e32 v6, v6, v15
	v_mul_f32_e32 v6, v13, v6
	v_sub_f32_e32 v7, v7, v15
	v_mul_f32_e32 v7, v13, v7
	ds_write_b32 v70, v3 offset:3536
	s_waitcnt vmcnt(0)
	v_fma_f32 v3, v8, v10, v4
	v_fma_f32 v10, v9, v11, v5
	v_fma_f32 v4, v8, v6, v4
	v_fmac_f32_e32 v5, v9, v7
	v_cvt_pk_bf16_f32 v3, v3, v4
	ds_write_b32 v70, v3 offset:3808
	v_cvt_pk_bf16_f32 v3, v10, v5
	global_load_dwordx4 v[8:11], v[18:19], off offset:32
	global_load_dwordx4 v[4:7], v[18:19], off offset:2080
	global_load_dwordx2 v[22:23], v2, s[0:1] offset:64
	global_load_dwordx2 v[20:21], v2, s[4:5] offset:64
	ds_write_b32 v70, v3 offset:4080
	s_waitcnt vmcnt(3)
	v_lshlrev_b32_e32 v24, 16, v8
	v_and_b32_e32 v25, 0xffff0000, v8
	s_waitcnt vmcnt(2)
	v_lshlrev_b32_e32 v34, 16, v4
	v_and_b32_e32 v35, 0xffff0000, v4
	v_fma_f32 v36, |v24|, s40, 1.0
	v_fma_f32 v37, |v25|, s40, 1.0
	v_fma_f32 v40, |v34|, s40, 1.0
	v_fma_f32 v41, |v35|, s40, 1.0
	v_rcp_f32_e32 v36, v36
	v_rcp_f32_e32 v37, v37
	v_rcp_f32_e32 v40, v40
	v_rcp_f32_e32 v41, v41
	v_pk_mul_f32 v[38:39], v[24:25], v[24:25]
	v_pk_mul_f32 v[42:43], v[34:35], v[34:35]
	v_pk_mul_f32 v[38:39], v[38:39], s[64:65] op_sel_hi:[1,0]
	v_pk_fma_f32 v[44:45], v[36:37], s[42:43], v[16:17] op_sel_hi:[1,0,0]
	v_pk_mul_f32 v[42:43], v[42:43], s[64:65] op_sel_hi:[1,0]
	v_exp_f32_e32 v38, v38
	v_exp_f32_e32 v39, v39
	v_pk_fma_f32 v[46:47], v[40:41], s[42:43], v[16:17] op_sel_hi:[1,0,0]
	v_pk_fma_f32 v[44:45], v[36:37], v[44:45], s[48:49] op_sel_hi:[1,1,0]
	v_exp_f32_e32 v42, v42
	v_exp_f32_e32 v43, v43
	v_pk_fma_f32 v[46:47], v[40:41], v[46:47], s[48:49] op_sel_hi:[1,1,0]
	v_pk_fma_f32 v[44:45], v[36:37], v[44:45], s[50:51] op_sel_hi:[1,1,0]
	v_pk_fma_f32 v[46:47], v[40:41], v[46:47], s[50:51] op_sel_hi:[1,1,0]
	v_pk_fma_f32 v[44:45], v[36:37], v[44:45], s[56:57] op_sel_hi:[1,1,0]
	v_pk_fma_f32 v[46:47], v[40:41], v[46:47], s[56:57] op_sel_hi:[1,1,0]
	v_pk_mul_f32 v[36:37], v[36:37], v[44:45]
	v_pk_mul_f32 v[40:41], v[40:41], v[46:47]
	v_pk_mul_f32 v[36:37], v[38:39], v[36:37]
	v_pk_mul_f32 v[38:39], v[42:43], v[40:41]
	v_max_f32_e32 v86, 0, v24
	v_fma_f32 v3, -|v24|, v36, v86
	v_max_f32_e32 v90, 0, v25
	v_fma_f32 v4, -|v25|, v37, v90
	v_max_f32_e32 v91, 0, v34
	v_fma_f32 v8, -|v34|, v38, v91
	v_max_f32_e32 v92, 0, v35
	v_fma_f32 v24, -|v35|, v39, v92
	v_sub_f32_e32 v3, v3, v14
	v_mul_f32_e32 v3, v12, v3
	v_sub_f32_e32 v4, v4, v14
	v_mul_f32_e32 v4, v12, v4
	v_sub_f32_e32 v8, v8, v15
	v_mul_f32_e32 v8, v13, v8
	v_sub_f32_e32 v24, v24, v15
	v_mul_f32_e32 v24, v13, v24
	s_waitcnt vmcnt(0)
	v_fma_f32 v3, v22, v3, v20
	v_fma_f32 v4, v23, v4, v21
	v_fma_f32 v8, v22, v8, v20
	v_fmac_f32_e32 v21, v23, v24
	v_cvt_pk_bf16_f32 v3, v3, v8
	ds_write_b32 v70, v3 offset:4352
	v_cvt_pk_bf16_f32 v3, v4, v21
	global_load_dwordx2 v[22:23], v2, s[0:1] offset:72
	global_load_dwordx2 v[20:21], v2, s[4:5] offset:72
	v_lshlrev_b32_e32 v8, 16, v9
	v_and_b32_e32 v9, 0xffff0000, v9
	v_lshlrev_b32_e32 v4, 16, v5
	v_and_b32_e32 v5, 0xffff0000, v5
	v_fma_f32 v24, |v8|, s40, 1.0
	v_fma_f32 v25, |v9|, s40, 1.0
	v_fma_f32 v36, |v4|, s40, 1.0
	v_fma_f32 v37, |v5|, s40, 1.0
	v_rcp_f32_e32 v24, v24
	v_rcp_f32_e32 v25, v25
	v_rcp_f32_e32 v36, v36
	v_rcp_f32_e32 v37, v37
	v_pk_mul_f32 v[34:35], v[8:9], v[8:9]
	v_pk_mul_f32 v[38:39], v[4:5], v[4:5]
	v_pk_mul_f32 v[34:35], v[34:35], s[64:65] op_sel_hi:[1,0]
	v_pk_fma_f32 v[40:41], v[24:25], s[42:43], v[16:17] op_sel_hi:[1,0,0]
	v_pk_mul_f32 v[38:39], v[38:39], s[64:65] op_sel_hi:[1,0]
	v_exp_f32_e32 v34, v34
	v_exp_f32_e32 v35, v35
	v_pk_fma_f32 v[42:43], v[36:37], s[42:43], v[16:17] op_sel_hi:[1,0,0]
	v_pk_fma_f32 v[40:41], v[24:25], v[40:41], s[48:49] op_sel_hi:[1,1,0]
	v_exp_f32_e32 v38, v38
	v_exp_f32_e32 v39, v39
	v_pk_fma_f32 v[42:43], v[36:37], v[42:43], s[48:49] op_sel_hi:[1,1,0]
	v_pk_fma_f32 v[40:41], v[24:25], v[40:41], s[50:51] op_sel_hi:[1,1,0]
	v_pk_fma_f32 v[42:43], v[36:37], v[42:43], s[50:51] op_sel_hi:[1,1,0]
	v_pk_fma_f32 v[40:41], v[24:25], v[40:41], s[56:57] op_sel_hi:[1,1,0]
	v_pk_fma_f32 v[42:43], v[36:37], v[42:43], s[56:57] op_sel_hi:[1,1,0]
	v_pk_mul_f32 v[24:25], v[24:25], v[40:41]
	v_pk_mul_f32 v[36:37], v[36:37], v[42:43]
	v_pk_mul_f32 v[24:25], v[34:35], v[24:25]
	v_pk_mul_f32 v[34:35], v[38:39], v[36:37]
	v_max_f32_e32 v93, 0, v8
	v_fma_f32 v8, -|v8|, v24, v93
	v_max_f32_e32 v94, 0, v9
	v_fma_f32 v9, -|v9|, v25, v94
	v_max_f32_e32 v95, 0, v4
	v_fma_f32 v4, -|v4|, v34, v95
	v_max_f32_e32 v96, 0, v5
	v_fma_f32 v5, -|v5|, v35, v96
	v_sub_f32_e32 v8, v8, v14
	v_mul_f32_e32 v8, v12, v8
	v_sub_f32_e32 v9, v9, v14
	v_mul_f32_e32 v9, v12, v9
	v_sub_f32_e32 v4, v4, v15
	v_mul_f32_e32 v4, v13, v4
	v_sub_f32_e32 v5, v5, v15
	ds_write_b32 v70, v3 offset:4624
	v_mul_f32_e32 v5, v13, v5
	s_waitcnt vmcnt(0)
	v_fma_f32 v3, v22, v8, v20
	v_fma_f32 v8, v23, v9, v21
	v_fma_f32 v4, v22, v4, v20
	v_cvt_pk_bf16_f32 v3, v3, v4
	v_fmac_f32_e32 v21, v23, v5
	ds_write_b32 v70, v3 offset:4896
	v_cvt_pk_bf16_f32 v3, v8, v21
	global_load_dwordx2 v[8:9], v2, s[0:1] offset:80
	global_load_dwordx2 v[4:5], v2, s[4:5] offset:80
	v_lshlrev_b32_e32 v20, 16, v10
	v_and_b32_e32 v21, 0xffff0000, v10
	v_lshlrev_b32_e32 v22, 16, v6
	v_and_b32_e32 v23, 0xffff0000, v6
	v_fma_f32 v24, |v20|, s40, 1.0
	v_fma_f32 v25, |v21|, s40, 1.0
	v_fma_f32 v36, |v22|, s40, 1.0
	v_fma_f32 v37, |v23|, s40, 1.0
	v_rcp_f32_e32 v24, v24
	v_rcp_f32_e32 v25, v25
	v_rcp_f32_e32 v36, v36
	v_rcp_f32_e32 v37, v37
	v_pk_mul_f32 v[34:35], v[20:21], v[20:21]
	v_pk_mul_f32 v[38:39], v[22:23], v[22:23]
	v_pk_mul_f32 v[34:35], v[34:35], s[64:65] op_sel_hi:[1,0]
	v_pk_fma_f32 v[40:41], v[24:25], s[42:43], v[16:17] op_sel_hi:[1,0,0]
	v_pk_mul_f32 v[38:39], v[38:39], s[64:65] op_sel_hi:[1,0]
	v_exp_f32_e32 v34, v34
	v_exp_f32_e32 v35, v35
	v_pk_fma_f32 v[42:43], v[36:37], s[42:43], v[16:17] op_sel_hi:[1,0,0]
	v_pk_fma_f32 v[40:41], v[24:25], v[40:41], s[48:49] op_sel_hi:[1,1,0]
	v_exp_f32_e32 v38, v38
	v_exp_f32_e32 v39, v39
	v_pk_fma_f32 v[42:43], v[36:37], v[42:43], s[48:49] op_sel_hi:[1,1,0]
	v_pk_fma_f32 v[40:41], v[24:25], v[40:41], s[50:51] op_sel_hi:[1,1,0]
	v_pk_fma_f32 v[42:43], v[36:37], v[42:43], s[50:51] op_sel_hi:[1,1,0]
	v_pk_fma_f32 v[40:41], v[24:25], v[40:41], s[56:57] op_sel_hi:[1,1,0]
	v_pk_fma_f32 v[42:43], v[36:37], v[42:43], s[56:57] op_sel_hi:[1,1,0]
	v_pk_mul_f32 v[24:25], v[24:25], v[40:41]
	v_pk_mul_f32 v[36:37], v[36:37], v[42:43]
	v_pk_mul_f32 v[24:25], v[34:35], v[24:25]
	v_pk_mul_f32 v[34:35], v[38:39], v[36:37]
	v_max_f32_e32 v97, 0, v20
	v_fma_f32 v6, -|v20|, v24, v97
	v_max_f32_e32 v98, 0, v21
	v_fma_f32 v10, -|v21|, v25, v98
	v_max_f32_e32 v99, 0, v22
	v_fma_f32 v20, -|v22|, v34, v99
	v_max_f32_e32 v100, 0, v23
	v_fma_f32 v21, -|v23|, v35, v100
	v_sub_f32_e32 v6, v6, v14
	v_mul_f32_e32 v6, v12, v6
	v_sub_f32_e32 v10, v10, v14
	v_mul_f32_e32 v10, v12, v10
	v_sub_f32_e32 v20, v20, v15
	v_mul_f32_e32 v20, v13, v20
	v_sub_f32_e32 v21, v21, v15
	v_mul_f32_e32 v21, v13, v21
	ds_write_b32 v70, v3 offset:5168
	s_waitcnt vmcnt(0)
	v_fma_f32 v3, v8, v6, v4
	v_fma_f32 v6, v9, v10, v5
	v_fma_f32 v4, v8, v20, v4
	v_fmac_f32_e32 v5, v9, v21
	v_cvt_pk_bf16_f32 v3, v3, v4
	ds_write_b32 v70, v3 offset:5440
	v_cvt_pk_bf16_f32 v3, v6, v5
	global_load_dwordx2 v[8:9], v2, s[0:1] offset:88
	global_load_dwordx2 v[4:5], v2, s[4:5] offset:88
	v_lshlrev_b32_e32 v10, 16, v11
	v_and_b32_e32 v11, 0xffff0000, v11
	v_lshlrev_b32_e32 v6, 16, v7
	v_and_b32_e32 v7, 0xffff0000, v7
	v_fma_f32 v20, |v10|, s40, 1.0
	v_fma_f32 v21, |v11|, s40, 1.0
	v_fma_f32 v24, |v6|, s40, 1.0
	v_fma_f32 v25, |v7|, s40, 1.0
	v_rcp_f32_e32 v20, v20
	v_rcp_f32_e32 v21, v21
	v_rcp_f32_e32 v24, v24
	v_rcp_f32_e32 v25, v25
	v_pk_mul_f32 v[22:23], v[10:11], v[10:11]
	v_pk_mul_f32 v[34:35], v[6:7], v[6:7]
	v_pk_mul_f32 v[22:23], v[22:23], s[64:65] op_sel_hi:[1,0]
	v_pk_fma_f32 v[36:37], v[20:21], s[42:43], v[16:17] op_sel_hi:[1,0,0]
	v_pk_mul_f32 v[34:35], v[34:35], s[64:65] op_sel_hi:[1,0]
	v_exp_f32_e32 v22, v22
	v_exp_f32_e32 v23, v23
	v_pk_fma_f32 v[38:39], v[24:25], s[42:43], v[16:17] op_sel_hi:[1,0,0]
	v_pk_fma_f32 v[36:37], v[20:21], v[36:37], s[48:49] op_sel_hi:[1,1,0]
	v_exp_f32_e32 v34, v34
	v_exp_f32_e32 v35, v35
	v_pk_fma_f32 v[38:39], v[24:25], v[38:39], s[48:49] op_sel_hi:[1,1,0]
	v_pk_fma_f32 v[36:37], v[20:21], v[36:37], s[50:51] op_sel_hi:[1,1,0]
	v_pk_fma_f32 v[38:39], v[24:25], v[38:39], s[50:51] op_sel_hi:[1,1,0]
	v_pk_fma_f32 v[36:37], v[20:21], v[36:37], s[56:57] op_sel_hi:[1,1,0]
	v_pk_fma_f32 v[38:39], v[24:25], v[38:39], s[56:57] op_sel_hi:[1,1,0]
	v_pk_mul_f32 v[20:21], v[20:21], v[36:37]
	v_pk_mul_f32 v[24:25], v[24:25], v[38:39]
	v_pk_mul_f32 v[20:21], v[22:23], v[20:21]
	v_pk_mul_f32 v[22:23], v[34:35], v[24:25]
	v_max_f32_e32 v104, 0, v10
	v_fma_f32 v10, -|v10|, v20, v104
	v_max_f32_e32 v105, 0, v11
	v_fma_f32 v11, -|v11|, v21, v105
	v_max_f32_e32 v106, 0, v6
	v_fma_f32 v6, -|v6|, v22, v106
	v_max_f32_e32 v107, 0, v7
	v_fma_f32 v7, -|v7|, v23, v107
	v_sub_f32_e32 v10, v10, v14
	v_mul_f32_e32 v10, v12, v10
	v_sub_f32_e32 v11, v11, v14
	v_mul_f32_e32 v11, v12, v11
	v_sub_f32_e32 v6, v6, v15
	v_mul_f32_e32 v6, v13, v6
	v_sub_f32_e32 v7, v7, v15
	v_mul_f32_e32 v7, v13, v7
	ds_write_b32 v70, v3 offset:5712
	s_waitcnt vmcnt(0)
	v_fma_f32 v3, v8, v10, v4
	v_fma_f32 v10, v9, v11, v5
	v_fma_f32 v4, v8, v6, v4
	v_fmac_f32_e32 v5, v9, v7
	v_cvt_pk_bf16_f32 v3, v3, v4
	ds_write_b32 v70, v3 offset:5984
	v_cvt_pk_bf16_f32 v3, v10, v5
	global_load_dwordx4 v[8:11], v[18:19], off offset:48
	global_load_dwordx4 v[4:7], v[18:19], off offset:2096
	global_load_dwordx2 v[20:21], v2, s[0:1] offset:96
	s_nop 0
	global_load_dwordx2 v[18:19], v2, s[4:5] offset:96
	ds_write_b32 v70, v3 offset:6256
	s_waitcnt vmcnt(3)
	v_lshlrev_b32_e32 v22, 16, v8
	v_and_b32_e32 v23, 0xffff0000, v8
	s_waitcnt vmcnt(2)
	v_lshlrev_b32_e32 v24, 16, v4
	v_and_b32_e32 v25, 0xffff0000, v4
	v_fma_f32 v34, |v22|, s40, 1.0
	v_fma_f32 v35, |v23|, s40, 1.0
	v_fma_f32 v38, |v24|, s40, 1.0
	v_fma_f32 v39, |v25|, s40, 1.0
	v_rcp_f32_e32 v34, v34
	v_rcp_f32_e32 v35, v35
	v_rcp_f32_e32 v38, v38
	v_rcp_f32_e32 v39, v39
	v_pk_mul_f32 v[36:37], v[22:23], v[22:23]
	v_pk_mul_f32 v[40:41], v[24:25], v[24:25]
	v_pk_mul_f32 v[36:37], v[36:37], s[64:65] op_sel_hi:[1,0]
	v_pk_fma_f32 v[42:43], v[34:35], s[42:43], v[16:17] op_sel_hi:[1,0,0]
	v_pk_mul_f32 v[40:41], v[40:41], s[64:65] op_sel_hi:[1,0]
	v_exp_f32_e32 v36, v36
	v_exp_f32_e32 v37, v37
	v_pk_fma_f32 v[44:45], v[38:39], s[42:43], v[16:17] op_sel_hi:[1,0,0]
	v_pk_fma_f32 v[42:43], v[34:35], v[42:43], s[48:49] op_sel_hi:[1,1,0]
	v_exp_f32_e32 v40, v40
	v_exp_f32_e32 v41, v41
	v_pk_fma_f32 v[44:45], v[38:39], v[44:45], s[48:49] op_sel_hi:[1,1,0]
	v_pk_fma_f32 v[42:43], v[34:35], v[42:43], s[50:51] op_sel_hi:[1,1,0]
	v_pk_fma_f32 v[44:45], v[38:39], v[44:45], s[50:51] op_sel_hi:[1,1,0]
	v_pk_fma_f32 v[42:43], v[34:35], v[42:43], s[56:57] op_sel_hi:[1,1,0]
	v_pk_fma_f32 v[44:45], v[38:39], v[44:45], s[56:57] op_sel_hi:[1,1,0]
	v_pk_mul_f32 v[34:35], v[34:35], v[42:43]
	v_pk_mul_f32 v[38:39], v[38:39], v[44:45]
	v_pk_mul_f32 v[34:35], v[36:37], v[34:35]
	v_pk_mul_f32 v[36:37], v[40:41], v[38:39]
	v_max_f32_e32 v108, 0, v22
	v_fma_f32 v3, -|v22|, v34, v108
	v_max_f32_e32 v109, 0, v23
	v_fma_f32 v4, -|v23|, v35, v109
	v_max_f32_e32 v110, 0, v24
	v_fma_f32 v8, -|v24|, v36, v110
	v_max_f32_e32 v111, 0, v25
	v_fma_f32 v22, -|v25|, v37, v111
	v_sub_f32_e32 v3, v3, v14
	v_mul_f32_e32 v3, v12, v3
	v_sub_f32_e32 v4, v4, v14
	v_mul_f32_e32 v4, v12, v4
	v_sub_f32_e32 v8, v8, v15
	v_mul_f32_e32 v8, v13, v8
	v_sub_f32_e32 v22, v22, v15
	v_mul_f32_e32 v22, v13, v22
	s_waitcnt vmcnt(0)
	v_fma_f32 v3, v20, v3, v18
	v_fma_f32 v4, v21, v4, v19
	v_fma_f32 v8, v20, v8, v18
	v_fmac_f32_e32 v19, v21, v22
	v_cvt_pk_bf16_f32 v3, v3, v8
	ds_write_b32 v70, v3 offset:6528
	v_cvt_pk_bf16_f32 v3, v4, v19
	global_load_dwordx2 v[20:21], v2, s[0:1] offset:104
	global_load_dwordx2 v[18:19], v2, s[4:5] offset:104
	v_lshlrev_b32_e32 v8, 16, v9
	v_and_b32_e32 v9, 0xffff0000, v9
	v_lshlrev_b32_e32 v4, 16, v5
	v_and_b32_e32 v5, 0xffff0000, v5
	v_fma_f32 v22, |v8|, s40, 1.0
	v_fma_f32 v23, |v9|, s40, 1.0
	v_fma_f32 v34, |v4|, s40, 1.0
	v_fma_f32 v35, |v5|, s40, 1.0
	v_rcp_f32_e32 v22, v22
	v_rcp_f32_e32 v23, v23
	v_rcp_f32_e32 v34, v34
	v_rcp_f32_e32 v35, v35
	v_pk_mul_f32 v[24:25], v[8:9], v[8:9]
	v_pk_mul_f32 v[36:37], v[4:5], v[4:5]
	v_pk_mul_f32 v[24:25], v[24:25], s[64:65] op_sel_hi:[1,0]
	v_pk_fma_f32 v[38:39], v[22:23], s[42:43], v[16:17] op_sel_hi:[1,0,0]
	v_pk_mul_f32 v[36:37], v[36:37], s[64:65] op_sel_hi:[1,0]
	v_exp_f32_e32 v24, v24
	v_exp_f32_e32 v25, v25
	v_pk_fma_f32 v[40:41], v[34:35], s[42:43], v[16:17] op_sel_hi:[1,0,0]
	v_pk_fma_f32 v[38:39], v[22:23], v[38:39], s[48:49] op_sel_hi:[1,1,0]
	v_exp_f32_e32 v36, v36
	v_exp_f32_e32 v37, v37
	v_pk_fma_f32 v[40:41], v[34:35], v[40:41], s[48:49] op_sel_hi:[1,1,0]
	v_pk_fma_f32 v[38:39], v[22:23], v[38:39], s[50:51] op_sel_hi:[1,1,0]
	v_pk_fma_f32 v[40:41], v[34:35], v[40:41], s[50:51] op_sel_hi:[1,1,0]
	v_pk_fma_f32 v[38:39], v[22:23], v[38:39], s[56:57] op_sel_hi:[1,1,0]
	v_pk_fma_f32 v[40:41], v[34:35], v[40:41], s[56:57] op_sel_hi:[1,1,0]
	v_pk_mul_f32 v[22:23], v[22:23], v[38:39]
	v_pk_mul_f32 v[34:35], v[34:35], v[40:41]
	v_pk_mul_f32 v[22:23], v[24:25], v[22:23]
	v_pk_mul_f32 v[24:25], v[36:37], v[34:35]
	v_max_f32_e32 v112, 0, v8
	v_fma_f32 v8, -|v8|, v22, v112
	v_max_f32_e32 v113, 0, v9
	v_fma_f32 v9, -|v9|, v23, v113
	v_max_f32_e32 v114, 0, v4
	v_fma_f32 v4, -|v4|, v24, v114
	v_max_f32_e32 v115, 0, v5
	v_fma_f32 v5, -|v5|, v25, v115
	v_sub_f32_e32 v8, v8, v14
	v_mul_f32_e32 v8, v12, v8
	v_sub_f32_e32 v9, v9, v14
	v_mul_f32_e32 v9, v12, v9
	v_sub_f32_e32 v4, v4, v15
	v_mul_f32_e32 v4, v13, v4
	v_sub_f32_e32 v5, v5, v15
	ds_write_b32 v70, v3 offset:6800
	v_mul_f32_e32 v5, v13, v5
	s_waitcnt vmcnt(0)
	v_fma_f32 v3, v20, v8, v18
	v_fma_f32 v8, v21, v9, v19
	v_fma_f32 v4, v20, v4, v18
	v_cvt_pk_bf16_f32 v3, v3, v4
	v_fmac_f32_e32 v19, v21, v5
	ds_write_b32 v70, v3 offset:7072
	v_cvt_pk_bf16_f32 v3, v8, v19
	global_load_dwordx2 v[8:9], v2, s[0:1] offset:112
	global_load_dwordx2 v[4:5], v2, s[4:5] offset:112
	v_lshlrev_b32_e32 v18, 16, v10
	v_and_b32_e32 v19, 0xffff0000, v10
	v_lshlrev_b32_e32 v20, 16, v6
	v_and_b32_e32 v21, 0xffff0000, v6
	v_fma_f32 v22, |v18|, s40, 1.0
	v_fma_f32 v23, |v19|, s40, 1.0
	v_fma_f32 v34, |v20|, s40, 1.0
	v_fma_f32 v35, |v21|, s40, 1.0
	v_rcp_f32_e32 v22, v22
	v_rcp_f32_e32 v23, v23
	v_rcp_f32_e32 v34, v34
	v_rcp_f32_e32 v35, v35
	v_pk_mul_f32 v[24:25], v[18:19], v[18:19]
	v_pk_mul_f32 v[36:37], v[20:21], v[20:21]
	v_pk_mul_f32 v[24:25], v[24:25], s[64:65] op_sel_hi:[1,0]
	v_pk_fma_f32 v[38:39], v[22:23], s[42:43], v[16:17] op_sel_hi:[1,0,0]
	v_pk_mul_f32 v[36:37], v[36:37], s[64:65] op_sel_hi:[1,0]
	v_exp_f32_e32 v24, v24
	v_exp_f32_e32 v25, v25
	v_pk_fma_f32 v[40:41], v[34:35], s[42:43], v[16:17] op_sel_hi:[1,0,0]
	v_pk_fma_f32 v[38:39], v[22:23], v[38:39], s[48:49] op_sel_hi:[1,1,0]
	v_exp_f32_e32 v36, v36
	v_exp_f32_e32 v37, v37
	v_pk_fma_f32 v[40:41], v[34:35], v[40:41], s[48:49] op_sel_hi:[1,1,0]
	v_pk_fma_f32 v[38:39], v[22:23], v[38:39], s[50:51] op_sel_hi:[1,1,0]
	v_pk_fma_f32 v[40:41], v[34:35], v[40:41], s[50:51] op_sel_hi:[1,1,0]
	v_pk_fma_f32 v[38:39], v[22:23], v[38:39], s[56:57] op_sel_hi:[1,1,0]
	v_pk_fma_f32 v[40:41], v[34:35], v[40:41], s[56:57] op_sel_hi:[1,1,0]
	v_pk_mul_f32 v[22:23], v[22:23], v[38:39]
	v_pk_mul_f32 v[34:35], v[34:35], v[40:41]
	v_pk_mul_f32 v[22:23], v[24:25], v[22:23]
	v_pk_mul_f32 v[24:25], v[36:37], v[34:35]
	v_max_f32_e32 v116, 0, v18
	v_fma_f32 v6, -|v18|, v22, v116
	v_max_f32_e32 v117, 0, v19
	v_fma_f32 v10, -|v19|, v23, v117
	v_max_f32_e32 v80, 0, v20
	v_fma_f32 v18, -|v20|, v24, v80
	v_max_f32_e32 v81, 0, v21
	v_fma_f32 v19, -|v21|, v25, v81
	v_sub_f32_e32 v6, v6, v14
	v_mul_f32_e32 v6, v12, v6
	v_sub_f32_e32 v10, v10, v14
	v_mul_f32_e32 v10, v12, v10
	v_sub_f32_e32 v18, v18, v15
	v_mul_f32_e32 v18, v13, v18
	v_sub_f32_e32 v19, v19, v15
	v_mul_f32_e32 v19, v13, v19
	ds_write_b32 v70, v3 offset:7344
	s_andn2_b64 vcc, exec, s[80:81]
	s_waitcnt vmcnt(0)
	v_fma_f32 v3, v8, v6, v4
	v_fma_f32 v6, v9, v10, v5
	v_fma_f32 v4, v8, v18, v4
	v_fmac_f32_e32 v5, v9, v19
	v_cvt_pk_bf16_f32 v3, v3, v4
	ds_write_b32 v70, v3 offset:7616
	v_cvt_pk_bf16_f32 v3, v6, v5
	global_load_dwordx2 v[8:9], v2, s[0:1] offset:120
	global_load_dwordx2 v[4:5], v2, s[4:5] offset:120
	v_lshlrev_b32_e32 v10, 16, v11
	v_and_b32_e32 v11, 0xffff0000, v11
	v_cndmask_b32_e64 v6, 0, 1, s[80:81]
	v_cmp_ne_u32_e64 s[4:5], 1, v6
	v_lshlrev_b32_e32 v6, 16, v7
	v_and_b32_e32 v7, 0xffff0000, v7
	v_fma_f32 v18, |v10|, s40, 1.0
	v_fma_f32 v19, |v11|, s40, 1.0
	v_rcp_f32_e32 v18, v18
	v_rcp_f32_e32 v19, v19
	v_fma_f32 v22, |v6|, s40, 1.0
	v_fma_f32 v23, |v7|, s40, 1.0
	v_pk_mul_f32 v[20:21], v[10:11], v[10:11]
	v_rcp_f32_e32 v22, v22
	v_rcp_f32_e32 v23, v23
	v_pk_mul_f32 v[20:21], v[20:21], s[64:65] op_sel_hi:[1,0]
	v_pk_fma_f32 v[34:35], v[18:19], s[42:43], v[16:17] op_sel_hi:[1,0,0]
	v_pk_mul_f32 v[24:25], v[6:7], v[6:7]
	v_exp_f32_e32 v20, v20
	v_exp_f32_e32 v21, v21
	v_pk_fma_f32 v[34:35], v[18:19], v[34:35], s[48:49] op_sel_hi:[1,1,0]
	v_pk_mul_f32 v[24:25], v[24:25], s[64:65] op_sel_hi:[1,0]
	v_pk_fma_f32 v[16:17], v[22:23], s[42:43], v[16:17] op_sel_hi:[1,0,0]
	v_pk_fma_f32 v[34:35], v[18:19], v[34:35], s[50:51] op_sel_hi:[1,1,0]
	v_exp_f32_e32 v24, v24
	v_exp_f32_e32 v25, v25
	v_pk_fma_f32 v[16:17], v[22:23], v[16:17], s[48:49] op_sel_hi:[1,1,0]
	v_pk_fma_f32 v[34:35], v[18:19], v[34:35], s[56:57] op_sel_hi:[1,1,0]
	v_pk_fma_f32 v[16:17], v[22:23], v[16:17], s[50:51] op_sel_hi:[1,1,0]
	v_pk_mul_f32 v[18:19], v[18:19], v[34:35]
	v_pk_fma_f32 v[16:17], v[22:23], v[16:17], s[56:57] op_sel_hi:[1,1,0]
	v_pk_mul_f32 v[18:19], v[20:21], v[18:19]
	v_pk_mul_f32 v[16:17], v[22:23], v[16:17]
	v_max_f32_e32 v82, 0, v10
	v_fma_f32 v10, -|v10|, v18, v82
	v_max_f32_e32 v83, 0, v11
	v_fma_f32 v11, -|v11|, v19, v83
	v_pk_mul_f32 v[16:17], v[24:25], v[16:17]
	ds_write_b32 v70, v3 offset:7888
	v_max_f32_e32 v84, 0, v6
	v_fma_f32 v6, -|v6|, v16, v84
	v_max_f32_e32 v85, 0, v7
	v_fma_f32 v7, -|v7|, v17, v85
	v_sub_f32_e32 v10, v10, v14
	v_sub_f32_e32 v11, v11, v14
	v_sub_f32_e32 v6, v6, v15
	v_mul_f32_e32 v10, v12, v10
	v_sub_f32_e32 v7, v7, v15
	v_mul_f32_e32 v11, v12, v11
	v_mul_f32_e32 v6, v13, v6
	v_mul_f32_e32 v7, v13, v7
	s_waitcnt vmcnt(0)
	v_fma_f32 v3, v8, v10, v4
	v_fma_f32 v10, v9, v11, v5
	v_fma_f32 v4, v8, v6, v4
	v_fmac_f32_e32 v5, v9, v7
	v_cvt_pk_bf16_f32 v3, v3, v4
	ds_write_b32 v70, v3 offset:8160
	v_cvt_pk_bf16_f32 v3, v10, v5
	v_lshl_add_u64 v[4:5], s[12:13], 0, v[28:29]
	ds_write_b32 v70, v3 offset:8432
	s_cbranch_vccnz .LBB0_458
	v_add_co_u32_e32 v6, vcc, 0x2688000, v4
	s_nop 1
	v_addc_co_u32_e32 v7, vcc, 0, v5, vcc
	global_load_dwordx4 v[6:9], v[6:7], off
	v_cndmask_b32_e64 v3, 0, 1, s[82:83]
	v_cmp_ne_u32_e64 s[6:7], 1, v3
	s_andn2_b64 vcc, exec, s[82:83]
	s_cbranch_vccz .LBB0_459
